# cross-lane butterfly reductions (sum/max, xor 1,2,8 via DPP, xor 16,32 via permlane swaps) instead of ds_bpermute at 72 sites
# baseline (speedup 1.0000x reference)
.LBB0_76:
	v_ashrrev_i32_e32 v3, 31, v2
	v_lshlrev_b64 v[14:15], 12, v[2:3]
	v_lshl_add_u64 v[26:27], v[4:5], 0, v[14:15]
	global_load_dwordx4 v[14:17], v[26:27], off
	global_load_dwordx4 v[18:21], v[26:27], off offset:16
	global_load_dwordx4 v[22:25], v[26:27], off offset:32
	s_nop 0
	global_load_dwordx4 v[26:29], v[26:27], off offset:48
	v_mov_b32_e32 v31, 0
	v_mov_b32_e32 v32, 0
	s_waitcnt vmcnt(3)
	v_max3_f32 v13, |v14|, 0, |v15|
	v_max3_f32 v13, v13, |v16|, |v17|
	s_waitcnt vmcnt(2)
	v_max3_f32 v13, v13, |v18|, |v19|
	v_max3_f32 v13, v13, |v20|, |v21|
	s_waitcnt vmcnt(1)
	v_max3_f32 v13, v13, |v22|, |v23|
	v_max3_f32 v13, v13, |v24|, |v25|
	s_waitcnt vmcnt(0)
	v_max3_f32 v13, v13, |v26|, |v27|
	v_max3_f32 v13, v13, |v28|, |v29|
	v_mov_b32_e32 v30, v13
	s_waitcnt lgkmcnt(0)
	s_nop 1
	v_permlane32_swap_b32_e32 v30, v13
	v_max_f32_e32 v13, v13, v30
	v_mov_b32_e32 v30, v13
	s_waitcnt lgkmcnt(0)
	s_nop 1
	v_permlane16_swap_b32_e32 v30, v13
	v_max_f32_e32 v13, v13, v30
	s_waitcnt lgkmcnt(0)
	s_nop 1
	v_max_f32_dpp v13, v13, v13 row_ror:8 row_mask:0xf bank_mask:0xf
	ds_bpermute_b32 v30, v10, v13
	s_waitcnt lgkmcnt(0)
	v_max_f32_e32 v30, v30, v30
	v_max_f32_e32 v13, v13, v30
	s_waitcnt lgkmcnt(0)
	s_nop 1
	v_max_f32_dpp v13, v13, v13 quad_perm:[2,3,0,1] row_mask:0xf bank_mask:0xf
	v_mov_b32_e32 v30, 0
	s_waitcnt lgkmcnt(0)
	s_nop 1
	v_max_f32_dpp v13, v13, v13 quad_perm:[1,0,3,2] row_mask:0xf bank_mask:0xf
	v_div_scale_f32 v34, s[0:1], v13, v13, s15
	v_rcp_f32_e32 v35, v34
	v_div_scale_f32 v36, vcc, s15, v13, s15
	v_cmp_lt_f32_e64 s[0:1], 0, v13
	v_fma_f32 v37, -v34, v35, 1.0
	v_fmac_f32_e32 v35, v37, v35
	v_mul_f32_e32 v37, v36, v35
	v_fma_f32 v38, -v34, v37, v36
	v_fmac_f32_e32 v37, v38, v35
	v_fma_f32 v34, -v34, v37, v36
	v_div_fmas_f32 v34, v34, v35, v37
	v_div_fixup_f32 v34, v34, v13, s15
	v_cndmask_b32_e64 v34, 1.0, v34, s[0:1]
	v_mov_b32_e32 v33, 0
	v_mul_f32_e32 v14, v14, v34
	v_mul_f32_e32 v15, v15, v34
	v_mul_f32_e32 v18, v18, v34
	v_mul_f32_e32 v19, v19, v34
	v_mul_f32_e32 v22, v22, v34
	v_mul_f32_e32 v23, v23, v34
	v_mul_f32_e32 v26, v26, v34
	v_mul_f32_e32 v27, v27, v34
	v_cvt_pk_fp8_f32 v30, v14, v15
	v_cvt_pk_fp8_f32 v31, v18, v19
	v_cvt_pk_fp8_f32 v32, v22, v23
	v_cvt_pk_fp8_f32 v33, v26, v27
	v_mul_f32_e32 v16, v16, v34
	v_mul_f32_e32 v17, v17, v34
	v_mul_f32_e32 v20, v20, v34
	v_mul_f32_e32 v21, v21, v34
	v_mul_f32_e32 v24, v24, v34
	v_mul_f32_e32 v25, v25, v34
	v_mul_f32_e32 v28, v28, v34
	v_mul_f32_e32 v29, v29, v34
	v_cvt_pk_fp8_f32 v30, v16, v17 op_sel:[0,0,1]
	v_cvt_pk_fp8_f32 v31, v20, v21 op_sel:[0,0,1]
	v_cvt_pk_fp8_f32 v32, v24, v25 op_sel:[0,0,1]
	v_cvt_pk_fp8_f32 v33, v28, v29 op_sel:[0,0,1]
	v_lshlrev_b64 v[14:15], 10, v[2:3]
	v_lshl_add_u64 v[14:15], v[6:7], 0, v[14:15]
	global_store_dwordx4 v[14:15], v[30:33], off
	s_and_saveexec_b64 s[12:13], s[4:5]
	s_cbranch_execz .LBB0_75
	v_div_scale_f32 v14, s[18:19], s15, s15, v13
	v_rcp_f32_e32 v15, v14
	v_div_scale_f32 v16, vcc, v13, s15, v13
	v_fma_f32 v17, -v14, v15, 1.0
	v_fmac_f32_e32 v15, v17, v15
	v_mul_f32_e32 v17, v16, v15
	v_fma_f32 v18, -v14, v17, v16
	v_fmac_f32_e32 v17, v18, v15
	v_fma_f32 v14, -v14, v17, v16
	v_div_fmas_f32 v14, v14, v15, v17
	v_div_fixup_f32 v13, v14, s15, v13
	v_cndmask_b32_e64 v13, 1.0, v13, s[0:1]
	v_lshl_add_u64 v[14:15], v[2:3], 2, s[8:9]
	global_store_dword v[14:15], v13, off
	s_branch .LBB0_75

.LBB0_196:
	s_and_b64 vcc, exec, s[0:1]
	s_cbranch_vccz .LBB0_217
	s_and_b64 s[0:1], s[94:95], exec
	v_readlane_b32 s48, v252, 56
	v_readlane_b32 s0, v255, 24
	v_readlane_b32 s52, v252, 60
	v_readlane_b32 s53, v252, 61
	v_readlane_b32 s54, v252, 62
	v_readlane_b32 s55, v252, 63
	v_readlane_b32 s1, v255, 25
	s_cselect_b32 s8, s53, s55
	s_cselect_b32 s9, s52, s54
	s_lshl_b64 s[0:1], s[0:1], 2
	s_add_u32 s0, s9, s0
	s_addc_u32 s1, s8, s1
	global_load_dwordx4 v[132:135], v146, s[0:1]
	global_load_dwordx4 v[180:183], v146, s[0:1] offset:64
	global_load_dwordx4 v[136:139], v146, s[0:1] offset:128
	global_load_dwordx4 v[188:191], v146, s[0:1] offset:192
	v_and_b32_e32 v141, 64, v215
	v_readlane_b32 s8, v255, 19
	v_lshlrev_b32_e32 v165, 6, v130
	v_mov_b32_e32 v131, v1
	s_waitcnt vmcnt(5)
	v_pk_mul_f32 v[170:171], v[122:123], v[122:123]
	v_xor_b32_e32 v147, 16, v215
	v_lshl_or_b32 v140, v158, 1, s8
	v_and_b32_e32 v144, 0xfc0, v150
	v_mov_b32_e32 v145, v1
	v_pk_mul_f32 v[166:167], v[124:125], v[124:125]
	s_waitcnt vmcnt(4)
	v_add_u32_e32 v175, 64, v141
	v_and_b32_e32 v168, 0x3c0, v165
	v_mad_u64_u32 v[130:131], s[8:9], v164, s28, v[130:131]
	v_pk_fma_f32 v[164:165], v[126:127], v[126:127], v[170:171]
	v_lshl_add_u64 v[162:163], v[152:153], 0, v[144:145]
	v_lshl_add_u64 v[160:161], v[154:155], 0, v[144:145]
	v_pk_fma_f32 v[144:145], v[128:129], v[128:129], v[166:167]
	v_cmp_lt_i32_e32 vcc, v147, v175
	v_pk_fma_f32 v[164:165], v[118:119], v[118:119], v[164:165]
	v_ashrrev_i32_e32 v159, 31, v158
	v_cndmask_b32_e32 v147, v215, v147, vcc
	v_pk_fma_f32 v[144:145], v[120:121], v[120:121], v[144:145]
	v_pk_fma_f32 v[164:165], v[114:115], v[114:115], v[164:165]
	v_lshlrev_b64 v[172:173], 16, v[158:159]
	v_lshlrev_b32_e32 v159, 2, v147
	v_pk_fma_f32 v[144:145], v[116:117], v[116:117], v[144:145]
	v_add_f32_e32 v147, v164, v165
	v_add_f32_e32 v144, v144, v147
	v_add_f32_e32 v144, v145, v144
	v_mov_b32_e32 v145, v144
	v_xor_b32_e32 v174, 32, v215
	v_cmp_lt_i32_e32 vcc, v174, v175
	v_mov_b32_e32 v169, v1
	v_lshlrev_b64 v[130:131], 8, v[130:131]
	v_cndmask_b32_e32 v147, v215, v174, vcc
	v_lshlrev_b32_e32 v187, 2, v147
	s_waitcnt lgkmcnt(0)
	s_nop 1
	v_permlane16_swap_b32_e32 v145, v144
	v_add_f32_e32 v144, v144, v145
	v_mov_b32_e32 v145, v144
	v_lshl_add_u64 v[166:167], v[152:153], 0, v[168:169]
	v_lshl_add_u64 v[164:165], v[154:155], 0, v[168:169]
	v_lshl_add_u64 v[168:169], v[156:157], 0, v[130:131]
	v_ashrrev_i32_e32 v141, 31, v140
	s_waitcnt lgkmcnt(0)
	s_nop 1
	v_permlane32_swap_b32_e32 v145, v144
	v_add_f32_e32 v144, v144, v145
	v_fmamk_f32 v144, v144, 0x3c800000, v178
	v_mul_f32_e32 v145, 0x4b800000, v144
	v_cmp_gt_f32_e32 vcc, s64, v144
	v_lshlrev_b32_e32 v142, 8, v151
	v_mov_b32_e32 v143, v1
	v_cndmask_b32_e32 v144, v144, v145, vcc
	v_rsq_f32_e32 v144, v144
	v_lshlrev_b64 v[174:175], 10, v[140:141]
	v_lshl_add_u64 v[140:141], s[92:93], 0, v[172:173]
	v_mov_b32_e32 v176, v129
	v_mul_f32_e32 v130, 0x45800000, v144
	v_cndmask_b32_e32 v170, v144, v130, vcc
	v_mov_b32_e32 v177, v125
	v_lshl_add_u64 v[140:141], v[140:141], 0, v[142:143]
	v_lshl_add_u64 v[172:173], v[140:141], 0, v[0:1]
	v_lshl_or_b32 v174, v151, 1, v174
	s_mov_b64 s[8:9], -1
	s_and_b64 vcc, exec, s[66:67]
	v_readlane_b32 s49, v252, 57
	v_readlane_b32 s50, v252, 58
	v_readlane_b32 s51, v252, 59
	v_readlane_b32 s56, v253, 0
	v_readlane_b32 s57, v253, 1
	v_readlane_b32 s58, v253, 2
	v_readlane_b32 s59, v253, 3
	v_readlane_b32 s60, v253, 4
	v_readlane_b32 s61, v253, 5
	v_readlane_b32 s62, v253, 6
	v_readlane_b32 s63, v253, 7
	s_waitcnt vmcnt(3)
	v_pk_mul_f32 v[130:131], v[132:133], v[170:171] op_sel_hi:[1,0]
	s_waitcnt vmcnt(2)
	v_pk_mul_f32 v[132:133], v[180:181], v[170:171] op_sel_hi:[1,0]
	v_mul_f32_e32 v145, v182, v170
	v_mov_b32_e32 v182, v135
	s_waitcnt vmcnt(1)
	v_pk_mul_f32 v[180:181], v[138:139], v[170:171] op_sel_hi:[1,0]
	v_pk_mul_f32 v[138:139], v[122:123], v[132:133]
	v_pk_mul_f32 v[132:133], v[182:183], v[170:171] op_sel_hi:[1,0]
	v_pk_mul_f32 v[136:137], v[136:137], v[170:171] op_sel_hi:[1,0]
	s_waitcnt vmcnt(0)
	v_pk_mul_f32 v[140:141], v[188:189], v[170:171] op_sel_hi:[1,0]
	v_mul_f32_e32 v144, v134, v170
	v_pk_mul_f32 v[176:177], v[176:177], v[132:133]
	v_pk_mul_f32 v[132:133], v[190:191], v[170:171] op_sel_hi:[1,0]
	v_pk_mul_f32 v[142:143], v[126:127], v[130:131]
	v_pk_mul_f32 v[134:135], v[118:119], v[136:137]
	v_pk_mul_f32 v[130:131], v[114:115], v[140:141]
	v_mul_f32_e32 v144, v128, v144
	v_mul_f32_e32 v140, v124, v145
	v_pk_mul_f32 v[136:137], v[120:121], v[180:181]
	v_pk_mul_f32 v[132:133], v[116:117], v[132:133]
	s_cbranch_vccz .LBB0_203
	v_mov_b32_e32 v145, v176
	v_mov_b32_e32 v141, v177
	s_and_saveexec_b64 s[8:9], s[44:45]
	s_xor_b64 s[8:9], exec, s[8:9]
	s_cbranch_execz .LBB0_200
	v_readlane_b32 s46, v253, 15
	v_lshlrev_b64 v[170:171], 8, v[174:175]
	v_readlane_b32 s47, v253, 16
	v_mov_b32_e32 v147, v1
	v_cvt_pk_bf16_f32 v182, v130, v131
	v_lshl_add_u64 v[170:171], s[46:47], 0, v[170:171]
	v_lshl_add_u64 v[170:171], v[170:171], 0, v[146:147]
	global_store_dwordx4 v[170:171], v[142:145], off
	global_store_dwordx4 v[170:171], v[138:141], off offset:64
	global_store_dwordx4 v[170:171], v[134:137], off offset:128
	global_store_dwordx4 v[170:171], v[130:133], off offset:192
	v_cvt_pk_bf16_f32 v170, v142, v143
	v_cvt_pk_bf16_f32 v171, v144, v176
	global_store_dwordx2 v[172:173], v[170:171], off
	v_cvt_pk_bf16_f32 v170, v138, v139
	v_cvt_pk_bf16_f32 v171, v140, v177
	global_store_dwordx2 v[172:173], v[170:171], off offset:32
	v_cvt_pk_bf16_f32 v170, v134, v135
	v_cvt_pk_bf16_f32 v171, v136, v137
	global_store_dwordx2 v[172:173], v[170:171], off offset:64

.LBB0_207:
	v_mov_b32_e32 v147, v1
	v_cvt_pk_bf16_f32 v183, v180, v181
	v_lshl_add_u64 v[130:131], s[0:1], 0, v[146:147]
	global_store_dwordx2 v[184:185], v[182:183], off offset:96
	global_load_dwordx4 v[132:135], v[130:131], off
	s_nop 0
	global_load_dwordx4 v[180:183], v[130:131], off offset:64
	global_load_dwordx4 v[136:139], v[130:131], off offset:128
	global_load_dwordx4 v[188:191], v[130:131], off offset:192
	v_pk_mul_f32 v[140:141], v[106:107], v[106:107]
	v_pk_mul_f32 v[130:131], v[108:109], v[108:109]
	v_pk_fma_f32 v[140:141], v[110:111], v[110:111], v[140:141]
	v_pk_fma_f32 v[130:131], v[112:113], v[112:113], v[130:131]
	v_pk_fma_f32 v[140:141], v[102:103], v[102:103], v[140:141]
	v_pk_fma_f32 v[130:131], v[104:105], v[104:105], v[130:131]
	v_pk_fma_f32 v[140:141], v[98:99], v[98:99], v[140:141]
	v_pk_fma_f32 v[130:131], v[100:101], v[100:101], v[130:131]
	v_add_f32_e32 v140, v140, v141
	v_add_f32_e32 v130, v130, v140
	v_add_f32_e32 v130, v131, v130
	v_mov_b32_e32 v131, v130
	v_mov_b32_e32 v176, v113
	v_mov_b32_e32 v177, v109
	v_mov_b32_e32 v184, v105
	v_mov_b32_e32 v185, v101
	s_waitcnt lgkmcnt(0)
	s_nop 1
	v_permlane16_swap_b32_e32 v131, v130
	v_add_f32_e32 v130, v130, v131
	v_mov_b32_e32 v131, v130
	s_andn2_b64 vcc, exec, s[66:67]
	s_waitcnt lgkmcnt(0)
	s_nop 1
	v_permlane32_swap_b32_e32 v131, v130
	v_add_f32_e32 v130, v130, v131
	v_fmamk_f32 v130, v130, 0x3c800000, v178
	v_mul_f32_e32 v131, 0x4b800000, v130
	v_cmp_gt_f32_e64 s[0:1], s64, v130
	s_nop 1
	v_cndmask_b32_e64 v130, v130, v131, s[0:1]
	v_rsq_f32_e32 v130, v130
	s_nop 0
	v_mul_f32_e32 v131, 0x45800000, v130
	v_cndmask_b32_e64 v192, v130, v131, s[0:1]
	s_mov_b64 s[0:1], -1
	s_waitcnt vmcnt(3)
	v_pk_mul_f32 v[130:131], v[132:133], v[192:193] op_sel_hi:[1,0]
	s_waitcnt vmcnt(2)
	v_mul_f32_e32 v145, v182, v192
	v_mov_b32_e32 v182, v135
	s_waitcnt vmcnt(0)
	v_mul_f32_e32 v151, v190, v192
	v_mov_b32_e32 v190, v139
	v_pk_mul_f32 v[132:133], v[180:181], v[192:193] op_sel_hi:[1,0]
	v_pk_mul_f32 v[180:181], v[182:183], v[192:193] op_sel_hi:[1,0]
	v_pk_mul_f32 v[182:183], v[190:191], v[192:193] op_sel_hi:[1,0]
	v_pk_mul_f32 v[136:137], v[136:137], v[192:193] op_sel_hi:[1,0]
	v_pk_mul_f32 v[140:141], v[188:189], v[192:193] op_sel_hi:[1,0]
	v_mul_f32_e32 v144, v134, v192
	v_mul_f32_e32 v147, v138, v192
	v_pk_mul_f32 v[180:181], v[176:177], v[180:181]
	v_pk_mul_f32 v[176:177], v[184:185], v[182:183]
	v_pk_mul_f32 v[142:143], v[110:111], v[130:131]
	v_pk_mul_f32 v[138:139], v[106:107], v[132:133]
	v_pk_mul_f32 v[134:135], v[102:103], v[136:137]
	v_pk_mul_f32 v[130:131], v[98:99], v[140:141]
	v_mul_f32_e32 v144, v112, v144
	v_mul_f32_e32 v140, v108, v145
	v_mul_f32_e32 v136, v104, v147
	v_mul_f32_e32 v132, v100, v151
	v_mov_b32_e32 v145, v180
	v_mov_b32_e32 v141, v181
	v_mov_b32_e32 v137, v176
	v_mov_b32_e32 v133, v177
	s_cbranch_vccnz .LBB0_213
	s_and_saveexec_b64 s[0:1], s[44:45]
	s_xor_b64 s[0:1], exec, s[0:1]
	s_cbranch_execz .LBB0_210
	v_readlane_b32 s8, v253, 17
	v_lshlrev_b64 v[168:169], 8, v[174:175]
	v_readlane_b32 s9, v253, 18
	v_mov_b32_e32 v147, v1
	s_nop 0
	v_lshl_add_u64 v[168:169], s[8:9], 0, v[168:169]
	v_lshl_add_u64 v[168:169], v[168:169], 0, v[146:147]
	global_store_dwordx4 v[168:169], v[142:145], off
	global_store_dwordx4 v[168:169], v[138:141], off offset:64
	global_store_dwordx4 v[168:169], v[134:137], off offset:128
	global_store_dwordx4 v[168:169], v[130:133], off offset:192
	v_cvt_pk_bf16_f32 v168, v142, v143
	v_cvt_pk_bf16_f32 v169, v144, v180
	global_store_dwordx2 v[172:173], v[168:169], off offset:128
	v_cvt_pk_bf16_f32 v168, v138, v139
	v_cvt_pk_bf16_f32 v169, v140, v181
	global_store_dwordx2 v[172:173], v[168:169], off offset:160
	v_cvt_pk_bf16_f32 v168, v134, v135
	v_cvt_pk_bf16_f32 v169, v136, v176
	global_store_dwordx2 v[172:173], v[168:169], off offset:192
	v_cvt_pk_bf16_f32 v168, v130, v131
	v_cvt_pk_bf16_f32 v169, v132, v177
	global_store_dwordx2 v[172:173], v[168:169], off offset:224

.LBB0_253:
	s_and_b64 vcc, exec, s[0:1]
	s_cbranch_vccz .LBB0_274
	s_and_b64 s[0:1], s[94:95], exec
	v_readlane_b32 s48, v252, 56
	v_readlane_b32 s0, v255, 24
	v_readlane_b32 s52, v252, 60
	v_readlane_b32 s53, v252, 61
	v_readlane_b32 s54, v252, 62
	v_readlane_b32 s55, v252, 63
	v_readlane_b32 s1, v255, 25
	s_cselect_b32 s8, s53, s55
	s_cselect_b32 s9, s52, s54
	s_lshl_b64 s[0:1], s[0:1], 2
	s_add_u32 s0, s9, s0
	s_addc_u32 s1, s8, s1
	global_load_dwordx4 v[100:103], v146, s[0:1]
	global_load_dwordx4 v[134:137], v146, s[0:1] offset:64
	global_load_dwordx4 v[104:107], v146, s[0:1] offset:128
	global_load_dwordx4 v[138:141], v146, s[0:1] offset:192
	v_readlane_b32 s8, v255, 19
	v_mbcnt_hi_u32_b32 v143, -1, v214
	v_and_b32_e32 v112, 0xfc0, v150
	v_lshl_or_b32 v108, v158, 1, s8
	v_mov_b32_e32 v113, v1
	v_lshlrev_b32_e32 v121, 6, v98
	v_mov_b32_e32 v99, v1
	v_pk_mul_f32 v[122:123], v[92:93], v[92:93]
	v_pk_mul_f32 v[126:127], v[90:91], v[90:91]
	v_and_b32_e32 v128, 64, v143
	v_ashrrev_i32_e32 v109, 31, v108
	v_lshl_add_u64 v[118:119], v[152:153], 0, v[112:113]
	v_lshl_add_u64 v[116:117], v[154:155], 0, v[112:113]
	v_and_b32_e32 v124, 0x7c0, v121
	v_mad_u64_u32 v[98:99], s[8:9], v120, s28, v[98:99]
	v_pk_fma_f32 v[112:113], v[96:97], v[96:97], v[122:123]
	v_pk_fma_f32 v[120:121], v[94:95], v[94:95], v[126:127]
	v_add_u32_e32 v122, 64, v128
	v_lshlrev_b64 v[128:129], 10, v[108:109]
	v_pk_fma_f32 v[108:109], v[88:89], v[88:89], v[112:113]
	v_pk_fma_f32 v[112:113], v[86:87], v[86:87], v[120:121]
	v_xor_b32_e32 v142, 16, v143
	v_pk_fma_f32 v[112:113], v[82:83], v[82:83], v[112:113]
	v_cmp_lt_i32_e32 vcc, v142, v122
	v_pk_fma_f32 v[108:109], v[84:85], v[84:85], v[108:109]
	v_add_f32_e32 v112, v112, v113
	v_cndmask_b32_e32 v120, v143, v142, vcc
	v_add_f32_e32 v108, v108, v112
	v_lshlrev_b32_e32 v142, 2, v120
	v_add_f32_e32 v112, v109, v108
	v_mov_b32_e32 v113, v112
	v_xor_b32_e32 v147, 32, v143
	v_cmp_lt_i32_e32 vcc, v147, v122
	v_ashrrev_i32_e32 v159, 31, v158
	v_mov_b32_e32 v125, v1
	v_cndmask_b32_e32 v120, v143, v147, vcc
	v_lshlrev_b32_e32 v143, 2, v120
	s_waitcnt lgkmcnt(0)
	s_nop 1
	v_permlane16_swap_b32_e32 v113, v112
	v_add_f32_e32 v112, v112, v113
	v_mov_b32_e32 v113, v112
	v_lshlrev_b64 v[98:99], 8, v[98:99]
	v_lshlrev_b64 v[132:133], 16, v[158:159]
	v_lshl_add_u64 v[122:123], v[152:153], 0, v[124:125]
	v_lshl_add_u64 v[120:121], v[154:155], 0, v[124:125]
	s_waitcnt lgkmcnt(0)
	s_nop 1
	v_permlane32_swap_b32_e32 v113, v112
	v_add_f32_e32 v112, v112, v113
	v_fmamk_f32 v112, v112, 0x3c800000, v178
	v_mul_f32_e32 v113, 0x4b800000, v112
	v_cmp_gt_f32_e32 vcc, s64, v112
	v_lshl_add_u64 v[124:125], v[156:157], 0, v[98:99]
	v_lshlrev_b32_e32 v110, 8, v115
	v_cndmask_b32_e32 v112, v112, v113, vcc
	v_rsq_f32_e32 v112, v112
	v_mov_b32_e32 v111, v1
	v_lshl_add_u64 v[108:109], s[92:93], 0, v[132:133]
	v_lshl_add_u64 v[108:109], v[108:109], 0, v[110:111]
	v_mul_f32_e32 v98, 0x45800000, v112
	v_cndmask_b32_e32 v126, v112, v98, vcc
	v_mov_b32_e32 v144, v97
	v_mov_b32_e32 v145, v93
	v_lshl_add_u64 v[132:133], v[108:109], 0, v[0:1]
	v_readlane_b32 s49, v252, 57
	v_lshl_or_b32 v128, v115, 1, v128
	v_cndmask_b32_e64 v115, 0, 1, s[66:67]
	v_cmp_ne_u32_e64 s[48:49], 1, v115
	s_andn2_b64 vcc, exec, s[66:67]
	s_mov_b64 s[8:9], -1
	v_readlane_b32 s50, v252, 58
	v_readlane_b32 s51, v252, 59
	v_readlane_b32 s56, v253, 0
	v_readlane_b32 s57, v253, 1
	v_readlane_b32 s58, v253, 2
	v_readlane_b32 s59, v253, 3
	v_readlane_b32 s60, v253, 4
	v_readlane_b32 s61, v253, 5
	v_readlane_b32 s62, v253, 6
	v_readlane_b32 s63, v253, 7
	s_waitcnt vmcnt(3)
	v_pk_mul_f32 v[98:99], v[100:101], v[126:127] op_sel_hi:[1,0]
	s_waitcnt vmcnt(2)
	v_pk_mul_f32 v[100:101], v[134:135], v[126:127] op_sel_hi:[1,0]
	v_mul_f32_e32 v113, v136, v126
	v_mov_b32_e32 v136, v103
	s_waitcnt vmcnt(0)
	v_pk_mul_f32 v[108:109], v[138:139], v[126:127] op_sel_hi:[1,0]
	v_pk_mul_f32 v[138:139], v[106:107], v[126:127] op_sel_hi:[1,0]
	v_pk_mul_f32 v[106:107], v[90:91], v[100:101]
	v_pk_mul_f32 v[100:101], v[136:137], v[126:127] op_sel_hi:[1,0]
	v_pk_mul_f32 v[104:105], v[104:105], v[126:127] op_sel_hi:[1,0]
	v_mul_f32_e32 v112, v102, v126
	v_pk_mul_f32 v[134:135], v[144:145], v[100:101]
	v_pk_mul_f32 v[100:101], v[140:141], v[126:127] op_sel_hi:[1,0]
	v_pk_mul_f32 v[110:111], v[94:95], v[98:99]
	v_pk_mul_f32 v[102:103], v[86:87], v[104:105]
	v_pk_mul_f32 v[98:99], v[82:83], v[108:109]
	v_mul_f32_e32 v112, v96, v112
	v_mul_f32_e32 v108, v92, v113
	v_pk_mul_f32 v[104:105], v[88:89], v[138:139]
	v_pk_mul_f32 v[100:101], v[84:85], v[100:101]
	s_cbranch_vccnz .LBB0_260
	v_mov_b32_e32 v113, v134
	v_mov_b32_e32 v109, v135
	s_and_saveexec_b64 s[8:9], s[46:47]
	s_xor_b64 s[8:9], exec, s[8:9]
	s_cbranch_execz .LBB0_257
	v_readlane_b32 s20, v253, 15
	v_lshlrev_b64 v[126:127], 8, v[128:129]
	v_readlane_b32 s21, v253, 16
	v_mov_b32_e32 v147, v1
	v_cvt_pk_bf16_f32 v138, v98, v99
	v_lshl_add_u64 v[126:127], s[20:21], 0, v[126:127]
	v_lshl_add_u64 v[126:127], v[126:127], 0, v[146:147]
	global_store_dwordx4 v[126:127], v[110:113], off
	global_store_dwordx4 v[126:127], v[106:109], off offset:64
	global_store_dwordx4 v[126:127], v[102:105], off offset:128
	global_store_dwordx4 v[126:127], v[98:101], off offset:192
	v_cvt_pk_bf16_f32 v126, v110, v111
	v_cvt_pk_bf16_f32 v127, v112, v134
	global_store_dwordx2 v[132:133], v[126:127], off
	v_cvt_pk_bf16_f32 v126, v106, v107
	v_cvt_pk_bf16_f32 v127, v108, v135
	global_store_dwordx2 v[132:133], v[126:127], off offset:32
	v_cvt_pk_bf16_f32 v126, v102, v103
	v_cvt_pk_bf16_f32 v127, v104, v105
	global_store_dwordx2 v[132:133], v[126:127], off offset:64

.LBB0_264:
	v_mov_b32_e32 v147, v1
	v_cvt_pk_bf16_f32 v139, v136, v137
	v_lshl_add_u64 v[98:99], s[0:1], 0, v[146:147]
	global_store_dwordx2 v[140:141], v[138:139], off offset:96
	global_load_dwordx4 v[100:103], v[98:99], off
	global_load_dwordx4 v[134:137], v[98:99], off offset:64
	global_load_dwordx4 v[104:107], v[98:99], off offset:128
	s_nop 0
	global_load_dwordx4 v[138:141], v[98:99], off offset:192
	v_pk_mul_f32 v[108:109], v[74:75], v[74:75]
	v_pk_mul_f32 v[98:99], v[76:77], v[76:77]
	v_pk_fma_f32 v[108:109], v[78:79], v[78:79], v[108:109]
	v_pk_fma_f32 v[98:99], v[80:81], v[80:81], v[98:99]
	v_pk_fma_f32 v[108:109], v[70:71], v[70:71], v[108:109]
	v_pk_fma_f32 v[98:99], v[72:73], v[72:73], v[98:99]
	v_pk_fma_f32 v[108:109], v[66:67], v[66:67], v[108:109]
	v_pk_fma_f32 v[98:99], v[68:69], v[68:69], v[98:99]
	v_add_f32_e32 v108, v108, v109
	v_add_f32_e32 v98, v98, v108
	v_add_f32_e32 v98, v99, v98
	v_mov_b32_e32 v99, v98
	v_mov_b32_e32 v142, v81
	v_mov_b32_e32 v144, v73
	v_mov_b32_e32 v145, v69
	s_and_b64 vcc, exec, s[48:49]
	s_waitcnt lgkmcnt(0)
	s_nop 1
	v_permlane16_swap_b32_e32 v99, v98
	v_add_f32_e32 v98, v98, v99
	v_mov_b32_e32 v99, v98
	v_mov_b32_e32 v143, v77
	s_waitcnt lgkmcnt(0)
	s_nop 1
	v_permlane32_swap_b32_e32 v99, v98
	v_add_f32_e32 v98, v98, v99
	v_fmamk_f32 v98, v98, 0x3c800000, v178
	v_mul_f32_e32 v99, 0x4b800000, v98
	v_cmp_gt_f32_e64 s[0:1], s64, v98
	s_nop 1
	v_cndmask_b32_e64 v98, v98, v99, s[0:1]
	v_rsq_f32_e32 v98, v98
	s_nop 0
	v_mul_f32_e32 v99, 0x45800000, v98
	v_cndmask_b32_e64 v160, v98, v99, s[0:1]
	s_mov_b64 s[0:1], -1
	s_waitcnt vmcnt(3)
	v_pk_mul_f32 v[98:99], v[100:101], v[160:161] op_sel_hi:[1,0]
	s_waitcnt vmcnt(2)
	v_pk_mul_f32 v[100:101], v[134:135], v[160:161] op_sel_hi:[1,0]
	v_mul_f32_e32 v113, v136, v160
	s_waitcnt vmcnt(0)
	v_mul_f32_e32 v134, v140, v160
	v_mov_b32_e32 v136, v103
	v_mov_b32_e32 v140, v107
	v_pk_mul_f32 v[108:109], v[138:139], v[160:161] op_sel_hi:[1,0]
	v_mul_f32_e32 v115, v106, v160
	v_pk_mul_f32 v[106:107], v[74:75], v[100:101]
	v_mul_f32_e32 v100, v68, v134
	v_pk_mul_f32 v[134:135], v[136:137], v[160:161] op_sel_hi:[1,0]
	v_pk_mul_f32 v[138:139], v[140:141], v[160:161] op_sel_hi:[1,0]
	v_pk_mul_f32 v[104:105], v[104:105], v[160:161] op_sel_hi:[1,0]
	v_mul_f32_e32 v112, v102, v160
	v_pk_mul_f32 v[136:137], v[142:143], v[134:135]
	v_pk_mul_f32 v[134:135], v[144:145], v[138:139]
	v_pk_mul_f32 v[110:111], v[78:79], v[98:99]
	v_pk_mul_f32 v[102:103], v[70:71], v[104:105]
	v_pk_mul_f32 v[98:99], v[66:67], v[108:109]
	v_mul_f32_e32 v112, v80, v112
	v_mul_f32_e32 v108, v76, v113
	v_mul_f32_e32 v104, v72, v115
	v_mov_b32_e32 v113, v136
	v_mov_b32_e32 v109, v137
	v_mov_b32_e32 v105, v134
	v_mov_b32_e32 v101, v135
	s_cbranch_vccnz .LBB0_270
	s_and_saveexec_b64 s[0:1], s[46:47]
	s_xor_b64 s[0:1], exec, s[0:1]
	s_cbranch_execz .LBB0_267
	v_readlane_b32 s8, v253, 17
	v_lshlrev_b64 v[124:125], 8, v[128:129]
	v_readlane_b32 s9, v253, 18
	v_mov_b32_e32 v147, v1
	s_nop 0
	v_lshl_add_u64 v[124:125], s[8:9], 0, v[124:125]
	v_lshl_add_u64 v[124:125], v[124:125], 0, v[146:147]
	global_store_dwordx4 v[124:125], v[110:113], off
	global_store_dwordx4 v[124:125], v[106:109], off offset:64
	global_store_dwordx4 v[124:125], v[102:105], off offset:128
	global_store_dwordx4 v[124:125], v[98:101], off offset:192
	v_cvt_pk_bf16_f32 v124, v110, v111
	v_cvt_pk_bf16_f32 v125, v112, v136
	global_store_dwordx2 v[132:133], v[124:125], off offset:128
	v_cvt_pk_bf16_f32 v124, v106, v107
	v_cvt_pk_bf16_f32 v125, v108, v137
	global_store_dwordx2 v[132:133], v[124:125], off offset:160
	v_cvt_pk_bf16_f32 v124, v102, v103
	v_cvt_pk_bf16_f32 v125, v104, v134
	global_store_dwordx2 v[132:133], v[124:125], off offset:192
	v_cvt_pk_bf16_f32 v124, v98, v99
	v_cvt_pk_bf16_f32 v125, v100, v135
	global_store_dwordx2 v[132:133], v[124:125], off offset:224

.LBB0_303:
	s_and_b64 vcc, exec, s[0:1]
	s_cbranch_vccz .LBB0_324
	s_and_b64 s[0:1], s[94:95], exec
	v_readlane_b32 s48, v252, 56
	v_readlane_b32 s0, v255, 24
	v_readlane_b32 s52, v252, 60
	v_readlane_b32 s53, v252, 61
	v_readlane_b32 s54, v252, 62
	v_readlane_b32 s55, v252, 63
	v_readlane_b32 s1, v255, 25
	s_cselect_b32 s8, s53, s55
	s_cselect_b32 s9, s52, s54
	s_lshl_b64 s[0:1], s[0:1], 2
	s_add_u32 s0, s9, s0
	s_addc_u32 s1, s8, s1
	global_load_dwordx4 v[68:71], v146, s[0:1]
	global_load_dwordx4 v[100:103], v146, s[0:1] offset:64
	global_load_dwordx4 v[72:75], v146, s[0:1] offset:128
	global_load_dwordx4 v[104:107], v146, s[0:1] offset:192
	v_readlane_b32 s8, v255, 19
	v_mbcnt_hi_u32_b32 v109, -1, v214
	v_and_b32_e32 v80, 0xfc0, v150
	v_lshl_or_b32 v76, v158, 1, s8
	v_mov_b32_e32 v81, v1
	v_lshlrev_b32_e32 v89, 6, v66
	v_mov_b32_e32 v67, v1
	v_pk_mul_f32 v[90:91], v[60:61], v[60:61]
	v_pk_mul_f32 v[94:95], v[58:59], v[58:59]
	v_and_b32_e32 v96, 64, v109
	v_ashrrev_i32_e32 v77, 31, v76
	v_lshl_add_u64 v[86:87], v[152:153], 0, v[80:81]
	v_lshl_add_u64 v[84:85], v[154:155], 0, v[80:81]
	v_and_b32_e32 v92, 0xbc0, v89
	v_mad_u64_u32 v[66:67], s[8:9], v88, s28, v[66:67]
	v_pk_fma_f32 v[80:81], v[64:65], v[64:65], v[90:91]
	v_pk_fma_f32 v[88:89], v[62:63], v[62:63], v[94:95]
	v_add_u32_e32 v90, 64, v96
	v_lshlrev_b64 v[96:97], 10, v[76:77]
	v_pk_fma_f32 v[76:77], v[56:57], v[56:57], v[80:81]
	v_pk_fma_f32 v[80:81], v[54:55], v[54:55], v[88:89]
	v_xor_b32_e32 v108, 16, v109
	v_pk_fma_f32 v[80:81], v[50:51], v[50:51], v[80:81]
	v_cmp_lt_i32_e32 vcc, v108, v90
	v_pk_fma_f32 v[76:77], v[52:53], v[52:53], v[76:77]
	v_add_f32_e32 v80, v80, v81
	v_cndmask_b32_e32 v88, v109, v108, vcc
	v_add_f32_e32 v76, v76, v80
	v_lshlrev_b32_e32 v108, 2, v88
	v_add_f32_e32 v80, v77, v76
	v_mov_b32_e32 v81, v80
	v_xor_b32_e32 v112, 32, v109
	v_cmp_lt_i32_e32 vcc, v112, v90
	v_ashrrev_i32_e32 v159, 31, v158
	v_mov_b32_e32 v93, v1
	v_cndmask_b32_e32 v88, v109, v112, vcc
	v_lshlrev_b32_e32 v109, 2, v88
	s_waitcnt lgkmcnt(0)
	s_nop 1
	v_permlane16_swap_b32_e32 v81, v80
	v_add_f32_e32 v80, v80, v81
	v_mov_b32_e32 v81, v80
	v_lshlrev_b64 v[66:67], 8, v[66:67]
	v_lshlrev_b64 v[98:99], 16, v[158:159]
	v_lshl_add_u64 v[90:91], v[152:153], 0, v[92:93]
	v_lshl_add_u64 v[88:89], v[154:155], 0, v[92:93]
	s_waitcnt lgkmcnt(0)
	s_nop 1
	v_permlane32_swap_b32_e32 v81, v80
	v_add_f32_e32 v80, v80, v81
	v_fmamk_f32 v80, v80, 0x3c800000, v178
	v_mul_f32_e32 v81, 0x4b800000, v80
	v_cmp_gt_f32_e32 vcc, s64, v80
	v_lshl_add_u64 v[92:93], v[156:157], 0, v[66:67]
	v_lshlrev_b32_e32 v78, 8, v83
	v_cndmask_b32_e32 v80, v80, v81, vcc
	v_rsq_f32_e32 v80, v80
	v_mov_b32_e32 v79, v1
	v_lshl_add_u64 v[76:77], s[92:93], 0, v[98:99]
	v_lshl_add_u64 v[76:77], v[76:77], 0, v[78:79]
	v_mul_f32_e32 v66, 0x45800000, v80
	v_cndmask_b32_e32 v94, v80, v66, vcc
	v_mov_b32_e32 v110, v65
	v_mov_b32_e32 v111, v61
	v_lshl_add_u64 v[98:99], v[76:77], 0, v[0:1]
	v_readlane_b32 s49, v252, 57
	v_lshl_or_b32 v96, v83, 1, v96
	v_cndmask_b32_e64 v83, 0, 1, s[66:67]
	v_cmp_ne_u32_e64 s[48:49], 1, v83
	s_andn2_b64 vcc, exec, s[66:67]
	s_mov_b64 s[8:9], -1
	v_readlane_b32 s50, v252, 58
	v_readlane_b32 s51, v252, 59
	v_readlane_b32 s56, v253, 0
	v_readlane_b32 s57, v253, 1
	v_readlane_b32 s58, v253, 2
	v_readlane_b32 s59, v253, 3
	v_readlane_b32 s60, v253, 4
	v_readlane_b32 s61, v253, 5
	v_readlane_b32 s62, v253, 6
	v_readlane_b32 s63, v253, 7
	s_waitcnt vmcnt(3)
	v_pk_mul_f32 v[66:67], v[68:69], v[94:95] op_sel_hi:[1,0]
	s_waitcnt vmcnt(2)
	v_pk_mul_f32 v[68:69], v[100:101], v[94:95] op_sel_hi:[1,0]
	v_mul_f32_e32 v81, v102, v94
	v_mov_b32_e32 v102, v71
	s_waitcnt vmcnt(0)
	v_pk_mul_f32 v[76:77], v[104:105], v[94:95] op_sel_hi:[1,0]
	v_pk_mul_f32 v[104:105], v[74:75], v[94:95] op_sel_hi:[1,0]
	v_pk_mul_f32 v[74:75], v[58:59], v[68:69]
	v_pk_mul_f32 v[68:69], v[102:103], v[94:95] op_sel_hi:[1,0]
	v_pk_mul_f32 v[72:73], v[72:73], v[94:95] op_sel_hi:[1,0]
	v_mul_f32_e32 v80, v70, v94
	v_pk_mul_f32 v[100:101], v[110:111], v[68:69]
	v_pk_mul_f32 v[68:69], v[106:107], v[94:95] op_sel_hi:[1,0]
	v_pk_mul_f32 v[78:79], v[62:63], v[66:67]
	v_pk_mul_f32 v[70:71], v[54:55], v[72:73]
	v_pk_mul_f32 v[66:67], v[50:51], v[76:77]
	v_mul_f32_e32 v80, v64, v80
	v_mul_f32_e32 v76, v60, v81
	v_pk_mul_f32 v[72:73], v[56:57], v[104:105]
	v_pk_mul_f32 v[68:69], v[52:53], v[68:69]
	s_cbranch_vccnz .LBB0_310
	v_mov_b32_e32 v81, v100
	v_mov_b32_e32 v77, v101
	s_and_saveexec_b64 s[8:9], s[46:47]
	s_xor_b64 s[8:9], exec, s[8:9]
	s_cbranch_execz .LBB0_307
	v_readlane_b32 s20, v253, 15
	v_lshlrev_b64 v[94:95], 8, v[96:97]
	v_readlane_b32 s21, v253, 16
	v_mov_b32_e32 v147, v1
	v_cvt_pk_bf16_f32 v104, v66, v67
	v_lshl_add_u64 v[94:95], s[20:21], 0, v[94:95]
	v_lshl_add_u64 v[94:95], v[94:95], 0, v[146:147]
	global_store_dwordx4 v[94:95], v[78:81], off
	global_store_dwordx4 v[94:95], v[74:77], off offset:64
	global_store_dwordx4 v[94:95], v[70:73], off offset:128
	global_store_dwordx4 v[94:95], v[66:69], off offset:192
	v_cvt_pk_bf16_f32 v94, v78, v79
	v_cvt_pk_bf16_f32 v95, v80, v100
	global_store_dwordx2 v[98:99], v[94:95], off
	v_cvt_pk_bf16_f32 v94, v74, v75
	v_cvt_pk_bf16_f32 v95, v76, v101
	global_store_dwordx2 v[98:99], v[94:95], off offset:32
	v_cvt_pk_bf16_f32 v94, v70, v71
	v_cvt_pk_bf16_f32 v95, v72, v73
	global_store_dwordx2 v[98:99], v[94:95], off offset:64

.LBB0_314:
	v_mov_b32_e32 v147, v1
	v_cvt_pk_bf16_f32 v105, v102, v103
	v_lshl_add_u64 v[66:67], s[0:1], 0, v[146:147]
	global_store_dwordx2 v[106:107], v[104:105], off offset:96
	global_load_dwordx4 v[68:71], v[66:67], off
	global_load_dwordx4 v[100:103], v[66:67], off offset:64
	global_load_dwordx4 v[72:75], v[66:67], off offset:128
	s_nop 0
	global_load_dwordx4 v[104:107], v[66:67], off offset:192
	v_pk_mul_f32 v[76:77], v[42:43], v[42:43]
	v_pk_mul_f32 v[66:67], v[44:45], v[44:45]
	v_pk_fma_f32 v[76:77], v[46:47], v[46:47], v[76:77]
	v_pk_fma_f32 v[66:67], v[48:49], v[48:49], v[66:67]
	v_pk_fma_f32 v[76:77], v[38:39], v[38:39], v[76:77]
	v_pk_fma_f32 v[66:67], v[40:41], v[40:41], v[66:67]
	v_pk_fma_f32 v[76:77], v[34:35], v[34:35], v[76:77]
	v_pk_fma_f32 v[66:67], v[36:37], v[36:37], v[66:67]
	v_add_f32_e32 v76, v76, v77
	v_add_f32_e32 v66, v66, v76
	v_add_f32_e32 v66, v67, v66
	v_mov_b32_e32 v67, v66
	v_mov_b32_e32 v108, v49
	v_mov_b32_e32 v110, v41
	v_mov_b32_e32 v111, v37
	s_and_b64 vcc, exec, s[48:49]
	s_waitcnt lgkmcnt(0)
	s_nop 1
	v_permlane16_swap_b32_e32 v67, v66
	v_add_f32_e32 v66, v66, v67
	v_mov_b32_e32 v67, v66
	v_mov_b32_e32 v109, v45
	s_waitcnt lgkmcnt(0)
	s_nop 1
	v_permlane32_swap_b32_e32 v67, v66
	v_add_f32_e32 v66, v66, v67
	v_fmamk_f32 v66, v66, 0x3c800000, v178
	v_mul_f32_e32 v67, 0x4b800000, v66
	v_cmp_gt_f32_e64 s[0:1], s64, v66
	s_nop 1
	v_cndmask_b32_e64 v66, v66, v67, s[0:1]
	v_rsq_f32_e32 v66, v66
	s_nop 0
	v_mul_f32_e32 v67, 0x45800000, v66
	v_cndmask_b32_e64 v112, v66, v67, s[0:1]
	s_mov_b64 s[0:1], -1
	s_waitcnt vmcnt(3)
	v_pk_mul_f32 v[66:67], v[68:69], v[112:113] op_sel_hi:[1,0]
	s_waitcnt vmcnt(2)
	v_pk_mul_f32 v[68:69], v[100:101], v[112:113] op_sel_hi:[1,0]
	v_mul_f32_e32 v81, v102, v112
	s_waitcnt vmcnt(0)
	v_mul_f32_e32 v100, v106, v112
	v_mov_b32_e32 v102, v71
	v_mov_b32_e32 v106, v75
	v_pk_mul_f32 v[76:77], v[104:105], v[112:113] op_sel_hi:[1,0]
	v_mul_f32_e32 v83, v74, v112
	v_pk_mul_f32 v[74:75], v[42:43], v[68:69]
	v_mul_f32_e32 v68, v36, v100
	v_pk_mul_f32 v[100:101], v[102:103], v[112:113] op_sel_hi:[1,0]
	v_pk_mul_f32 v[104:105], v[106:107], v[112:113] op_sel_hi:[1,0]
	v_pk_mul_f32 v[72:73], v[72:73], v[112:113] op_sel_hi:[1,0]
	v_mul_f32_e32 v80, v70, v112
	v_pk_mul_f32 v[102:103], v[108:109], v[100:101]
	v_pk_mul_f32 v[100:101], v[110:111], v[104:105]
	v_pk_mul_f32 v[78:79], v[46:47], v[66:67]
	v_pk_mul_f32 v[70:71], v[38:39], v[72:73]
	v_pk_mul_f32 v[66:67], v[34:35], v[76:77]
	v_mul_f32_e32 v80, v48, v80
	v_mul_f32_e32 v76, v44, v81
	v_mul_f32_e32 v72, v40, v83
	v_mov_b32_e32 v81, v102
	v_mov_b32_e32 v77, v103
	v_mov_b32_e32 v73, v100
	v_mov_b32_e32 v69, v101
	s_cbranch_vccnz .LBB0_320
	s_and_saveexec_b64 s[0:1], s[46:47]
	s_xor_b64 s[0:1], exec, s[0:1]
	s_cbranch_execz .LBB0_317
	v_readlane_b32 s8, v253, 17
	v_lshlrev_b64 v[92:93], 8, v[96:97]
	v_readlane_b32 s9, v253, 18
	v_mov_b32_e32 v147, v1
	s_nop 0
	v_lshl_add_u64 v[92:93], s[8:9], 0, v[92:93]
	v_lshl_add_u64 v[92:93], v[92:93], 0, v[146:147]
	global_store_dwordx4 v[92:93], v[78:81], off
	global_store_dwordx4 v[92:93], v[74:77], off offset:64
	global_store_dwordx4 v[92:93], v[70:73], off offset:128
	global_store_dwordx4 v[92:93], v[66:69], off offset:192
	v_cvt_pk_bf16_f32 v92, v78, v79
	v_cvt_pk_bf16_f32 v93, v80, v102
	global_store_dwordx2 v[98:99], v[92:93], off offset:128
	v_cvt_pk_bf16_f32 v92, v74, v75
	v_cvt_pk_bf16_f32 v93, v76, v103
	global_store_dwordx2 v[98:99], v[92:93], off offset:160
	v_cvt_pk_bf16_f32 v92, v70, v71
	v_cvt_pk_bf16_f32 v93, v72, v100
	global_store_dwordx2 v[98:99], v[92:93], off offset:192
	v_cvt_pk_bf16_f32 v92, v66, v67
	v_cvt_pk_bf16_f32 v93, v68, v101
	global_store_dwordx2 v[98:99], v[92:93], off offset:224

.LBB0_364:
	v_mov_b32_e32 v147, v1
	v_cvt_pk_bf16_f32 v73, v70, v71
	v_lshl_add_u64 v[34:35], s[0:1], 0, v[146:147]
	global_store_dwordx2 v[74:75], v[72:73], off offset:96
	global_load_dwordx4 v[36:39], v[34:35], off
	global_load_dwordx4 v[68:71], v[34:35], off offset:64
	global_load_dwordx4 v[40:43], v[34:35], off offset:128
	s_nop 0
	global_load_dwordx4 v[72:75], v[34:35], off offset:192
	v_pk_mul_f32 v[44:45], v[10:11], v[10:11]
	v_pk_mul_f32 v[34:35], v[12:13], v[12:13]
	v_pk_fma_f32 v[44:45], v[14:15], v[14:15], v[44:45]
	v_pk_fma_f32 v[34:35], v[16:17], v[16:17], v[34:35]
	v_pk_fma_f32 v[44:45], v[6:7], v[6:7], v[44:45]
	v_pk_fma_f32 v[34:35], v[8:9], v[8:9], v[34:35]
	v_pk_fma_f32 v[44:45], v[2:3], v[2:3], v[44:45]
	v_pk_fma_f32 v[34:35], v[4:5], v[4:5], v[34:35]
	v_add_f32_e32 v0, v44, v45
	v_add_f32_e32 v0, v34, v0
	v_add_f32_e32 v0, v35, v0
	v_mov_b32_e32 v34, v0
	v_mov_b32_e32 v76, v17
	v_mov_b32_e32 v78, v9
	v_mov_b32_e32 v79, v5
	s_and_b64 vcc, exec, s[40:41]
	s_waitcnt lgkmcnt(0)
	s_nop 1
	v_permlane16_swap_b32_e32 v34, v0
	v_add_f32_e32 v0, v0, v34
	v_mov_b32_e32 v34, v0
	v_mov_b32_e32 v77, v13
	s_waitcnt lgkmcnt(0)
	s_nop 1
	v_permlane32_swap_b32_e32 v34, v0
	v_add_f32_e32 v0, v0, v34
	v_fmamk_f32 v0, v0, 0x3c800000, v178
	v_mul_f32_e32 v34, 0x4b800000, v0
	v_cmp_gt_f32_e64 s[0:1], s64, v0
	s_nop 1
	v_cndmask_b32_e64 v0, v0, v34, s[0:1]
	v_rsq_f32_e32 v0, v0
	s_nop 0
	v_mul_f32_e32 v34, 0x45800000, v0
	v_cndmask_b32_e64 v0, v0, v34, s[0:1]
	s_mov_b64 s[0:1], -1
	s_waitcnt vmcnt(3)
	v_pk_mul_f32 v[34:35], v[36:37], v[0:1] op_sel_hi:[1,0]
	s_waitcnt vmcnt(2)
	v_pk_mul_f32 v[36:37], v[68:69], v[0:1] op_sel_hi:[1,0]
	v_mul_f32_e32 v49, v70, v0
	s_waitcnt vmcnt(0)
	v_mul_f32_e32 v68, v74, v0
	v_mov_b32_e32 v70, v39
	v_mov_b32_e32 v74, v43
	v_pk_mul_f32 v[44:45], v[72:73], v[0:1] op_sel_hi:[1,0]
	v_mul_f32_e32 v51, v42, v0
	v_pk_mul_f32 v[42:43], v[10:11], v[36:37]
	v_mul_f32_e32 v36, v4, v68
	v_pk_mul_f32 v[68:69], v[70:71], v[0:1] op_sel_hi:[1,0]
	v_pk_mul_f32 v[72:73], v[74:75], v[0:1] op_sel_hi:[1,0]
	v_pk_mul_f32 v[40:41], v[40:41], v[0:1] op_sel_hi:[1,0]
	v_mul_f32_e32 v48, v38, v0
	v_pk_mul_f32 v[70:71], v[76:77], v[68:69]
	v_pk_mul_f32 v[68:69], v[78:79], v[72:73]
	v_pk_mul_f32 v[46:47], v[14:15], v[34:35]
	v_pk_mul_f32 v[38:39], v[6:7], v[40:41]
	v_pk_mul_f32 v[34:35], v[2:3], v[44:45]
	v_mul_f32_e32 v48, v16, v48
	v_mul_f32_e32 v44, v12, v49
	v_mul_f32_e32 v40, v8, v51
	v_mov_b32_e32 v49, v70
	v_mov_b32_e32 v45, v71
	v_mov_b32_e32 v41, v68
	v_mov_b32_e32 v37, v69
	s_cbranch_vccnz .LBB0_370
	s_and_saveexec_b64 s[0:1], s[44:45]
	s_xor_b64 s[0:1], exec, s[0:1]
	s_cbranch_execz .LBB0_367
	v_readlane_b32 s8, v253, 17
	v_lshlrev_b64 v[60:61], 8, v[64:65]
	v_readlane_b32 s9, v253, 18
	v_mov_b32_e32 v147, v1
	s_nop 0
	v_lshl_add_u64 v[60:61], s[8:9], 0, v[60:61]
	v_lshl_add_u64 v[60:61], v[60:61], 0, v[146:147]
	global_store_dwordx4 v[60:61], v[46:49], off
	global_store_dwordx4 v[60:61], v[42:45], off offset:64
	global_store_dwordx4 v[60:61], v[38:41], off offset:128
	global_store_dwordx4 v[60:61], v[34:37], off offset:192
	v_cvt_pk_bf16_f32 v60, v46, v47
	v_cvt_pk_bf16_f32 v61, v48, v70
	global_store_dwordx2 v[66:67], v[60:61], off offset:128
	v_cvt_pk_bf16_f32 v60, v42, v43
	v_cvt_pk_bf16_f32 v61, v44, v71
	global_store_dwordx2 v[66:67], v[60:61], off offset:160
	v_cvt_pk_bf16_f32 v60, v38, v39
	v_cvt_pk_bf16_f32 v61, v40, v68
	global_store_dwordx2 v[66:67], v[60:61], off offset:192
	v_cvt_pk_bf16_f32 v60, v34, v35
	v_cvt_pk_bf16_f32 v61, v36, v69
	global_store_dwordx2 v[66:67], v[60:61], off offset:224

.LBB0_508:
	s_lshl_b64 s[0:1], s[38:39], 11
	s_add_u32 s0, s10, s0
	s_addc_u32 s1, s13, s1
	s_lshl_b32 s8, s19, 1
	s_add_u32 s0, s0, s8
	s_addc_u32 s1, s1, 0
	v_lshlrev_b32_e32 v0, 1, v121
	v_lshl_add_u64 v[2:3], s[0:1], 0, v[0:1]
	ds_bpermute_b32 v0, v136, v124
	s_mov_b64 s[0:1], 0x2513db00
	v_lshl_add_u64 v[2:3], v[2:3], 0, s[0:1]
	s_waitcnt lgkmcnt(0)
	v_add_f32_e32 v0, v124, v0
	v_mov_b32_e32 v4, v0
	s_waitcnt lgkmcnt(0)
	s_nop 1
	v_permlane32_swap_b32_e32 v4, v0
	v_add_f32_e32 v0, v0, v4
	v_div_scale_f32 v4, s[0:1], v0, v0, 1.0
	v_rcp_f32_e32 v5, v4
	s_nop 0
	v_fma_f32 v6, -v4, v5, 1.0
	v_fmac_f32_e32 v5, v6, v5
	v_div_scale_f32 v6, vcc, 1.0, v0, 1.0
	v_mul_f32_e32 v7, v6, v5
	v_fma_f32 v8, -v4, v7, v6
	v_fmac_f32_e32 v7, v8, v5
	v_fma_f32 v4, -v4, v7, v6
	v_div_fmas_f32 v4, v4, v5, v7
	v_div_fixup_f32 v0, v4, v0, 1.0
	v_lshlrev_b64 v[4:5], 11, v[118:119]
	v_mul_f32_e32 v6, v80, v0
	v_mul_f32_e32 v7, v81, v0
	v_mul_f32_e32 v8, v82, v0
	v_mul_f32_e32 v9, v83, v0
	v_lshl_add_u64 v[4:5], v[2:3], 0, v[4:5]
	v_cvt_pk_bf16_f32 v6, v6, v7
	v_cvt_pk_bf16_f32 v7, v8, v9
	global_store_dwordx2 v[4:5], v[6:7], off
	v_mul_f32_e32 v6, v76, v0
	v_mul_f32_e32 v7, v77, v0
	v_mul_f32_e32 v8, v78, v0
	v_mul_f32_e32 v9, v79, v0
	v_cvt_pk_bf16_f32 v6, v6, v7
	v_cvt_pk_bf16_f32 v7, v8, v9
	global_store_dwordx2 v[4:5], v[6:7], off offset:32
	v_mul_f32_e32 v6, v72, v0
	v_mul_f32_e32 v7, v73, v0
	v_mul_f32_e32 v8, v74, v0
	v_mul_f32_e32 v9, v75, v0
	v_cvt_pk_bf16_f32 v6, v6, v7
	v_cvt_pk_bf16_f32 v7, v8, v9
	global_store_dwordx2 v[4:5], v[6:7], off offset:64
	v_mul_f32_e32 v6, v68, v0
	v_mul_f32_e32 v7, v69, v0
	v_mul_f32_e32 v8, v70, v0
	v_mul_f32_e32 v0, v71, v0
	v_cvt_pk_bf16_f32 v6, v6, v7
	v_cvt_pk_bf16_f32 v7, v8, v0
	ds_bpermute_b32 v0, v136, v125
	global_store_dwordx2 v[4:5], v[6:7], off offset:96
	s_waitcnt lgkmcnt(0)
	v_add_f32_e32 v0, v125, v0
	v_mov_b32_e32 v4, v0
	s_waitcnt lgkmcnt(0)
	s_nop 1
	v_permlane32_swap_b32_e32 v4, v0
	v_add_f32_e32 v0, v0, v4
	v_div_scale_f32 v4, s[0:1], v0, v0, 1.0
	v_rcp_f32_e32 v5, v4
	s_mov_b64 s[0:1], 0
	v_fma_f32 v6, -v4, v5, 1.0
	v_fmac_f32_e32 v5, v6, v5
	v_div_scale_f32 v6, vcc, 1.0, v0, 1.0
	v_mul_f32_e32 v7, v6, v5
	v_fma_f32 v8, -v4, v7, v6
	v_fmac_f32_e32 v7, v8, v5
	v_fma_f32 v4, -v4, v7, v6
	v_div_fmas_f32 v4, v4, v5, v7
	v_div_fixup_f32 v0, v4, v0, 1.0
	v_lshlrev_b64 v[4:5], 11, v[116:117]
	v_lshl_add_u64 v[2:3], v[2:3], 0, v[4:5]
	v_mul_f32_e32 v4, v64, v0
	v_mul_f32_e32 v5, v65, v0
	v_mul_f32_e32 v6, v66, v0
	v_mul_f32_e32 v7, v67, v0
	v_cvt_pk_bf16_f32 v4, v4, v5
	v_cvt_pk_bf16_f32 v5, v6, v7
	global_store_dwordx2 v[2:3], v[4:5], off
	v_mul_f32_e32 v4, v60, v0
	v_mul_f32_e32 v5, v61, v0
	v_mul_f32_e32 v6, v62, v0
	v_mul_f32_e32 v7, v63, v0
	v_cvt_pk_bf16_f32 v4, v4, v5
	v_cvt_pk_bf16_f32 v5, v6, v7
	global_store_dwordx2 v[2:3], v[4:5], off offset:32
	v_mul_f32_e32 v4, v56, v0
	v_mul_f32_e32 v5, v57, v0
	v_mul_f32_e32 v6, v58, v0
	v_mul_f32_e32 v7, v59, v0
	v_cvt_pk_bf16_f32 v4, v4, v5
	v_cvt_pk_bf16_f32 v5, v6, v7
	global_store_dwordx2 v[2:3], v[4:5], off offset:64
	v_mul_f32_e32 v4, v52, v0
	v_mul_f32_e32 v5, v53, v0
	v_mul_f32_e32 v6, v54, v0
	v_mul_f32_e32 v0, v55, v0
	v_cvt_pk_bf16_f32 v4, v4, v5
	v_cvt_pk_bf16_f32 v5, v6, v0
	global_store_dwordx2 v[2:3], v[4:5], off offset:96

.LBB0_581:
	v_cmp_lt_i32_e32 vcc, v135, v134
	s_lshl_b32 s8, s75, 6
	s_lshl_b64 s[0:1], s[0:1], 11
	v_cndmask_b32_e32 v0, v85, v135, vcc
	v_lshlrev_b32_e32 v0, 2, v0
	ds_bpermute_b32 v2, v0, v124
	v_cmp_lt_i32_e32 vcc, v136, v134
	s_add_u32 s0, s22, s0
	s_addc_u32 s1, s73, s1
	v_cndmask_b32_e32 v3, v85, v136, vcc
	s_waitcnt vmcnt(2)
	v_lshlrev_b32_e32 v8, 2, v3
	s_waitcnt lgkmcnt(0)
	v_add_f32_e32 v2, v124, v2
	ds_bpermute_b32 v3, v8, v2
	s_lshl_b32 s8, s8, 1
	s_add_u32 s0, s0, s8
	s_addc_u32 s1, s1, 0
	v_mov_b32_e32 v85, v1
	s_waitcnt lgkmcnt(0)
	v_add_f32_e32 v4, v2, v3
	v_div_scale_f32 v5, s[8:9], v4, v4, 1.0
	v_rcp_f32_e32 v6, v5
	v_lshl_add_u64 v[2:3], v[84:85], 1, s[0:1]
	s_mov_b64 s[0:1], 0x2513db00
	v_lshl_add_u64 v[2:3], v[2:3], 0, s[0:1]
	v_fma_f32 v7, -v5, v6, 1.0
	v_fmac_f32_e32 v6, v7, v6
	v_div_scale_f32 v7, vcc, 1.0, v4, 1.0
	v_mul_f32_e32 v9, v7, v6
	v_fma_f32 v10, -v5, v9, v7
	v_fmac_f32_e32 v9, v10, v6
	v_fma_f32 v5, -v5, v9, v7
	v_div_fmas_f32 v5, v5, v6, v9
	v_div_fixup_f32 v9, v5, v4, 1.0
	v_lshlrev_b64 v[4:5], 11, v[118:119]
	v_mul_f32_e32 v6, v80, v9
	v_mul_f32_e32 v7, v81, v9
	v_mul_f32_e32 v10, v82, v9
	v_mul_f32_e32 v11, v83, v9
	ds_bpermute_b32 v0, v0, v125
	v_lshl_add_u64 v[4:5], v[2:3], 0, v[4:5]
	v_cvt_pk_bf16_f32 v6, v6, v7
	v_cvt_pk_bf16_f32 v7, v10, v11
	global_store_dwordx2 v[4:5], v[6:7], off
	v_mul_f32_e32 v6, v76, v9
	v_mul_f32_e32 v7, v77, v9
	v_mul_f32_e32 v10, v78, v9
	v_mul_f32_e32 v11, v79, v9
	v_cvt_pk_bf16_f32 v6, v6, v7
	v_cvt_pk_bf16_f32 v7, v10, v11
	global_store_dwordx2 v[4:5], v[6:7], off offset:32
	v_mul_f32_e32 v6, v72, v9
	v_mul_f32_e32 v7, v73, v9
	v_mul_f32_e32 v10, v74, v9
	v_mul_f32_e32 v11, v75, v9
	v_cvt_pk_bf16_f32 v6, v6, v7
	v_cvt_pk_bf16_f32 v7, v10, v11
	s_waitcnt lgkmcnt(0)
	v_add_f32_e32 v0, v125, v0
	global_store_dwordx2 v[4:5], v[6:7], off offset:64
	v_mov_b32_e32 v6, v0
	v_mul_f32_e32 v7, v68, v9
	v_mul_f32_e32 v8, v69, v9
	v_mul_f32_e32 v10, v70, v9
	v_mul_f32_e32 v9, v71, v9
	s_waitcnt lgkmcnt(0)
	s_nop 1
	v_permlane32_swap_b32_e32 v6, v0
	v_add_f32_e32 v0, v0, v6
	v_div_scale_f32 v11, s[0:1], v0, v0, 1.0
	v_rcp_f32_e32 v12, v11
	v_cvt_pk_bf16_f32 v6, v7, v8
	v_cvt_pk_bf16_f32 v7, v10, v9
	global_store_dwordx2 v[4:5], v[6:7], off offset:96
	v_fma_f32 v4, -v11, v12, 1.0
	v_fmac_f32_e32 v12, v4, v12
	v_div_scale_f32 v4, vcc, 1.0, v0, 1.0
	v_mul_f32_e32 v5, v4, v12
	v_fma_f32 v6, -v11, v5, v4
	v_fmac_f32_e32 v5, v6, v12
	v_fma_f32 v4, -v11, v5, v4
	v_div_fmas_f32 v4, v4, v12, v5
	v_div_fixup_f32 v0, v4, v0, 1.0
	v_lshlrev_b64 v[4:5], 11, v[116:117]
	v_lshl_add_u64 v[2:3], v[2:3], 0, v[4:5]
	v_mul_f32_e32 v4, v60, v0
	v_mul_f32_e32 v5, v61, v0
	v_mul_f32_e32 v6, v62, v0
	v_mul_f32_e32 v7, v63, v0
	v_cvt_pk_bf16_f32 v4, v4, v5
	v_cvt_pk_bf16_f32 v5, v6, v7
	global_store_dwordx2 v[2:3], v[4:5], off
	v_mul_f32_e32 v4, v56, v0
	v_mul_f32_e32 v5, v57, v0
	v_mul_f32_e32 v6, v58, v0
	v_mul_f32_e32 v7, v59, v0
	v_cvt_pk_bf16_f32 v4, v4, v5
	v_cvt_pk_bf16_f32 v5, v6, v7
	global_store_dwordx2 v[2:3], v[4:5], off offset:32
	v_mul_f32_e32 v4, v52, v0
	v_mul_f32_e32 v5, v53, v0
	v_mul_f32_e32 v6, v54, v0
	v_mul_f32_e32 v7, v55, v0
	v_cvt_pk_bf16_f32 v4, v4, v5
	v_cvt_pk_bf16_f32 v5, v6, v7
	global_store_dwordx2 v[2:3], v[4:5], off offset:64
	v_mul_f32_e32 v4, v64, v0
	v_mul_f32_e32 v5, v65, v0
	v_mul_f32_e32 v6, v66, v0
	v_mul_f32_e32 v0, v67, v0
	s_mov_b32 s76, s3
	v_cvt_pk_bf16_f32 v4, v4, v5
	v_cvt_pk_bf16_f32 v5, v6, v0
	s_mov_b32 s75, s2
	s_movk_i32 s68, 0x2000
	s_movk_i32 s73, 0x5fff
	global_store_dwordx2 v[2:3], v[4:5], off offset:96

.LBB0_762:
	s_or_b64 exec, exec, s[0:1]
	v_lshl_add_u64 v[16:17], v[16:17], 0, v[0:1]
	global_load_dwordx4 v[24:27], v[16:17], off
	global_load_dwordx4 v[28:31], v[16:17], off offset:1024
	global_load_dwordx4 v[32:35], v[16:17], off offset:2048
	global_load_dwordx4 v[36:39], v[16:17], off offset:3072
	v_lshrrev_b32_e32 v9, 12, v14
	v_add_u32_e32 v9, 1, v9
	v_mov_b64_e32 v[14:15], s[20:21]
	v_cndmask_b32_e64 v9, v9, 0, vcc
	s_waitcnt vmcnt(13)
	v_mad_u64_u32 v[44:45], s[0:1], v9, s29, v[14:15]
	s_waitcnt vmcnt(12)
	v_lshl_add_u64 v[48:49], v[44:45], 0, s[96:97]
	v_lshl_add_u64 v[14:15], v[48:49], 0, v[0:1]
	global_load_dwordx4 v[14:17], v[14:15], off
	s_nop 0
	global_load_dwordx4 v[40:43], v[4:5], off
	v_lshl_add_u64 v[50:51], v[44:45], 0, v[0:1]
	global_load_dwordx4 v[44:47], v[50:51], off
	s_waitcnt vmcnt(6)
	v_mov_b32_e32 v58, v25
	s_waitcnt vmcnt(5)
	v_mov_b32_e32 v59, v29
	v_mov_b32_e32 v56, v24
	v_mov_b32_e32 v57, v28
	s_waitcnt vmcnt(4)
	v_mov_b32_e32 v66, v33
	s_waitcnt vmcnt(3)
	v_mov_b32_e32 v67, v37
	v_pk_mul_f32 v[58:59], v[58:59], v[58:59]
	v_mov_b32_e32 v52, v26
	v_mov_b32_e32 v53, v30
	v_mov_b32_e32 v64, v32
	v_mov_b32_e32 v65, v36
	v_pk_mul_f32 v[66:67], v[66:67], v[66:67]
	v_pk_fma_f32 v[56:57], v[56:57], v[56:57], v[58:59]
	v_mov_b32_e32 v54, v27
	v_mov_b32_e32 v55, v31
	v_mov_b32_e32 v60, v34
	v_mov_b32_e32 v61, v38
	v_pk_fma_f32 v[58:59], v[64:65], v[64:65], v[66:67]
	v_pk_fma_f32 v[52:53], v[52:53], v[52:53], v[56:57]
	v_mov_b32_e32 v62, v35
	v_mov_b32_e32 v63, v39
	v_pk_fma_f32 v[56:57], v[60:61], v[60:61], v[58:59]
	v_pk_fma_f32 v[52:53], v[54:55], v[54:55], v[52:53]
	v_pk_fma_f32 v[54:55], v[62:63], v[62:63], v[56:57]
	v_add_f32_e32 v9, v52, v53
	v_add_f32_e32 v9, v9, v54
	v_add_f32_e32 v9, v9, v55
	v_mov_b32_e32 v11, v9
	v_lshlrev_b64 v[52:53], 11, v[2:3]
	s_waitcnt vmcnt(2)
	v_pk_add_f32 v[16:17], v[16:17], 1.0 op_sel_hi:[1,0]
	v_pk_add_f32 v[14:15], v[14:15], 1.0 op_sel_hi:[1,0]
	v_lshl_add_u64 v[52:53], v[6:7], 0, v[52:53]
	s_waitcnt lgkmcnt(0)
	s_nop 1
	v_permlane32_swap_b32_e32 v11, v9
	v_add_f32_e32 v9, v9, v11
	v_mov_b32_e32 v11, v9
	v_add_u32_e32 v2, s30, v2
	s_waitcnt lgkmcnt(0)
	s_nop 1
	v_permlane16_swap_b32_e32 v11, v9
	v_add_f32_e32 v9, v9, v11
	s_waitcnt lgkmcnt(0)
	s_nop 1
	v_add_f32_dpp v9, v9, v9 row_ror:8 row_mask:0xf bank_mask:0xf
	ds_bpermute_b32 v11, v21, v9
	s_waitcnt lgkmcnt(0)
	v_add_f32_e32 v9, v9, v11
	ds_bpermute_b32 v11, v22, v9
	s_waitcnt lgkmcnt(0)
	v_add_f32_e32 v11, v9, v11
	ds_bpermute_b32 v13, v23, v11
	v_mov_b32_e32 v9, v1
	v_lshl_add_u64 v[54:55], v[48:49], 0, v[8:9]
	s_waitcnt lgkmcnt(0)
	v_add_f32_e32 v3, v11, v13
	v_fmamk_f32 v3, v3, 0x3a800000, v178
	v_mul_f32_e32 v11, 0x4b800000, v3
	v_cmp_gt_f32_e32 vcc, s64, v3
	v_mov_b32_e32 v13, v1
	s_nop 0
	v_cndmask_b32_e32 v3, v3, v11, vcc
	v_rsq_f32_e32 v3, v3
	v_mov_b32_e32 v11, v1
	v_mul_f32_e32 v9, 0x45800000, v3
	v_cndmask_b32_e32 v56, v3, v9, vcc
	v_pk_mul_f32 v[24:25], v[24:25], v[56:57] op_sel_hi:[1,0]
	v_pk_mul_f32 v[26:27], v[26:27], v[56:57] op_sel_hi:[1,0]
	s_waitcnt vmcnt(1)
	v_pk_mul_f32 v[24:25], v[40:41], v[24:25]
	v_pk_mul_f32 v[26:27], v[42:43], v[26:27]
	s_waitcnt vmcnt(0)
	v_pk_fma_f32 v[14:15], v[14:15], v[24:25], v[44:45]
	v_pk_fma_f32 v[16:17], v[16:17], v[26:27], v[46:47]
	v_cvt_pk_bf16_f32 v14, v14, v15
	v_cvt_pk_bf16_f32 v15, v16, v17
	global_store_dwordx2 v[52:53], v[14:15], off
	global_load_dwordx4 v[14:17], v[4:5], off offset:1024
	s_nop 0
	global_load_dwordx4 v[24:27], v[54:55], off
	global_load_dwordx4 v[40:43], v[50:51], off offset:1024
	v_pk_mul_f32 v[28:29], v[28:29], v[56:57] op_sel_hi:[1,0]
	v_pk_mul_f32 v[30:31], v[30:31], v[56:57] op_sel_hi:[1,0]
	v_lshl_add_u64 v[44:45], v[48:49], 0, v[10:11]
	v_pk_mul_f32 v[32:33], v[32:33], v[56:57] op_sel_hi:[1,0]
	v_pk_mul_f32 v[34:35], v[34:35], v[56:57] op_sel_hi:[1,0]
	v_cmp_lt_i32_e32 vcc, s73, v2
	s_or_b64 s[22:23], vcc, s[22:23]
	s_waitcnt vmcnt(2)
	v_pk_mul_f32 v[14:15], v[28:29], v[14:15]
	s_waitcnt vmcnt(1)
	v_pk_add_f32 v[24:25], v[24:25], 1.0 op_sel_hi:[1,0]
	v_pk_mul_f32 v[16:17], v[30:31], v[16:17]
	v_pk_add_f32 v[26:27], v[26:27], 1.0 op_sel_hi:[1,0]
	s_waitcnt vmcnt(0)
	v_pk_fma_f32 v[14:15], v[14:15], v[24:25], v[40:41]
	v_pk_fma_f32 v[16:17], v[16:17], v[26:27], v[42:43]
	v_cvt_pk_bf16_f32 v14, v14, v15
	v_cvt_pk_bf16_f32 v15, v16, v17
	global_store_dwordx2 v[52:53], v[14:15], off offset:512
	global_load_dwordx4 v[14:17], v[4:5], off offset:2048
	s_nop 0
	global_load_dwordx4 v[24:27], v[44:45], off
	global_load_dwordx4 v[28:31], v[50:51], off offset:2048
	v_lshl_add_u64 v[40:41], v[48:49], 0, v[12:13]
	s_waitcnt vmcnt(2)
	v_pk_mul_f32 v[14:15], v[32:33], v[14:15]
	s_waitcnt vmcnt(1)
	v_pk_add_f32 v[24:25], v[24:25], 1.0 op_sel_hi:[1,0]
	v_pk_mul_f32 v[16:17], v[34:35], v[16:17]
	v_pk_add_f32 v[26:27], v[26:27], 1.0 op_sel_hi:[1,0]
	s_waitcnt vmcnt(0)
	v_pk_fma_f32 v[14:15], v[14:15], v[24:25], v[28:29]
	v_pk_fma_f32 v[16:17], v[16:17], v[26:27], v[30:31]
	v_cvt_pk_bf16_f32 v14, v14, v15
	v_cvt_pk_bf16_f32 v15, v16, v17
	global_store_dwordx2 v[52:53], v[14:15], off offset:1024
	global_load_dwordx4 v[14:17], v[4:5], off offset:3072
	s_nop 0
	global_load_dwordx4 v[24:27], v[40:41], off
	global_load_dwordx4 v[28:31], v[50:51], off offset:3072
	v_pk_mul_f32 v[32:33], v[36:37], v[56:57] op_sel_hi:[1,0]
	v_pk_mul_f32 v[34:35], v[38:39], v[56:57] op_sel_hi:[1,0]
	s_waitcnt vmcnt(2)
	v_pk_mul_f32 v[14:15], v[32:33], v[14:15]
	s_waitcnt vmcnt(1)
	v_pk_add_f32 v[24:25], v[24:25], 1.0 op_sel_hi:[1,0]
	v_pk_mul_f32 v[16:17], v[34:35], v[16:17]
	v_pk_add_f32 v[26:27], v[26:27], 1.0 op_sel_hi:[1,0]
	s_waitcnt vmcnt(0)
	v_pk_fma_f32 v[14:15], v[14:15], v[24:25], v[28:29]
	v_pk_fma_f32 v[16:17], v[16:17], v[26:27], v[30:31]
	v_cvt_pk_bf16_f32 v14, v14, v15
	v_cvt_pk_bf16_f32 v15, v16, v17
	global_store_dwordx2 v[52:53], v[14:15], off offset:1536
	s_andn2_b64 exec, exec, s[22:23]
	s_cbranch_execz .LBB0_767

.LBB0_1244:
	s_or_saveexec_b64 s[8:9], s[8:9]
	v_mov_b64_e32 v[134:135], 0x1a33d700
	s_xor_b64 exec, exec, s[8:9]
	v_mov_b64_e32 v[130:131], s[22:23]
	v_mad_i64_i32 v[130:131], s[34:35], v170, s56, v[130:131]
	v_ashrrev_i32_e32 v171, 31, v170
	s_mov_b64 s[34:35], 0x1243df00
	v_lshl_add_u64 v[130:131], v[130:131], 0, s[34:35]
	v_mov_b32_e32 v162, 0
	v_mov_b64_e32 v[134:135], 0x1c73d700
	s_andn2_b64 s[20:21], s[20:21], exec
	v_mov_b64_e32 v[132:133], v[170:171]
	s_or_b64 exec, exec, s[8:9]
	v_and_b32_e32 v137, 64, v215
	v_lshrrev_b32_e32 v0, 2, v136
	v_xor_b32_e32 v136, 16, v215
	v_add_u32_e32 v137, 64, v137
	v_cmp_lt_i32_e32 vcc, v136, v137
	v_and_b32_e32 v163, 12, v0
	v_lshlrev_b32_e32 v0, 2, v163
	v_cndmask_b32_e32 v136, v215, v136, vcc
	v_lshlrev_b32_e32 v171, 2, v136
	v_xor_b32_e32 v136, 32, v215
	v_cmp_lt_i32_e32 vcc, v136, v137
	s_mov_b64 s[8:9], 0x7b700
	v_lshl_add_u64 v[134:135], s[22:23], 0, v[134:135]
	v_cndmask_b32_e32 v136, v215, v136, vcc
	v_lshlrev_b32_e32 v196, 2, v136
	v_lshl_add_u64 v[136:137], s[22:23], 0, v[0:1]
	v_lshl_add_u64 v[166:167], v[136:137], 0, s[8:9]
	s_mov_b64 s[8:9], 0x7c700
	v_lshlrev_b64 v[132:133], 11, v[132:133]
	v_lshl_add_u64 v[138:139], v[130:131], 0, v[0:1]
	v_lshl_add_u64 v[168:169], v[136:137], 0, s[8:9]
	v_lshl_add_u64 v[164:165], v[134:135], 0, v[132:133]
	global_load_dwordx4 v[130:133], v[138:139], off
	global_load_dwordx4 v[134:137], v[138:139], off offset:64
	global_load_dwordx4 v[142:145], v[138:139], off offset:128
	s_nop 0
	global_load_dwordx4 v[138:141], v[138:139], off offset:192
	v_lshlrev_b32_e32 v172, 1, v163
	v_mov_b32_e32 v173, v1
	v_lshl_add_u64 v[164:165], v[164:165], 0, v[172:173]
	s_waitcnt vmcnt(4)
	v_and_b32_e32 v174, 0xfc0, v162
	v_mov_b32_e32 v175, v1
	v_lshl_add_u64 v[184:185], v[166:167], 0, v[174:175]
	v_lshl_add_u64 v[180:181], v[168:169], 0, v[174:175]
	v_lshlrev_b32_e32 v162, 6, v162
	v_pk_mul_f32 v[174:175], v[118:119], v[118:119]
	v_and_b32_e32 v162, 0x3c0, v162
	v_mov_b32_e32 v163, v1
	v_lshl_add_u64 v[182:183], v[166:167], 0, v[162:163]
	v_lshl_add_u64 v[176:177], v[168:169], 0, v[162:163]
	v_pk_mul_f32 v[162:163], v[120:121], v[120:121]
	s_lshl_b32 s38, s62, 2
	s_waitcnt vmcnt(2)
	v_mul_f32_e32 v146, v134, v134
	v_mul_f32_e32 v147, v135, v135
	v_fmac_f32_e32 v146, v130, v130
	v_fmac_f32_e32 v147, v131, v131
	s_waitcnt vmcnt(1)
	v_fmac_f32_e32 v146, v142, v142
	v_fmac_f32_e32 v147, v143, v143
	s_waitcnt vmcnt(0)
	v_fmac_f32_e32 v146, v138, v138
	v_fmac_f32_e32 v147, v139, v139
	v_add_f32_e32 v146, v146, v147
	v_mul_f32_e32 v147, v136, v136
	v_fmac_f32_e32 v147, v132, v132
	v_fmac_f32_e32 v147, v144, v144
	v_fmac_f32_e32 v147, v140, v140
	v_add_f32_e32 v146, v147, v146
	v_mul_f32_e32 v147, v137, v137
	v_fmac_f32_e32 v147, v133, v133
	v_fmac_f32_e32 v147, v145, v145
	v_fmac_f32_e32 v147, v141, v141
	v_add_f32_e32 v197, v147, v146
	v_fma_f32 v173, v126, v126, v197
	v_fmac_f32_e32 v173, v127, v127
	v_fmac_f32_e32 v173, v128, v128
	v_fmac_f32_e32 v173, v129, v129
	v_fmac_f32_e32 v173, v122, v122
	v_fmac_f32_e32 v173, v123, v123
	v_fmac_f32_e32 v173, v124, v124
	v_fmac_f32_e32 v173, v125, v125
	v_add_f32_e32 v173, v174, v173
	v_add_f32_e32 v173, v175, v173
	v_add_f32_e32 v162, v162, v173
	v_add_f32_e32 v173, v163, v162
	v_pk_mul_f32 v[174:175], v[114:115], v[114:115]
	v_pk_mul_f32 v[162:163], v[116:117], v[116:117]
	v_add_f32_e32 v173, v174, v173
	v_add_f32_e32 v173, v175, v173
	v_add_f32_e32 v162, v162, v173
	v_add_f32_e32 v162, v163, v162
	v_mov_b32_e32 v163, v162
	global_load_dwordx4 v[146:149], v0, s[72:73] offset:256
	global_load_dwordx4 v[150:153], v0, s[72:73] offset:320
	global_load_dwordx4 v[154:157], v0, s[72:73] offset:384
	global_load_dwordx4 v[158:161], v0, s[72:73] offset:448
	v_lshl_add_u64 v[174:175], v[164:165], 0, s[38:39]
	s_waitcnt lgkmcnt(0)
	s_nop 1
	v_permlane16_swap_b32_e32 v163, v162
	v_add_f32_e32 v162, v162, v163
	v_mov_b32_e32 v163, v162
	s_waitcnt lgkmcnt(0)
	s_nop 1
	v_permlane32_swap_b32_e32 v163, v162
	v_add_f32_e32 v162, v162, v163
	v_fmamk_f32 v162, v162, 0x3c000000, v178
	v_cmp_gt_f32_e32 vcc, s64, v162
	v_mul_f32_e32 v163, 0x4b800000, v162
	s_nop 0
	v_cndmask_b32_e32 v162, v162, v163, vcc
	v_rsq_f32_e32 v162, v162
	s_nop 0
	v_mul_f32_e32 v163, 0x45800000, v162
	v_cndmask_b32_e32 v186, v162, v163, vcc
	global_load_dwordx4 v[162:165], v0, s[72:73]
	s_waitcnt vmcnt(0)
	v_pk_mul_f32 v[162:163], v[162:163], v[186:187] op_sel_hi:[1,0]
	s_nop 0
	v_pk_mul_f32 v[126:127], v[126:127], v[162:163]
	v_pk_mul_f32 v[162:163], v[164:165], v[186:187] op_sel_hi:[1,0]
	v_cvt_pk_bf16_f32 v126, v126, v127
	v_pk_mul_f32 v[128:129], v[128:129], v[162:163]
	s_nop 0
	v_cvt_pk_bf16_f32 v127, v128, v129
	global_store_dwordx2 v[174:175], v[126:127], off
	global_load_dwordx4 v[126:129], v0, s[72:73] offset:64
	s_waitcnt vmcnt(0)
	v_pk_mul_f32 v[126:127], v[126:127], v[186:187] op_sel_hi:[1,0]
	s_nop 0
	v_pk_mul_f32 v[122:123], v[122:123], v[126:127]
	v_pk_mul_f32 v[126:127], v[128:129], v[186:187] op_sel_hi:[1,0]
	v_cvt_pk_bf16_f32 v122, v122, v123
	v_pk_mul_f32 v[124:125], v[124:125], v[126:127]
	v_mov_b32_e32 v128, v157
	v_cvt_pk_bf16_f32 v123, v124, v125
	global_store_dwordx2 v[174:175], v[122:123], off offset:32
	global_load_dwordx4 v[122:125], v0, s[72:73] offset:128
	v_mov_b32_e32 v129, v161
	s_waitcnt vmcnt(0)
	v_pk_mul_f32 v[122:123], v[122:123], v[186:187] op_sel_hi:[1,0]
	s_nop 0
	v_pk_mul_f32 v[118:119], v[118:119], v[122:123]
	v_pk_mul_f32 v[122:123], v[124:125], v[186:187] op_sel_hi:[1,0]
	v_cvt_pk_bf16_f32 v118, v118, v119
	v_pk_mul_f32 v[120:121], v[120:121], v[122:123]
	s_nop 0
	v_cvt_pk_bf16_f32 v119, v120, v121
	global_store_dwordx2 v[174:175], v[118:119], off offset:64
	global_load_dwordx4 v[118:121], v0, s[72:73] offset:192
	s_waitcnt vmcnt(0)
	v_pk_mul_f32 v[118:119], v[118:119], v[186:187] op_sel_hi:[1,0]
	s_nop 0
	v_pk_mul_f32 v[114:115], v[114:115], v[118:119]
	v_pk_mul_f32 v[118:119], v[120:121], v[186:187] op_sel_hi:[1,0]
	v_cvt_pk_bf16_f32 v114, v114, v115
	v_pk_mul_f32 v[116:117], v[116:117], v[118:119]
	v_mov_b32_e32 v120, v149
	v_cvt_pk_bf16_f32 v115, v116, v117
	global_store_dwordx2 v[174:175], v[114:115], off offset:96
	v_pk_mul_f32 v[114:115], v[130:131], v[186:187] op_sel_hi:[1,0]
	v_mov_b32_e32 v121, v153
	v_pk_mul_f32 v[124:125], v[146:147], v[114:115]
	v_pk_mul_f32 v[114:115], v[134:135], v[186:187] op_sel_hi:[1,0]
	s_nop 0
	v_pk_mul_f32 v[122:123], v[150:151], v[114:115]
	v_pk_mul_f32 v[114:115], v[142:143], v[186:187] op_sel_hi:[1,0]
	s_nop 0
	v_pk_mul_f32 v[118:119], v[154:155], v[114:115]
	v_pk_mul_f32 v[114:115], v[138:139], v[186:187] op_sel_hi:[1,0]
	s_nop 0
	v_pk_mul_f32 v[116:117], v[158:159], v[114:115]
	v_mul_f32_e32 v114, v132, v186
	v_mul_f32_e32 v164, v148, v114
	v_mul_f32_e32 v114, v136, v186
	v_mul_f32_e32 v188, v152, v114
	v_mul_f32_e32 v114, v144, v186
	v_mul_f32_e32 v190, v156, v114
	v_mul_f32_e32 v114, v140, v186
	v_mul_f32_e32 v192, v160, v114
	v_mov_b32_e32 v114, v133
	v_mov_b32_e32 v115, v137
	v_pk_mul_f32 v[126:127], v[114:115], v[186:187] op_sel_hi:[1,0]
	s_nop 0
	v_pk_mul_f32 v[194:195], v[120:121], v[126:127]
	v_mov_b32_e32 v126, v145
	v_mov_b32_e32 v127, v141
	v_pk_mul_f32 v[162:163], v[126:127], v[186:187] op_sel_hi:[1,0]
	s_nop 0
	v_pk_mul_f32 v[186:187], v[128:129], v[162:163]
	s_and_saveexec_b64 s[8:9], s[20:21]
	s_cbranch_execz .LBB0_1248
	global_load_dwordx4 v[198:201], v[184:185], off
	global_load_dwordx4 v[202:205], v[180:181], off
	global_load_dwordx4 v[206:209], v[182:183], off
	global_load_dwordx4 v[216:219], v[176:177], off
	s_waitcnt vmcnt(3)
	v_mul_f32_e32 v228, v164, v200
	s_waitcnt vmcnt(2)
	v_pk_mul_f32 v[162:163], v[122:123], v[202:203]
	v_mul_f32_e32 v230, v188, v204
	v_mul_f32_e32 v188, v188, v200
	v_mov_b32_e32 v200, v205
	v_pk_mul_f32 v[202:203], v[124:125], v[202:203]
	s_waitcnt vmcnt(0)
	v_mul_f32_e32 v236, v192, v218
	v_mul_f32_e32 v238, v190, v218
	v_pk_fma_f32 v[124:125], v[124:125], v[198:199], v[162:163] neg_lo:[0,0,1] neg_hi:[0,0,1]
	v_pk_mul_f32 v[162:163], v[194:195], v[200:201]
	v_mov_b32_e32 v218, v209
	v_mul_f32_e32 v232, v164, v204
	v_mul_f32_e32 v234, v190, v208
	v_mul_f32_e32 v192, v192, v208
	v_mov_b32_e32 v204, v201
	v_mov_b32_e32 v189, v163
	v_mov_b32_e32 v233, v162
	v_pk_mul_f32 v[162:163], v[186:187], v[218:219]
	v_mov_b32_e32 v208, v219
	v_pk_mul_f32 v[164:165], v[194:195], v[204:205]
	v_mov_b32_e32 v235, v162
	v_mov_b32_e32 v237, v163
	v_pk_mul_f32 v[162:163], v[186:187], v[208:209]
	v_mov_b32_e32 v229, v164
	v_mov_b32_e32 v231, v165
	v_mov_b32_e32 v193, v163
	v_mov_b32_e32 v239, v162
	v_pk_mul_f32 v[226:227], v[116:117], v[216:217]
	v_pk_mul_f32 v[216:217], v[118:119], v[216:217]
	v_pk_add_f32 v[164:165], v[228:229], v[230:231] neg_lo:[0,1] neg_hi:[0,1]
	v_pk_add_f32 v[188:189], v[188:189], v[232:233]
	v_pk_add_f32 v[190:191], v[234:235], v[236:237] neg_lo:[0,1] neg_hi:[0,1]
	v_pk_add_f32 v[192:193], v[192:193], v[238:239]
	v_pk_fma_f32 v[122:123], v[122:123], v[198:199], v[202:203]
	v_pk_fma_f32 v[118:119], v[118:119], v[206:207], v[226:227] neg_lo:[0,0,1] neg_hi:[0,0,1]
	v_pk_fma_f32 v[116:117], v[116:117], v[206:207], v[216:217]
	v_mov_b32_e32 v194, v165
	v_mov_b32_e32 v195, v189
	v_mov_b32_e32 v186, v191
	v_mov_b32_e32 v187, v193
.LBB0_1248:
	s_or_b64 exec, exec, s[8:9]
	v_cvt_pk_bf16_f32 v124, v124, v125
	v_cvt_pk_bf16_f32 v125, v164, v194
	v_cvt_pk_bf16_f32 v122, v122, v123
	v_cvt_pk_bf16_f32 v123, v188, v195
	v_cvt_pk_bf16_f32 v118, v118, v119
	v_cvt_pk_bf16_f32 v119, v190, v186
	v_cvt_pk_bf16_f32 v116, v116, v117
	v_cvt_pk_bf16_f32 v117, v192, v187
	v_lshl_add_u64 v[162:163], s[72:73], 0, v[0:1]
	global_store_dwordx2 v[174:175], v[124:125], off offset:128
	global_store_dwordx2 v[174:175], v[122:123], off offset:160
	global_store_dwordx2 v[174:175], v[118:119], off offset:192
	global_store_dwordx2 v[174:175], v[116:117], off offset:224
	global_load_dwordx4 v[116:119], v[162:163], off
	v_fmac_f32_e32 v197, v110, v110
	v_fmac_f32_e32 v197, v111, v111
	v_fmac_f32_e32 v197, v112, v112
	v_fmac_f32_e32 v197, v113, v113
	v_fmac_f32_e32 v197, v106, v106
	v_fmac_f32_e32 v197, v107, v107
	v_fmac_f32_e32 v197, v108, v108
	v_pk_mul_f32 v[124:125], v[102:103], v[102:103]
	v_fmac_f32_e32 v197, v109, v109
	v_add_f32_e32 v124, v124, v197
	v_pk_mul_f32 v[122:123], v[104:105], v[104:105]
	v_add_f32_e32 v124, v125, v124
	v_add_f32_e32 v122, v122, v124
	v_pk_mul_f32 v[186:187], v[98:99], v[98:99]
	v_add_f32_e32 v122, v123, v122
	v_add_f32_e32 v122, v186, v122
	v_pk_mul_f32 v[164:165], v[100:101], v[100:101]
	v_add_f32_e32 v122, v187, v122
	v_add_f32_e32 v122, v164, v122
	v_add_f32_e32 v122, v165, v122
	v_mov_b32_e32 v123, v122
	s_waitcnt lgkmcnt(0)
	s_nop 1
	v_permlane16_swap_b32_e32 v123, v122
	v_add_f32_e32 v122, v122, v123
	v_mov_b32_e32 v123, v122
	s_waitcnt lgkmcnt(0)
	s_nop 1
	v_permlane32_swap_b32_e32 v123, v122
	v_add_f32_e32 v122, v122, v123
	v_fmamk_f32 v122, v122, 0x3c000000, v178
	v_mul_f32_e32 v123, 0x4b800000, v122
	v_cmp_gt_f32_e32 vcc, s64, v122
	s_nop 1
	v_cndmask_b32_e32 v122, v122, v123, vcc
	v_rsq_f32_e32 v122, v122
	s_nop 0
	v_mul_f32_e32 v123, 0x45800000, v122
	v_cndmask_b32_e32 v164, v122, v123, vcc
	v_pk_mul_f32 v[126:127], v[126:127], v[164:165] op_sel_hi:[1,0]
	s_waitcnt vmcnt(0)
	v_pk_mul_f32 v[116:117], v[116:117], v[164:165] op_sel_hi:[1,0]
	v_pk_mul_f32 v[118:119], v[118:119], v[164:165] op_sel_hi:[1,0]
	v_pk_mul_f32 v[110:111], v[110:111], v[116:117]
	v_pk_mul_f32 v[112:113], v[112:113], v[118:119]
	v_cvt_pk_bf16_f32 v110, v110, v111
	v_cvt_pk_bf16_f32 v111, v112, v113
	global_store_dwordx2 v[174:175], v[110:111], off offset:256
	global_load_dwordx4 v[110:113], v[162:163], off offset:64
	v_pk_mul_f32 v[116:117], v[114:115], v[164:165] op_sel_hi:[1,0]
	v_mul_f32_e32 v118, v132, v164
	v_pk_mul_f32 v[116:117], v[120:121], v[116:117]
	v_mul_f32_e32 v119, v136, v164
	s_waitcnt vmcnt(0)
	v_pk_mul_f32 v[110:111], v[110:111], v[164:165] op_sel_hi:[1,0]
	v_pk_mul_f32 v[112:113], v[112:113], v[164:165] op_sel_hi:[1,0]
	v_pk_mul_f32 v[106:107], v[106:107], v[110:111]
	v_pk_mul_f32 v[108:109], v[108:109], v[112:113]
	v_cvt_pk_bf16_f32 v106, v106, v107
	v_cvt_pk_bf16_f32 v107, v108, v109
	global_store_dwordx2 v[174:175], v[106:107], off offset:288
	global_load_dwordx4 v[106:109], v[162:163], off offset:128
	v_pk_mul_f32 v[110:111], v[142:143], v[164:165] op_sel_hi:[1,0]
	v_pk_mul_f32 v[112:113], v[138:139], v[164:165] op_sel_hi:[1,0]
	s_waitcnt vmcnt(0)
	v_pk_mul_f32 v[106:107], v[106:107], v[164:165] op_sel_hi:[1,0]
	v_pk_mul_f32 v[108:109], v[108:109], v[164:165] op_sel_hi:[1,0]
	v_pk_mul_f32 v[102:103], v[102:103], v[106:107]
	v_pk_mul_f32 v[104:105], v[104:105], v[108:109]
	v_cvt_pk_bf16_f32 v102, v102, v103
	v_cvt_pk_bf16_f32 v103, v104, v105
	global_store_dwordx2 v[174:175], v[102:103], off offset:320
	global_load_dwordx4 v[122:125], v[162:163], off offset:192
	v_pk_mul_f32 v[102:103], v[130:131], v[164:165] op_sel_hi:[1,0]
	v_pk_mul_f32 v[104:105], v[134:135], v[164:165] op_sel_hi:[1,0]
	v_mul_f32_e32 v130, v144, v164
	v_mul_f32_e32 v131, v140, v164
	v_pk_mul_f32 v[108:109], v[146:147], v[102:103]
	v_pk_mul_f32 v[106:107], v[150:151], v[104:105]
	v_pk_mul_f32 v[104:105], v[154:155], v[110:111]
	v_pk_mul_f32 v[102:103], v[158:159], v[112:113]
	v_mul_f32_e32 v110, v148, v118
	v_mul_f32_e32 v112, v152, v119
	v_mul_f32_e32 v114, v156, v130
	v_mul_f32_e32 v118, v160, v131
	s_waitcnt vmcnt(0)
	v_pk_mul_f32 v[120:121], v[122:123], v[164:165] op_sel_hi:[1,0]
	v_pk_mul_f32 v[122:123], v[124:125], v[164:165] op_sel_hi:[1,0]
	v_pk_mul_f32 v[98:99], v[98:99], v[120:121]
	v_pk_mul_f32 v[100:101], v[100:101], v[122:123]
	v_cvt_pk_bf16_f32 v98, v98, v99
	v_cvt_pk_bf16_f32 v99, v100, v101
	global_store_dwordx2 v[174:175], v[98:99], off offset:352
	v_pk_mul_f32 v[98:99], v[128:129], v[126:127]
	s_and_saveexec_b64 s[8:9], s[20:21]
	s_cbranch_execz .LBB0_1250
	global_load_dwordx4 v[120:123], v[184:185], off
	global_load_dwordx4 v[124:127], v[180:181], off
	global_load_dwordx4 v[128:131], v[182:183], off
	global_load_dwordx4 v[132:135], v[176:177], off
	s_waitcnt vmcnt(3)
	v_mul_f32_e32 v138, v110, v122
	s_waitcnt vmcnt(2)
	v_pk_mul_f32 v[100:101], v[106:107], v[124:125]
	v_mul_f32_e32 v140, v112, v126
	v_mul_f32_e32 v112, v112, v122
	v_mov_b32_e32 v122, v127
	v_pk_mul_f32 v[124:125], v[108:109], v[124:125]
	v_mul_f32_e32 v142, v110, v126
	s_waitcnt vmcnt(1)
	v_mul_f32_e32 v144, v114, v130
	s_waitcnt vmcnt(0)
	v_mul_f32_e32 v146, v118, v134
	v_mul_f32_e32 v118, v118, v130
	v_mul_f32_e32 v148, v114, v134
	v_mov_b32_e32 v126, v123
	v_pk_fma_f32 v[108:109], v[108:109], v[120:121], v[100:101] neg_lo:[0,0,1] neg_hi:[0,0,1]
	v_pk_mul_f32 v[100:101], v[116:117], v[122:123]
	v_mov_b32_e32 v134, v131
	v_mov_b32_e32 v130, v135
	v_pk_mul_f32 v[110:111], v[116:117], v[126:127]
	v_mov_b32_e32 v113, v101
	v_mov_b32_e32 v143, v100
	v_pk_mul_f32 v[100:101], v[98:99], v[134:135]
	v_pk_mul_f32 v[98:99], v[98:99], v[130:131]
	v_mov_b32_e32 v139, v110
	v_mov_b32_e32 v141, v111
	v_mov_b32_e32 v145, v100
	v_mov_b32_e32 v147, v101
	v_mov_b32_e32 v119, v99
	v_mov_b32_e32 v149, v98
	v_pk_mul_f32 v[136:137], v[102:103], v[132:133]
	v_pk_mul_f32 v[132:133], v[104:105], v[132:133]
	v_pk_add_f32 v[110:111], v[138:139], v[140:141] neg_lo:[0,1] neg_hi:[0,1]
	v_pk_add_f32 v[112:113], v[112:113], v[142:143]
	v_pk_add_f32 v[114:115], v[144:145], v[146:147] neg_lo:[0,1] neg_hi:[0,1]
	v_pk_add_f32 v[118:119], v[118:119], v[148:149]
	v_pk_fma_f32 v[106:107], v[106:107], v[120:121], v[124:125]
	v_pk_fma_f32 v[104:105], v[104:105], v[128:129], v[136:137] neg_lo:[0,0,1] neg_hi:[0,0,1]
	v_pk_fma_f32 v[102:103], v[102:103], v[128:129], v[132:133]
	v_mov_b32_e32 v116, v111
	v_mov_b32_e32 v117, v113
	v_mov_b32_e32 v98, v115
	v_mov_b32_e32 v99, v119

.LBB0_1256:
	s_or_saveexec_b64 s[8:9], s[8:9]
	v_mov_b64_e32 v[102:103], s[68:69]
	s_xor_b64 exec, exec, s[8:9]
	v_mov_b64_e32 v[98:99], s[22:23]
	v_mad_i64_i32 v[98:99], s[34:35], v100, s56, v[98:99]
	s_mov_b64 s[34:35], 0x1243df00
	v_ashrrev_i32_e32 v101, 31, v100
	v_lshl_add_u64 v[98:99], v[98:99], 0, s[34:35]
	v_mov_b32_e32 v130, 0
	v_mov_b64_e32 v[102:103], s[80:81]
	s_andn2_b64 s[20:21], s[20:21], exec
	s_or_b64 exec, exec, s[8:9]
	v_lshlrev_b64 v[100:101], 11, v[100:101]
	v_lshl_add_u64 v[106:107], v[98:99], 0, v[0:1]
	v_lshl_add_u64 v[132:133], v[102:103], 0, v[100:101]
	global_load_dwordx4 v[98:101], v[106:107], off
	global_load_dwordx4 v[102:105], v[106:107], off offset:64
	global_load_dwordx4 v[110:113], v[106:107], off offset:128
	s_nop 0
	global_load_dwordx4 v[106:109], v[106:107], off offset:192
	v_and_b32_e32 v134, 0xfc0, v130
	v_mov_b32_e32 v135, v1
	v_lshl_add_u64 v[142:143], v[166:167], 0, v[134:135]
	v_lshl_add_u64 v[138:139], v[168:169], 0, v[134:135]
	v_lshlrev_b32_e32 v130, 6, v130
	v_pk_mul_f32 v[134:135], v[86:87], v[86:87]
	v_and_b32_e32 v130, 0x7c0, v130
	v_mov_b32_e32 v131, v1
	v_lshl_add_u64 v[140:141], v[166:167], 0, v[130:131]
	v_lshl_add_u64 v[136:137], v[168:169], 0, v[130:131]
	v_pk_mul_f32 v[130:131], v[88:89], v[88:89]
	s_lshl_b32 s8, s62, 1
	v_mov_b32_e32 v173, v1
	v_lshl_add_u64 v[132:133], v[132:133], 0, v[172:173]
	s_lshl_b32 s38, s8, 1
	s_waitcnt vmcnt(2)
	v_mul_f32_e32 v114, v102, v102
	v_mul_f32_e32 v115, v103, v103
	v_fmac_f32_e32 v114, v98, v98
	v_fmac_f32_e32 v115, v99, v99
	s_waitcnt vmcnt(1)
	v_fmac_f32_e32 v114, v110, v110
	v_fmac_f32_e32 v115, v111, v111
	s_waitcnt vmcnt(0)
	v_fmac_f32_e32 v114, v106, v106
	v_fmac_f32_e32 v115, v107, v107
	v_add_f32_e32 v114, v114, v115
	v_mul_f32_e32 v115, v104, v104
	v_fmac_f32_e32 v115, v100, v100
	v_fmac_f32_e32 v115, v112, v112
	v_fmac_f32_e32 v115, v108, v108
	v_add_f32_e32 v114, v115, v114
	v_mul_f32_e32 v115, v105, v105
	v_fmac_f32_e32 v115, v101, v101
	v_fmac_f32_e32 v115, v113, v113
	v_fmac_f32_e32 v115, v109, v109
	v_add_f32_e32 v152, v115, v114
	v_fma_f32 v144, v94, v94, v152
	v_fmac_f32_e32 v144, v95, v95
	v_fmac_f32_e32 v144, v96, v96
	v_fmac_f32_e32 v144, v97, v97
	v_fmac_f32_e32 v144, v90, v90
	v_fmac_f32_e32 v144, v91, v91
	v_fmac_f32_e32 v144, v92, v92
	v_fmac_f32_e32 v144, v93, v93
	v_add_f32_e32 v134, v134, v144
	v_add_f32_e32 v134, v135, v134
	v_add_f32_e32 v130, v130, v134
	v_add_f32_e32 v144, v131, v130
	v_pk_mul_f32 v[134:135], v[82:83], v[82:83]
	v_pk_mul_f32 v[130:131], v[84:85], v[84:85]
	v_add_f32_e32 v134, v134, v144
	v_add_f32_e32 v134, v135, v134
	v_add_f32_e32 v130, v130, v134
	v_add_f32_e32 v130, v131, v130
	v_mov_b32_e32 v131, v130
	global_load_dwordx4 v[114:117], v[162:163], off offset:256
	global_load_dwordx4 v[118:121], v[162:163], off offset:320
	global_load_dwordx4 v[122:125], v[162:163], off offset:384
	global_load_dwordx4 v[126:129], v[162:163], off offset:448
	v_lshl_add_u64 v[134:135], v[132:133], 0, s[38:39]
	s_waitcnt lgkmcnt(0)
	s_nop 1
	v_permlane16_swap_b32_e32 v131, v130
	v_add_f32_e32 v130, v130, v131
	v_mov_b32_e32 v131, v130
	s_waitcnt lgkmcnt(0)
	s_nop 1
	v_permlane32_swap_b32_e32 v131, v130
	v_add_f32_e32 v130, v130, v131
	v_fmamk_f32 v130, v130, 0x3c000000, v178
	v_cmp_gt_f32_e32 vcc, s64, v130
	v_mul_f32_e32 v131, 0x4b800000, v130
	s_nop 0
	v_cndmask_b32_e32 v130, v130, v131, vcc
	v_rsq_f32_e32 v130, v130
	s_nop 0
	v_mul_f32_e32 v131, 0x45800000, v130
	v_cndmask_b32_e32 v144, v130, v131, vcc
	global_load_dwordx4 v[130:133], v[162:163], off
	s_waitcnt vmcnt(0)
	v_pk_mul_f32 v[130:131], v[130:131], v[144:145] op_sel_hi:[1,0]
	s_nop 0
	v_pk_mul_f32 v[94:95], v[94:95], v[130:131]
	v_pk_mul_f32 v[130:131], v[132:133], v[144:145] op_sel_hi:[1,0]
	v_cvt_pk_bf16_f32 v94, v94, v95
	v_pk_mul_f32 v[96:97], v[96:97], v[130:131]
	s_nop 0
	v_cvt_pk_bf16_f32 v95, v96, v97
	global_store_dwordx2 v[134:135], v[94:95], off
	global_load_dwordx4 v[94:97], v[162:163], off offset:64
	s_waitcnt vmcnt(0)
	v_pk_mul_f32 v[94:95], v[94:95], v[144:145] op_sel_hi:[1,0]
	s_nop 0
	v_pk_mul_f32 v[90:91], v[90:91], v[94:95]
	v_pk_mul_f32 v[94:95], v[96:97], v[144:145] op_sel_hi:[1,0]
	v_cvt_pk_bf16_f32 v90, v90, v91
	v_pk_mul_f32 v[92:93], v[92:93], v[94:95]
	v_mov_b32_e32 v96, v125
	v_cvt_pk_bf16_f32 v91, v92, v93
	global_store_dwordx2 v[134:135], v[90:91], off offset:32
	global_load_dwordx4 v[90:93], v[162:163], off offset:128
	v_mov_b32_e32 v97, v129
	s_waitcnt vmcnt(0)
	v_pk_mul_f32 v[90:91], v[90:91], v[144:145] op_sel_hi:[1,0]
	s_nop 0
	v_pk_mul_f32 v[86:87], v[86:87], v[90:91]
	v_pk_mul_f32 v[90:91], v[92:93], v[144:145] op_sel_hi:[1,0]
	v_cvt_pk_bf16_f32 v86, v86, v87
	v_pk_mul_f32 v[88:89], v[88:89], v[90:91]
	s_nop 0
	v_cvt_pk_bf16_f32 v87, v88, v89
	global_store_dwordx2 v[134:135], v[86:87], off offset:64
	global_load_dwordx4 v[86:89], v[162:163], off offset:192
	s_waitcnt vmcnt(0)
	v_pk_mul_f32 v[86:87], v[86:87], v[144:145] op_sel_hi:[1,0]
	s_nop 0
	v_pk_mul_f32 v[82:83], v[82:83], v[86:87]
	v_pk_mul_f32 v[86:87], v[88:89], v[144:145] op_sel_hi:[1,0]
	v_cvt_pk_bf16_f32 v82, v82, v83
	v_pk_mul_f32 v[84:85], v[84:85], v[86:87]
	s_nop 0
	v_cvt_pk_bf16_f32 v83, v84, v85
	global_store_dwordx2 v[134:135], v[82:83], off offset:96
	v_pk_mul_f32 v[82:83], v[98:99], v[144:145] op_sel_hi:[1,0]
	v_mov_b32_e32 v84, v117
	v_pk_mul_f32 v[94:95], v[114:115], v[82:83]
	v_pk_mul_f32 v[82:83], v[102:103], v[144:145] op_sel_hi:[1,0]
	v_mov_b32_e32 v85, v121
	v_pk_mul_f32 v[92:93], v[118:119], v[82:83]
	v_pk_mul_f32 v[82:83], v[110:111], v[144:145] op_sel_hi:[1,0]
	s_nop 0
	v_pk_mul_f32 v[88:89], v[122:123], v[82:83]
	v_pk_mul_f32 v[82:83], v[106:107], v[144:145] op_sel_hi:[1,0]
	s_nop 0
	v_pk_mul_f32 v[86:87], v[126:127], v[82:83]
	v_mul_f32_e32 v82, v100, v144
	v_mul_f32_e32 v130, v116, v82
	v_mul_f32_e32 v82, v104, v144
	v_mul_f32_e32 v132, v120, v82
	v_mul_f32_e32 v82, v112, v144
	v_mul_f32_e32 v146, v124, v82
	v_mul_f32_e32 v82, v108, v144
	v_mul_f32_e32 v148, v128, v82
	v_mov_b32_e32 v82, v101
	v_mov_b32_e32 v83, v105
	v_pk_mul_f32 v[90:91], v[82:83], v[144:145] op_sel_hi:[1,0]
	s_nop 0
	v_pk_mul_f32 v[150:151], v[84:85], v[90:91]
	v_mov_b32_e32 v90, v113
	v_mov_b32_e32 v91, v109
	v_pk_mul_f32 v[144:145], v[90:91], v[144:145] op_sel_hi:[1,0]
	s_nop 0
	v_pk_mul_f32 v[144:145], v[96:97], v[144:145]
	s_and_saveexec_b64 s[8:9], s[20:21]
	s_cbranch_execz .LBB0_1260
	global_load_dwordx4 v[154:157], v[142:143], off
	global_load_dwordx4 v[158:161], v[138:139], off
	global_load_dwordx4 v[174:177], v[140:141], off
	global_load_dwordx4 v[180:183], v[136:137], off
	s_waitcnt vmcnt(3)
	v_mul_f32_e32 v186, v130, v156
	s_waitcnt vmcnt(2)
	v_mul_f32_e32 v188, v132, v160
	v_mul_f32_e32 v132, v132, v156
	v_mov_b32_e32 v156, v161
	v_mul_f32_e32 v190, v130, v160
	s_waitcnt vmcnt(1)
	v_mul_f32_e32 v192, v146, v176
	s_waitcnt vmcnt(0)
	v_mul_f32_e32 v194, v148, v182
	v_mul_f32_e32 v148, v148, v176
	v_mul_f32_e32 v198, v146, v182
	v_mov_b32_e32 v160, v157
	v_pk_mul_f32 v[146:147], v[150:151], v[156:157]
	v_mov_b32_e32 v182, v177
	v_mov_b32_e32 v176, v183
	v_pk_mul_f32 v[130:131], v[150:151], v[160:161]
	v_mov_b32_e32 v133, v147
	v_mov_b32_e32 v191, v146
	v_pk_mul_f32 v[146:147], v[144:145], v[182:183]
	v_pk_mul_f32 v[144:145], v[144:145], v[176:177]
	v_mov_b32_e32 v187, v130
	v_mov_b32_e32 v189, v131
	v_mov_b32_e32 v193, v146
	v_mov_b32_e32 v195, v147
	v_mov_b32_e32 v149, v145
	v_mov_b32_e32 v199, v144
	v_pk_mul_f32 v[164:165], v[92:93], v[158:159]
	v_pk_mul_f32 v[158:159], v[94:95], v[158:159]
	v_pk_mul_f32 v[184:185], v[86:87], v[180:181]
	v_pk_mul_f32 v[180:181], v[88:89], v[180:181]
	v_pk_add_f32 v[130:131], v[186:187], v[188:189] neg_lo:[0,1] neg_hi:[0,1]
	v_pk_add_f32 v[132:133], v[132:133], v[190:191]
	v_pk_add_f32 v[146:147], v[192:193], v[194:195] neg_lo:[0,1] neg_hi:[0,1]
	v_pk_add_f32 v[148:149], v[148:149], v[198:199]
	v_pk_fma_f32 v[94:95], v[94:95], v[154:155], v[164:165] neg_lo:[0,0,1] neg_hi:[0,0,1]
	v_pk_fma_f32 v[92:93], v[92:93], v[154:155], v[158:159]
	v_pk_fma_f32 v[88:89], v[88:89], v[174:175], v[184:185] neg_lo:[0,0,1] neg_hi:[0,0,1]
	v_pk_fma_f32 v[86:87], v[86:87], v[174:175], v[180:181]
	v_mov_b32_e32 v150, v131
	v_mov_b32_e32 v151, v133
	v_mov_b32_e32 v144, v147
	v_mov_b32_e32 v145, v149
.LBB0_1260:
	s_or_b64 exec, exec, s[8:9]
	v_cvt_pk_bf16_f32 v94, v94, v95
	v_cvt_pk_bf16_f32 v95, v130, v150
	v_cvt_pk_bf16_f32 v92, v92, v93
	v_cvt_pk_bf16_f32 v93, v132, v151
	v_cvt_pk_bf16_f32 v88, v88, v89
	v_cvt_pk_bf16_f32 v89, v146, v144
	v_cvt_pk_bf16_f32 v86, v86, v87
	v_cvt_pk_bf16_f32 v87, v148, v145
	global_store_dwordx2 v[134:135], v[94:95], off offset:128
	global_store_dwordx2 v[134:135], v[92:93], off offset:160
	global_store_dwordx2 v[134:135], v[88:89], off offset:192
	global_store_dwordx2 v[134:135], v[86:87], off offset:224
	global_load_dwordx4 v[86:89], v[162:163], off
	v_fmac_f32_e32 v152, v78, v78
	v_fmac_f32_e32 v152, v79, v79
	v_fmac_f32_e32 v152, v80, v80
	v_fmac_f32_e32 v152, v81, v81
	v_fmac_f32_e32 v152, v74, v74
	v_fmac_f32_e32 v152, v75, v75
	v_fmac_f32_e32 v152, v76, v76
	v_pk_mul_f32 v[94:95], v[70:71], v[70:71]
	v_fmac_f32_e32 v152, v77, v77
	v_add_f32_e32 v94, v94, v152
	v_pk_mul_f32 v[92:93], v[72:73], v[72:73]
	v_add_f32_e32 v94, v95, v94
	v_add_f32_e32 v92, v92, v94
	v_pk_mul_f32 v[132:133], v[66:67], v[66:67]
	v_add_f32_e32 v92, v93, v92
	v_add_f32_e32 v92, v132, v92
	v_pk_mul_f32 v[130:131], v[68:69], v[68:69]
	v_add_f32_e32 v92, v133, v92
	v_add_f32_e32 v92, v130, v92
	v_add_f32_e32 v92, v131, v92
	v_mov_b32_e32 v93, v92
	s_waitcnt lgkmcnt(0)
	s_nop 1
	v_permlane16_swap_b32_e32 v93, v92
	v_add_f32_e32 v92, v92, v93
	v_mov_b32_e32 v93, v92
	s_waitcnt lgkmcnt(0)
	s_nop 1
	v_permlane32_swap_b32_e32 v93, v92
	v_add_f32_e32 v92, v92, v93
	v_fmamk_f32 v92, v92, 0x3c000000, v178
	v_mul_f32_e32 v93, 0x4b800000, v92
	v_cmp_gt_f32_e32 vcc, s64, v92
	s_nop 1
	v_cndmask_b32_e32 v92, v92, v93, vcc
	v_rsq_f32_e32 v92, v92
	s_nop 0
	v_mul_f32_e32 v93, 0x45800000, v92
	v_cndmask_b32_e32 v130, v92, v93, vcc
	v_pk_mul_f32 v[90:91], v[90:91], v[130:131] op_sel_hi:[1,0]
	s_waitcnt vmcnt(0)
	v_pk_mul_f32 v[86:87], v[86:87], v[130:131] op_sel_hi:[1,0]
	v_pk_mul_f32 v[88:89], v[88:89], v[130:131] op_sel_hi:[1,0]
	v_pk_mul_f32 v[78:79], v[78:79], v[86:87]
	v_pk_mul_f32 v[80:81], v[80:81], v[88:89]
	v_cvt_pk_bf16_f32 v78, v78, v79
	v_cvt_pk_bf16_f32 v79, v80, v81
	global_store_dwordx2 v[134:135], v[78:79], off offset:256
	global_load_dwordx4 v[78:81], v[162:163], off offset:64
	v_pk_mul_f32 v[88:89], v[82:83], v[130:131] op_sel_hi:[1,0]
	v_mul_f32_e32 v86, v100, v130
	v_pk_mul_f32 v[84:85], v[84:85], v[88:89]
	v_mul_f32_e32 v87, v104, v130
	s_waitcnt vmcnt(0)
	v_pk_mul_f32 v[78:79], v[78:79], v[130:131] op_sel_hi:[1,0]
	v_pk_mul_f32 v[80:81], v[80:81], v[130:131] op_sel_hi:[1,0]
	v_pk_mul_f32 v[74:75], v[74:75], v[78:79]
	v_pk_mul_f32 v[76:77], v[76:77], v[80:81]
	v_cvt_pk_bf16_f32 v74, v74, v75
	v_cvt_pk_bf16_f32 v75, v76, v77
	global_store_dwordx2 v[134:135], v[74:75], off offset:288
	global_load_dwordx4 v[74:77], v[162:163], off offset:128
	v_pk_mul_f32 v[78:79], v[110:111], v[130:131] op_sel_hi:[1,0]
	v_pk_mul_f32 v[80:81], v[106:107], v[130:131] op_sel_hi:[1,0]
	s_waitcnt vmcnt(0)
	v_pk_mul_f32 v[74:75], v[74:75], v[130:131] op_sel_hi:[1,0]
	v_pk_mul_f32 v[76:77], v[76:77], v[130:131] op_sel_hi:[1,0]
	v_pk_mul_f32 v[70:71], v[70:71], v[74:75]
	v_pk_mul_f32 v[72:73], v[72:73], v[76:77]
	v_cvt_pk_bf16_f32 v70, v70, v71
	v_cvt_pk_bf16_f32 v71, v72, v73
	global_store_dwordx2 v[134:135], v[70:71], off offset:320
	global_load_dwordx4 v[92:95], v[162:163], off offset:192
	v_pk_mul_f32 v[70:71], v[98:99], v[130:131] op_sel_hi:[1,0]
	v_pk_mul_f32 v[72:73], v[102:103], v[130:131] op_sel_hi:[1,0]
	v_mul_f32_e32 v98, v112, v130
	v_mul_f32_e32 v99, v108, v130
	v_pk_mul_f32 v[76:77], v[114:115], v[70:71]
	v_pk_mul_f32 v[74:75], v[118:119], v[72:73]
	v_pk_mul_f32 v[72:73], v[122:123], v[78:79]
	v_pk_mul_f32 v[70:71], v[126:127], v[80:81]
	v_mul_f32_e32 v78, v116, v86
	v_mul_f32_e32 v80, v120, v87
	v_mul_f32_e32 v82, v124, v98
	v_mul_f32_e32 v86, v128, v99
	s_waitcnt vmcnt(0)
	v_pk_mul_f32 v[88:89], v[92:93], v[130:131] op_sel_hi:[1,0]
	v_pk_mul_f32 v[92:93], v[94:95], v[130:131] op_sel_hi:[1,0]
	v_pk_mul_f32 v[66:67], v[66:67], v[88:89]
	v_pk_mul_f32 v[68:69], v[68:69], v[92:93]
	v_cvt_pk_bf16_f32 v66, v66, v67
	v_cvt_pk_bf16_f32 v67, v68, v69
	global_store_dwordx2 v[134:135], v[66:67], off offset:352
	v_pk_mul_f32 v[66:67], v[96:97], v[90:91]
	s_and_saveexec_b64 s[8:9], s[20:21]
	s_cbranch_execz .LBB0_1262
	global_load_dwordx4 v[88:91], v[142:143], off
	global_load_dwordx4 v[92:95], v[138:139], off
	global_load_dwordx4 v[96:99], v[140:141], off
	global_load_dwordx4 v[100:103], v[136:137], off
	s_waitcnt vmcnt(3)
	v_mul_f32_e32 v106, v78, v90
	s_waitcnt vmcnt(2)
	v_pk_mul_f32 v[68:69], v[74:75], v[92:93]
	v_mul_f32_e32 v108, v80, v94
	v_mul_f32_e32 v80, v80, v90
	v_mov_b32_e32 v90, v95
	v_pk_mul_f32 v[92:93], v[76:77], v[92:93]
	v_mul_f32_e32 v110, v78, v94
	s_waitcnt vmcnt(1)
	v_mul_f32_e32 v112, v82, v98
	s_waitcnt vmcnt(0)
	v_mul_f32_e32 v114, v86, v102
	v_mul_f32_e32 v86, v86, v98
	v_mul_f32_e32 v116, v82, v102
	v_mov_b32_e32 v94, v91
	v_pk_fma_f32 v[76:77], v[76:77], v[88:89], v[68:69] neg_lo:[0,0,1] neg_hi:[0,0,1]
	v_pk_mul_f32 v[68:69], v[84:85], v[90:91]
	v_mov_b32_e32 v102, v99
	v_mov_b32_e32 v98, v103
	v_pk_mul_f32 v[78:79], v[84:85], v[94:95]
	v_mov_b32_e32 v81, v69
	v_mov_b32_e32 v111, v68
	v_pk_mul_f32 v[68:69], v[66:67], v[102:103]
	v_pk_mul_f32 v[66:67], v[66:67], v[98:99]
	v_mov_b32_e32 v107, v78
	v_mov_b32_e32 v109, v79
	v_mov_b32_e32 v113, v68
	v_mov_b32_e32 v115, v69
	v_mov_b32_e32 v87, v67
	v_mov_b32_e32 v117, v66
	v_pk_mul_f32 v[104:105], v[70:71], v[100:101]
	v_pk_mul_f32 v[100:101], v[72:73], v[100:101]
	v_pk_add_f32 v[78:79], v[106:107], v[108:109] neg_lo:[0,1] neg_hi:[0,1]
	v_pk_add_f32 v[80:81], v[80:81], v[110:111]
	v_pk_add_f32 v[82:83], v[112:113], v[114:115] neg_lo:[0,1] neg_hi:[0,1]
	v_pk_add_f32 v[86:87], v[86:87], v[116:117]
	v_pk_fma_f32 v[74:75], v[74:75], v[88:89], v[92:93]
	v_pk_fma_f32 v[72:73], v[72:73], v[96:97], v[104:105] neg_lo:[0,0,1] neg_hi:[0,0,1]
	v_pk_fma_f32 v[70:71], v[70:71], v[96:97], v[100:101]
	v_mov_b32_e32 v84, v79
	v_mov_b32_e32 v85, v81
	v_mov_b32_e32 v66, v83
	v_mov_b32_e32 v67, v87

.LBB0_1268:
	s_or_saveexec_b64 s[8:9], s[8:9]
	v_mov_b64_e32 v[70:71], s[68:69]
	s_xor_b64 exec, exec, s[8:9]
	v_mov_b64_e32 v[66:67], s[22:23]
	v_mad_i64_i32 v[66:67], s[34:35], v68, s56, v[66:67]
	s_mov_b64 s[34:35], 0x1243df00
	v_ashrrev_i32_e32 v69, 31, v68
	v_lshl_add_u64 v[66:67], v[66:67], 0, s[34:35]
	v_mov_b32_e32 v98, 0
	v_mov_b64_e32 v[70:71], s[80:81]
	s_andn2_b64 s[20:21], s[20:21], exec
	s_or_b64 exec, exec, s[8:9]
	v_lshlrev_b64 v[68:69], 11, v[68:69]
	v_lshl_add_u64 v[74:75], v[66:67], 0, v[0:1]
	v_lshl_add_u64 v[100:101], v[70:71], 0, v[68:69]
	global_load_dwordx4 v[66:69], v[74:75], off
	global_load_dwordx4 v[70:73], v[74:75], off offset:64
	global_load_dwordx4 v[78:81], v[74:75], off offset:128
	s_nop 0
	global_load_dwordx4 v[74:77], v[74:75], off offset:192
	v_and_b32_e32 v102, 0xfc0, v98
	v_mov_b32_e32 v103, v1
	v_lshl_add_u64 v[110:111], v[166:167], 0, v[102:103]
	v_lshl_add_u64 v[106:107], v[168:169], 0, v[102:103]
	v_lshlrev_b32_e32 v98, 6, v98
	v_pk_mul_f32 v[102:103], v[54:55], v[54:55]
	v_and_b32_e32 v98, 0xbc0, v98
	v_mov_b32_e32 v99, v1
	v_lshl_add_u64 v[108:109], v[166:167], 0, v[98:99]
	v_lshl_add_u64 v[104:105], v[168:169], 0, v[98:99]
	v_pk_mul_f32 v[98:99], v[56:57], v[56:57]
	v_mov_b32_e32 v173, v1
	v_lshl_add_u64 v[100:101], v[100:101], 0, v[172:173]
	s_waitcnt vmcnt(2)
	v_mul_f32_e32 v82, v70, v70
	v_mul_f32_e32 v83, v71, v71
	v_fmac_f32_e32 v82, v66, v66
	v_fmac_f32_e32 v83, v67, v67
	s_waitcnt vmcnt(1)
	v_fmac_f32_e32 v82, v78, v78
	v_fmac_f32_e32 v83, v79, v79
	s_waitcnt vmcnt(0)
	v_fmac_f32_e32 v82, v74, v74
	v_fmac_f32_e32 v83, v75, v75
	v_add_f32_e32 v82, v82, v83
	v_mul_f32_e32 v83, v72, v72
	v_fmac_f32_e32 v83, v68, v68
	v_fmac_f32_e32 v83, v80, v80
	v_fmac_f32_e32 v83, v76, v76
	v_add_f32_e32 v82, v83, v82
	v_mul_f32_e32 v83, v73, v73
	v_fmac_f32_e32 v83, v69, v69
	v_fmac_f32_e32 v83, v81, v81
	v_fmac_f32_e32 v83, v77, v77
	v_add_f32_e32 v120, v83, v82
	v_fma_f32 v112, v62, v62, v120
	v_fmac_f32_e32 v112, v63, v63
	v_fmac_f32_e32 v112, v64, v64
	v_fmac_f32_e32 v112, v65, v65
	v_fmac_f32_e32 v112, v58, v58
	v_fmac_f32_e32 v112, v59, v59
	v_fmac_f32_e32 v112, v60, v60
	v_fmac_f32_e32 v112, v61, v61
	v_add_f32_e32 v102, v102, v112
	v_add_f32_e32 v102, v103, v102
	v_add_f32_e32 v98, v98, v102
	v_add_f32_e32 v112, v99, v98
	v_pk_mul_f32 v[102:103], v[50:51], v[50:51]
	v_pk_mul_f32 v[98:99], v[52:53], v[52:53]
	v_add_f32_e32 v102, v102, v112
	v_add_f32_e32 v102, v103, v102
	v_add_f32_e32 v98, v98, v102
	v_add_f32_e32 v98, v99, v98
	v_mov_b32_e32 v99, v98
	global_load_dwordx4 v[82:85], v[162:163], off offset:256
	global_load_dwordx4 v[86:89], v[162:163], off offset:320
	global_load_dwordx4 v[90:93], v[162:163], off offset:384
	global_load_dwordx4 v[94:97], v[162:163], off offset:448
	v_lshl_add_u64 v[102:103], v[100:101], 0, s[38:39]
	s_waitcnt lgkmcnt(0)
	s_nop 1
	v_permlane16_swap_b32_e32 v99, v98
	v_add_f32_e32 v98, v98, v99
	v_mov_b32_e32 v99, v98
	s_waitcnt lgkmcnt(0)
	s_nop 1
	v_permlane32_swap_b32_e32 v99, v98
	v_add_f32_e32 v98, v98, v99
	v_fmamk_f32 v98, v98, 0x3c000000, v178
	v_cmp_gt_f32_e32 vcc, s64, v98
	v_mul_f32_e32 v99, 0x4b800000, v98
	s_nop 0
	v_cndmask_b32_e32 v98, v98, v99, vcc
	v_rsq_f32_e32 v98, v98
	s_nop 0
	v_mul_f32_e32 v99, 0x45800000, v98
	v_cndmask_b32_e32 v112, v98, v99, vcc
	global_load_dwordx4 v[98:101], v[162:163], off
	s_waitcnt vmcnt(0)
	v_pk_mul_f32 v[98:99], v[98:99], v[112:113] op_sel_hi:[1,0]
	s_nop 0
	v_pk_mul_f32 v[62:63], v[62:63], v[98:99]
	v_pk_mul_f32 v[98:99], v[100:101], v[112:113] op_sel_hi:[1,0]
	v_cvt_pk_bf16_f32 v62, v62, v63
	v_pk_mul_f32 v[64:65], v[64:65], v[98:99]
	s_nop 0
	v_cvt_pk_bf16_f32 v63, v64, v65
	global_store_dwordx2 v[102:103], v[62:63], off
	global_load_dwordx4 v[62:65], v[162:163], off offset:64
	s_waitcnt vmcnt(0)
	v_pk_mul_f32 v[62:63], v[62:63], v[112:113] op_sel_hi:[1,0]
	s_nop 0
	v_pk_mul_f32 v[58:59], v[58:59], v[62:63]
	v_pk_mul_f32 v[62:63], v[64:65], v[112:113] op_sel_hi:[1,0]
	v_cvt_pk_bf16_f32 v58, v58, v59
	v_pk_mul_f32 v[60:61], v[60:61], v[62:63]
	v_mov_b32_e32 v64, v93
	v_cvt_pk_bf16_f32 v59, v60, v61
	global_store_dwordx2 v[102:103], v[58:59], off offset:32
	global_load_dwordx4 v[58:61], v[162:163], off offset:128
	v_mov_b32_e32 v65, v97
	s_waitcnt vmcnt(0)
	v_pk_mul_f32 v[58:59], v[58:59], v[112:113] op_sel_hi:[1,0]
	s_nop 0
	v_pk_mul_f32 v[54:55], v[54:55], v[58:59]
	v_pk_mul_f32 v[58:59], v[60:61], v[112:113] op_sel_hi:[1,0]
	v_cvt_pk_bf16_f32 v54, v54, v55
	v_pk_mul_f32 v[56:57], v[56:57], v[58:59]
	s_nop 0
	v_cvt_pk_bf16_f32 v55, v56, v57
	global_store_dwordx2 v[102:103], v[54:55], off offset:64
	global_load_dwordx4 v[54:57], v[162:163], off offset:192
	s_waitcnt vmcnt(0)
	v_pk_mul_f32 v[54:55], v[54:55], v[112:113] op_sel_hi:[1,0]
	s_nop 0
	v_pk_mul_f32 v[50:51], v[50:51], v[54:55]
	v_pk_mul_f32 v[54:55], v[56:57], v[112:113] op_sel_hi:[1,0]
	v_cvt_pk_bf16_f32 v50, v50, v51
	v_pk_mul_f32 v[52:53], v[52:53], v[54:55]
	s_nop 0
	v_cvt_pk_bf16_f32 v51, v52, v53
	global_store_dwordx2 v[102:103], v[50:51], off offset:96
	v_pk_mul_f32 v[50:51], v[66:67], v[112:113] op_sel_hi:[1,0]
	v_mov_b32_e32 v52, v85
	v_pk_mul_f32 v[62:63], v[82:83], v[50:51]
	v_pk_mul_f32 v[50:51], v[70:71], v[112:113] op_sel_hi:[1,0]
	v_mov_b32_e32 v53, v89
	v_pk_mul_f32 v[60:61], v[86:87], v[50:51]
	v_pk_mul_f32 v[50:51], v[78:79], v[112:113] op_sel_hi:[1,0]
	s_nop 0
	v_pk_mul_f32 v[56:57], v[90:91], v[50:51]
	v_pk_mul_f32 v[50:51], v[74:75], v[112:113] op_sel_hi:[1,0]
	s_nop 0
	v_pk_mul_f32 v[54:55], v[94:95], v[50:51]
	v_mul_f32_e32 v50, v68, v112
	v_mul_f32_e32 v98, v84, v50
	v_mul_f32_e32 v50, v72, v112
	v_mul_f32_e32 v100, v88, v50
	v_mul_f32_e32 v50, v80, v112
	v_mul_f32_e32 v114, v92, v50
	v_mul_f32_e32 v50, v76, v112
	v_mul_f32_e32 v116, v96, v50
	v_mov_b32_e32 v50, v69
	v_mov_b32_e32 v51, v73
	v_pk_mul_f32 v[58:59], v[50:51], v[112:113] op_sel_hi:[1,0]
	s_nop 0
	v_pk_mul_f32 v[118:119], v[52:53], v[58:59]
	v_mov_b32_e32 v58, v81
	v_mov_b32_e32 v59, v77
	v_pk_mul_f32 v[112:113], v[58:59], v[112:113] op_sel_hi:[1,0]
	s_nop 0
	v_pk_mul_f32 v[112:113], v[64:65], v[112:113]
	s_and_saveexec_b64 s[8:9], s[20:21]
	s_cbranch_execz .LBB0_1272
	global_load_dwordx4 v[122:125], v[110:111], off
	global_load_dwordx4 v[126:129], v[106:107], off
	global_load_dwordx4 v[130:133], v[108:109], off
	global_load_dwordx4 v[134:137], v[104:105], off
	s_waitcnt vmcnt(3)
	v_mul_f32_e32 v142, v98, v124
	s_waitcnt vmcnt(2)
	v_mul_f32_e32 v144, v100, v128
	v_mul_f32_e32 v100, v100, v124
	v_mov_b32_e32 v124, v129
	v_mul_f32_e32 v146, v98, v128
	s_waitcnt vmcnt(1)
	v_mul_f32_e32 v148, v114, v132
	s_waitcnt vmcnt(0)
	v_mul_f32_e32 v150, v116, v136
	v_mul_f32_e32 v116, v116, v132
	v_mul_f32_e32 v152, v114, v136
	v_mov_b32_e32 v128, v125
	v_pk_mul_f32 v[114:115], v[118:119], v[124:125]
	v_mov_b32_e32 v136, v133
	v_mov_b32_e32 v132, v137
	v_pk_mul_f32 v[98:99], v[118:119], v[128:129]
	v_mov_b32_e32 v101, v115
	v_mov_b32_e32 v147, v114
	v_pk_mul_f32 v[114:115], v[112:113], v[136:137]
	v_pk_mul_f32 v[112:113], v[112:113], v[132:133]
	v_mov_b32_e32 v143, v98
	v_mov_b32_e32 v145, v99
	v_mov_b32_e32 v149, v114
	v_mov_b32_e32 v151, v115
	v_mov_b32_e32 v117, v113
	v_mov_b32_e32 v153, v112
	v_pk_mul_f32 v[138:139], v[60:61], v[126:127]
	v_pk_mul_f32 v[126:127], v[62:63], v[126:127]
	v_pk_mul_f32 v[140:141], v[54:55], v[134:135]
	v_pk_mul_f32 v[134:135], v[56:57], v[134:135]
	v_pk_add_f32 v[98:99], v[142:143], v[144:145] neg_lo:[0,1] neg_hi:[0,1]
	v_pk_add_f32 v[100:101], v[100:101], v[146:147]
	v_pk_add_f32 v[114:115], v[148:149], v[150:151] neg_lo:[0,1] neg_hi:[0,1]
	v_pk_add_f32 v[116:117], v[116:117], v[152:153]
	v_pk_fma_f32 v[62:63], v[62:63], v[122:123], v[138:139] neg_lo:[0,0,1] neg_hi:[0,0,1]
	v_pk_fma_f32 v[60:61], v[60:61], v[122:123], v[126:127]
	v_pk_fma_f32 v[56:57], v[56:57], v[130:131], v[140:141] neg_lo:[0,0,1] neg_hi:[0,0,1]
	v_pk_fma_f32 v[54:55], v[54:55], v[130:131], v[134:135]
	v_mov_b32_e32 v118, v99
	v_mov_b32_e32 v119, v101
	v_mov_b32_e32 v112, v115
	v_mov_b32_e32 v113, v117
.LBB0_1272:
	s_or_b64 exec, exec, s[8:9]
	v_cvt_pk_bf16_f32 v62, v62, v63
	v_cvt_pk_bf16_f32 v63, v98, v118
	v_cvt_pk_bf16_f32 v60, v60, v61
	v_cvt_pk_bf16_f32 v61, v100, v119
	v_cvt_pk_bf16_f32 v56, v56, v57
	v_cvt_pk_bf16_f32 v57, v114, v112
	v_cvt_pk_bf16_f32 v54, v54, v55
	v_cvt_pk_bf16_f32 v55, v116, v113
	global_store_dwordx2 v[102:103], v[62:63], off offset:128
	global_store_dwordx2 v[102:103], v[60:61], off offset:160
	global_store_dwordx2 v[102:103], v[56:57], off offset:192
	global_store_dwordx2 v[102:103], v[54:55], off offset:224
	global_load_dwordx4 v[54:57], v[162:163], off
	v_fmac_f32_e32 v120, v46, v46
	v_fmac_f32_e32 v120, v47, v47
	v_fmac_f32_e32 v120, v48, v48
	v_fmac_f32_e32 v120, v49, v49
	v_fmac_f32_e32 v120, v42, v42
	v_fmac_f32_e32 v120, v43, v43
	v_fmac_f32_e32 v120, v44, v44
	v_pk_mul_f32 v[62:63], v[38:39], v[38:39]
	v_fmac_f32_e32 v120, v45, v45
	v_add_f32_e32 v62, v62, v120
	v_pk_mul_f32 v[60:61], v[40:41], v[40:41]
	v_add_f32_e32 v62, v63, v62
	v_add_f32_e32 v60, v60, v62
	v_pk_mul_f32 v[100:101], v[34:35], v[34:35]
	v_add_f32_e32 v60, v61, v60
	v_add_f32_e32 v60, v100, v60
	v_pk_mul_f32 v[98:99], v[36:37], v[36:37]
	v_add_f32_e32 v60, v101, v60
	v_add_f32_e32 v60, v98, v60
	v_add_f32_e32 v60, v99, v60
	v_mov_b32_e32 v61, v60
	s_waitcnt lgkmcnt(0)
	s_nop 1
	v_permlane16_swap_b32_e32 v61, v60
	v_add_f32_e32 v60, v60, v61
	v_mov_b32_e32 v61, v60
	s_waitcnt lgkmcnt(0)
	s_nop 1
	v_permlane32_swap_b32_e32 v61, v60
	v_add_f32_e32 v60, v60, v61
	v_fmamk_f32 v60, v60, 0x3c000000, v178
	v_mul_f32_e32 v61, 0x4b800000, v60
	v_cmp_gt_f32_e32 vcc, s64, v60
	s_nop 1
	v_cndmask_b32_e32 v60, v60, v61, vcc
	v_rsq_f32_e32 v60, v60
	s_nop 0
	v_mul_f32_e32 v61, 0x45800000, v60
	v_cndmask_b32_e32 v98, v60, v61, vcc
	v_pk_mul_f32 v[58:59], v[58:59], v[98:99] op_sel_hi:[1,0]
	s_waitcnt vmcnt(0)
	v_pk_mul_f32 v[54:55], v[54:55], v[98:99] op_sel_hi:[1,0]
	v_pk_mul_f32 v[56:57], v[56:57], v[98:99] op_sel_hi:[1,0]
	v_pk_mul_f32 v[46:47], v[46:47], v[54:55]
	v_pk_mul_f32 v[48:49], v[48:49], v[56:57]
	v_cvt_pk_bf16_f32 v46, v46, v47
	v_cvt_pk_bf16_f32 v47, v48, v49
	global_store_dwordx2 v[102:103], v[46:47], off offset:256
	global_load_dwordx4 v[46:49], v[162:163], off offset:64
	v_pk_mul_f32 v[56:57], v[50:51], v[98:99] op_sel_hi:[1,0]
	v_mul_f32_e32 v54, v68, v98
	v_pk_mul_f32 v[52:53], v[52:53], v[56:57]
	v_mul_f32_e32 v55, v72, v98
	s_waitcnt vmcnt(0)
	v_pk_mul_f32 v[46:47], v[46:47], v[98:99] op_sel_hi:[1,0]
	v_pk_mul_f32 v[48:49], v[48:49], v[98:99] op_sel_hi:[1,0]
	v_pk_mul_f32 v[42:43], v[42:43], v[46:47]
	v_pk_mul_f32 v[44:45], v[44:45], v[48:49]
	v_cvt_pk_bf16_f32 v42, v42, v43
	v_cvt_pk_bf16_f32 v43, v44, v45
	global_store_dwordx2 v[102:103], v[42:43], off offset:288
	global_load_dwordx4 v[42:45], v[162:163], off offset:128
	v_pk_mul_f32 v[46:47], v[78:79], v[98:99] op_sel_hi:[1,0]
	v_pk_mul_f32 v[48:49], v[74:75], v[98:99] op_sel_hi:[1,0]
	s_waitcnt vmcnt(0)
	v_pk_mul_f32 v[42:43], v[42:43], v[98:99] op_sel_hi:[1,0]
	v_pk_mul_f32 v[44:45], v[44:45], v[98:99] op_sel_hi:[1,0]
	v_pk_mul_f32 v[38:39], v[38:39], v[42:43]
	v_pk_mul_f32 v[40:41], v[40:41], v[44:45]
	v_cvt_pk_bf16_f32 v38, v38, v39
	v_cvt_pk_bf16_f32 v39, v40, v41
	global_store_dwordx2 v[102:103], v[38:39], off offset:320
	global_load_dwordx4 v[60:63], v[162:163], off offset:192
	v_pk_mul_f32 v[38:39], v[66:67], v[98:99] op_sel_hi:[1,0]
	v_pk_mul_f32 v[40:41], v[70:71], v[98:99] op_sel_hi:[1,0]
	v_mul_f32_e32 v66, v80, v98
	v_mul_f32_e32 v67, v76, v98
	v_pk_mul_f32 v[44:45], v[82:83], v[38:39]
	v_pk_mul_f32 v[42:43], v[86:87], v[40:41]
	v_pk_mul_f32 v[40:41], v[90:91], v[46:47]
	v_pk_mul_f32 v[38:39], v[94:95], v[48:49]
	v_mul_f32_e32 v46, v84, v54
	v_mul_f32_e32 v48, v88, v55
	v_mul_f32_e32 v50, v92, v66
	v_mul_f32_e32 v54, v96, v67
	s_waitcnt vmcnt(0)
	v_pk_mul_f32 v[56:57], v[60:61], v[98:99] op_sel_hi:[1,0]
	v_pk_mul_f32 v[60:61], v[62:63], v[98:99] op_sel_hi:[1,0]
	v_pk_mul_f32 v[34:35], v[34:35], v[56:57]
	v_pk_mul_f32 v[36:37], v[36:37], v[60:61]
	v_cvt_pk_bf16_f32 v34, v34, v35
	v_cvt_pk_bf16_f32 v35, v36, v37
	global_store_dwordx2 v[102:103], v[34:35], off offset:352
	v_pk_mul_f32 v[34:35], v[64:65], v[58:59]
	s_and_saveexec_b64 s[8:9], s[20:21]
	s_cbranch_execz .LBB0_1274
	global_load_dwordx4 v[56:59], v[110:111], off
	global_load_dwordx4 v[60:63], v[106:107], off
	global_load_dwordx4 v[64:67], v[108:109], off
	global_load_dwordx4 v[68:71], v[104:105], off
	s_waitcnt vmcnt(3)
	v_mul_f32_e32 v74, v46, v58
	s_waitcnt vmcnt(2)
	v_pk_mul_f32 v[36:37], v[42:43], v[60:61]
	v_mul_f32_e32 v76, v48, v62
	v_mul_f32_e32 v48, v48, v58
	v_mov_b32_e32 v58, v63
	v_pk_mul_f32 v[60:61], v[44:45], v[60:61]
	v_mul_f32_e32 v78, v46, v62
	s_waitcnt vmcnt(1)
	v_mul_f32_e32 v80, v50, v66
	s_waitcnt vmcnt(0)
	v_mul_f32_e32 v82, v54, v70
	v_mul_f32_e32 v54, v54, v66
	v_mul_f32_e32 v84, v50, v70
	v_mov_b32_e32 v62, v59
	v_pk_fma_f32 v[44:45], v[44:45], v[56:57], v[36:37] neg_lo:[0,0,1] neg_hi:[0,0,1]
	v_pk_mul_f32 v[36:37], v[52:53], v[58:59]
	v_mov_b32_e32 v70, v67
	v_mov_b32_e32 v66, v71
	v_pk_mul_f32 v[46:47], v[52:53], v[62:63]
	v_mov_b32_e32 v49, v37
	v_mov_b32_e32 v79, v36
	v_pk_mul_f32 v[36:37], v[34:35], v[70:71]
	v_pk_mul_f32 v[34:35], v[34:35], v[66:67]
	v_mov_b32_e32 v75, v46
	v_mov_b32_e32 v77, v47
	v_mov_b32_e32 v81, v36
	v_mov_b32_e32 v83, v37
	v_mov_b32_e32 v55, v35
	v_mov_b32_e32 v85, v34
	v_pk_mul_f32 v[72:73], v[38:39], v[68:69]
	v_pk_mul_f32 v[68:69], v[40:41], v[68:69]
	v_pk_add_f32 v[46:47], v[74:75], v[76:77] neg_lo:[0,1] neg_hi:[0,1]
	v_pk_add_f32 v[48:49], v[48:49], v[78:79]
	v_pk_add_f32 v[50:51], v[80:81], v[82:83] neg_lo:[0,1] neg_hi:[0,1]
	v_pk_add_f32 v[54:55], v[54:55], v[84:85]
	v_pk_fma_f32 v[42:43], v[42:43], v[56:57], v[60:61]
	v_pk_fma_f32 v[40:41], v[40:41], v[64:65], v[72:73] neg_lo:[0,0,1] neg_hi:[0,0,1]
	v_pk_fma_f32 v[38:39], v[38:39], v[64:65], v[68:69]
	v_mov_b32_e32 v52, v47
	v_mov_b32_e32 v53, v49
	v_mov_b32_e32 v34, v51
	v_mov_b32_e32 v35, v55

.LBB0_1280:
	s_or_saveexec_b64 s[8:9], s[8:9]
	v_mov_b64_e32 v[38:39], s[68:69]
	s_xor_b64 exec, exec, s[8:9]
	v_mov_b64_e32 v[34:35], s[22:23]
	v_mad_i64_i32 v[34:35], s[22:23], v36, s56, v[34:35]
	s_mov_b64 s[22:23], 0x1243df00
	v_ashrrev_i32_e32 v37, 31, v36
	v_lshl_add_u64 v[34:35], v[34:35], 0, s[22:23]
	v_mov_b32_e32 v66, 0
	v_mov_b64_e32 v[38:39], s[80:81]
	s_andn2_b64 s[20:21], s[20:21], exec
	s_or_b64 exec, exec, s[8:9]
	v_lshlrev_b64 v[36:37], 11, v[36:37]
	v_lshl_add_u64 v[42:43], v[34:35], 0, v[0:1]
	v_lshl_add_u64 v[68:69], v[38:39], 0, v[36:37]
	global_load_dwordx4 v[34:37], v[42:43], off
	global_load_dwordx4 v[38:41], v[42:43], off offset:64
	global_load_dwordx4 v[46:49], v[42:43], off offset:128
	s_nop 0
	global_load_dwordx4 v[42:45], v[42:43], off offset:192
	v_pk_mul_f32 v[70:71], v[22:23], v[22:23]
	v_mov_b32_e32 v173, v1
	v_lshl_add_u64 v[68:69], v[68:69], 0, v[172:173]
	s_waitcnt vmcnt(2)
	v_mul_f32_e32 v0, v38, v38
	v_mul_f32_e32 v50, v39, v39
	v_fmac_f32_e32 v0, v34, v34
	v_fmac_f32_e32 v50, v35, v35
	s_waitcnt vmcnt(1)
	v_fmac_f32_e32 v0, v46, v46
	v_fmac_f32_e32 v50, v47, v47
	s_waitcnt vmcnt(0)
	v_fmac_f32_e32 v0, v42, v42
	v_fmac_f32_e32 v50, v43, v43
	v_add_f32_e32 v0, v0, v50
	v_mul_f32_e32 v50, v40, v40
	v_fmac_f32_e32 v50, v36, v36
	v_fmac_f32_e32 v50, v48, v48
	v_fmac_f32_e32 v50, v44, v44
	v_add_f32_e32 v0, v50, v0
	v_mul_f32_e32 v50, v41, v41
	v_fmac_f32_e32 v50, v37, v37
	v_fmac_f32_e32 v50, v49, v49
	v_fmac_f32_e32 v50, v45, v45
	v_add_f32_e32 v88, v50, v0
	v_and_b32_e32 v0, 0xfc0, v66
	v_lshl_add_u64 v[78:79], v[166:167], 0, v[0:1]
	v_lshl_add_u64 v[74:75], v[168:169], 0, v[0:1]
	v_lshlrev_b32_e32 v0, 6, v66
	v_and_b32_e32 v0, 0xfc0, v0
	v_lshl_add_u64 v[76:77], v[166:167], 0, v[0:1]
	v_lshl_add_u64 v[72:73], v[168:169], 0, v[0:1]
	v_fma_f32 v0, v30, v30, v88
	v_fmac_f32_e32 v0, v31, v31
	v_fmac_f32_e32 v0, v32, v32
	v_fmac_f32_e32 v0, v33, v33
	v_fmac_f32_e32 v0, v26, v26
	v_fmac_f32_e32 v0, v27, v27
	v_fmac_f32_e32 v0, v28, v28
	v_fmac_f32_e32 v0, v29, v29
	v_add_f32_e32 v0, v70, v0
	v_pk_mul_f32 v[66:67], v[24:25], v[24:25]
	v_add_f32_e32 v0, v71, v0
	v_add_f32_e32 v0, v66, v0
	v_add_f32_e32 v0, v67, v0
	v_pk_mul_f32 v[70:71], v[18:19], v[18:19]
	v_pk_mul_f32 v[66:67], v[20:21], v[20:21]
	v_add_f32_e32 v0, v70, v0
	v_add_f32_e32 v0, v71, v0
	v_add_f32_e32 v0, v66, v0
	v_add_f32_e32 v0, v67, v0
	v_mov_b32_e32 v66, v0
	global_load_dwordx4 v[50:53], v[162:163], off offset:256
	global_load_dwordx4 v[54:57], v[162:163], off offset:320
	global_load_dwordx4 v[58:61], v[162:163], off offset:384
	global_load_dwordx4 v[62:65], v[162:163], off offset:448
	v_lshl_add_u64 v[70:71], v[68:69], 0, s[38:39]
	s_waitcnt lgkmcnt(0)
	s_nop 1
	v_permlane16_swap_b32_e32 v66, v0
	v_add_f32_e32 v0, v0, v66
	v_mov_b32_e32 v66, v0
	s_waitcnt lgkmcnt(0)
	s_nop 1
	v_permlane32_swap_b32_e32 v66, v0
	v_add_f32_e32 v0, v0, v66
	v_fmamk_f32 v0, v0, 0x3c000000, v178
	v_cmp_gt_f32_e32 vcc, s64, v0
	v_mul_f32_e32 v66, 0x4b800000, v0
	s_nop 0
	v_cndmask_b32_e32 v0, v0, v66, vcc
	v_rsq_f32_e32 v0, v0
	s_nop 0
	v_mul_f32_e32 v66, 0x45800000, v0
	v_cndmask_b32_e32 v0, v0, v66, vcc
	global_load_dwordx4 v[66:69], v[162:163], off
	s_waitcnt vmcnt(0)
	v_pk_mul_f32 v[66:67], v[66:67], v[0:1] op_sel_hi:[1,0]
	s_nop 0
	v_pk_mul_f32 v[30:31], v[30:31], v[66:67]
	v_pk_mul_f32 v[66:67], v[68:69], v[0:1] op_sel_hi:[1,0]
	v_cvt_pk_bf16_f32 v30, v30, v31
	v_pk_mul_f32 v[32:33], v[32:33], v[66:67]
	s_nop 0
	v_cvt_pk_bf16_f32 v31, v32, v33
	global_store_dwordx2 v[70:71], v[30:31], off
	global_load_dwordx4 v[30:33], v[162:163], off offset:64
	s_waitcnt vmcnt(0)
	v_pk_mul_f32 v[30:31], v[30:31], v[0:1] op_sel_hi:[1,0]
	s_nop 0
	v_pk_mul_f32 v[26:27], v[26:27], v[30:31]
	v_pk_mul_f32 v[30:31], v[32:33], v[0:1] op_sel_hi:[1,0]
	v_cvt_pk_bf16_f32 v26, v26, v27
	v_pk_mul_f32 v[28:29], v[28:29], v[30:31]
	s_nop 0
	v_cvt_pk_bf16_f32 v27, v28, v29
	global_store_dwordx2 v[70:71], v[26:27], off offset:32
	global_load_dwordx4 v[26:29], v[162:163], off offset:128
	s_waitcnt vmcnt(0)
	v_pk_mul_f32 v[26:27], v[26:27], v[0:1] op_sel_hi:[1,0]
	s_nop 0
	v_pk_mul_f32 v[22:23], v[22:23], v[26:27]
	v_pk_mul_f32 v[26:27], v[28:29], v[0:1] op_sel_hi:[1,0]
	v_cvt_pk_bf16_f32 v22, v22, v23
	v_pk_mul_f32 v[24:25], v[24:25], v[26:27]
	v_mov_b32_e32 v26, v61
	v_cvt_pk_bf16_f32 v23, v24, v25
	global_store_dwordx2 v[70:71], v[22:23], off offset:64
	global_load_dwordx4 v[22:25], v[162:163], off offset:192
	v_mov_b32_e32 v27, v65
	s_waitcnt vmcnt(0)
	v_pk_mul_f32 v[22:23], v[22:23], v[0:1] op_sel_hi:[1,0]
	s_nop 0
	v_pk_mul_f32 v[18:19], v[18:19], v[22:23]
	v_pk_mul_f32 v[22:23], v[24:25], v[0:1] op_sel_hi:[1,0]
	v_cvt_pk_bf16_f32 v18, v18, v19
	v_pk_mul_f32 v[20:21], v[20:21], v[22:23]
	s_nop 0
	v_cvt_pk_bf16_f32 v19, v20, v21
	global_store_dwordx2 v[70:71], v[18:19], off offset:96
	v_pk_mul_f32 v[18:19], v[34:35], v[0:1] op_sel_hi:[1,0]
	v_mov_b32_e32 v20, v53
	v_pk_mul_f32 v[32:33], v[50:51], v[18:19]
	v_pk_mul_f32 v[18:19], v[38:39], v[0:1] op_sel_hi:[1,0]
	v_mov_b32_e32 v21, v57
	v_pk_mul_f32 v[30:31], v[54:55], v[18:19]
	v_pk_mul_f32 v[18:19], v[46:47], v[0:1] op_sel_hi:[1,0]
	s_nop 0
	v_pk_mul_f32 v[28:29], v[58:59], v[18:19]
	v_pk_mul_f32 v[18:19], v[42:43], v[0:1] op_sel_hi:[1,0]
	s_nop 0
	v_pk_mul_f32 v[24:25], v[62:63], v[18:19]
	v_mul_f32_e32 v18, v36, v0
	v_mul_f32_e32 v66, v52, v18
	v_mul_f32_e32 v18, v40, v0
	v_mul_f32_e32 v68, v56, v18
	v_mul_f32_e32 v18, v48, v0
	v_mul_f32_e32 v80, v60, v18
	v_mul_f32_e32 v18, v44, v0
	v_mul_f32_e32 v82, v64, v18
	v_mov_b32_e32 v18, v37
	v_mov_b32_e32 v19, v41
	v_pk_mul_f32 v[22:23], v[18:19], v[0:1] op_sel_hi:[1,0]
	s_nop 0
	v_pk_mul_f32 v[84:85], v[20:21], v[22:23]
	v_mov_b32_e32 v22, v49
	v_mov_b32_e32 v23, v45
	v_pk_mul_f32 v[86:87], v[22:23], v[0:1] op_sel_hi:[1,0]
	s_nop 0
	v_pk_mul_f32 v[86:87], v[26:27], v[86:87]
	s_and_saveexec_b64 s[8:9], s[20:21]
	s_cbranch_execz .LBB0_1284
	global_load_dwordx4 v[90:93], v[78:79], off
	global_load_dwordx4 v[94:97], v[74:75], off
	global_load_dwordx4 v[98:101], v[76:77], off
	global_load_dwordx4 v[102:105], v[72:73], off
	s_waitcnt vmcnt(3)
	v_mul_f32_e32 v110, v66, v92
	s_waitcnt vmcnt(2)
	v_mul_f32_e32 v112, v68, v96
	v_mul_f32_e32 v68, v68, v92
	v_mov_b32_e32 v92, v97
	v_mul_f32_e32 v114, v66, v96
	s_waitcnt vmcnt(1)
	v_mul_f32_e32 v116, v80, v100
	s_waitcnt vmcnt(0)
	v_mul_f32_e32 v118, v82, v104
	v_mul_f32_e32 v82, v82, v100
	v_mul_f32_e32 v120, v80, v104
	v_mov_b32_e32 v96, v93
	v_pk_mul_f32 v[80:81], v[84:85], v[92:93]
	v_mov_b32_e32 v104, v101
	v_mov_b32_e32 v100, v105
	v_pk_mul_f32 v[66:67], v[84:85], v[96:97]
	v_mov_b32_e32 v69, v81
	v_mov_b32_e32 v115, v80
	v_pk_mul_f32 v[80:81], v[86:87], v[104:105]
	v_pk_mul_f32 v[84:85], v[86:87], v[100:101]
	v_mov_b32_e32 v111, v66
	v_mov_b32_e32 v113, v67
	v_mov_b32_e32 v117, v80
	v_mov_b32_e32 v119, v81
	v_mov_b32_e32 v83, v85
	v_mov_b32_e32 v121, v84
	v_pk_mul_f32 v[106:107], v[30:31], v[94:95]
	v_pk_mul_f32 v[94:95], v[32:33], v[94:95]
	v_pk_mul_f32 v[108:109], v[24:25], v[102:103]
	v_pk_mul_f32 v[102:103], v[28:29], v[102:103]
	v_pk_add_f32 v[66:67], v[110:111], v[112:113] neg_lo:[0,1] neg_hi:[0,1]
	v_pk_add_f32 v[68:69], v[68:69], v[114:115]
	v_pk_add_f32 v[80:81], v[116:117], v[118:119] neg_lo:[0,1] neg_hi:[0,1]
	v_pk_add_f32 v[82:83], v[82:83], v[120:121]
	v_pk_fma_f32 v[32:33], v[32:33], v[90:91], v[106:107] neg_lo:[0,0,1] neg_hi:[0,0,1]
	v_pk_fma_f32 v[30:31], v[30:31], v[90:91], v[94:95]
	v_pk_fma_f32 v[28:29], v[28:29], v[98:99], v[108:109] neg_lo:[0,0,1] neg_hi:[0,0,1]
	v_pk_fma_f32 v[24:25], v[24:25], v[98:99], v[102:103]
	v_mov_b32_e32 v84, v67
	v_mov_b32_e32 v85, v69
	v_mov_b32_e32 v86, v81
	v_mov_b32_e32 v87, v83
.LBB0_1284:
	s_or_b64 exec, exec, s[8:9]
	v_cvt_pk_bf16_f32 v32, v32, v33
	v_cvt_pk_bf16_f32 v33, v66, v84
	v_cvt_pk_bf16_f32 v30, v30, v31
	v_cvt_pk_bf16_f32 v31, v68, v85
	v_cvt_pk_bf16_f32 v28, v28, v29
	v_cvt_pk_bf16_f32 v29, v80, v86
	v_cvt_pk_bf16_f32 v24, v24, v25
	v_cvt_pk_bf16_f32 v25, v82, v87
	global_store_dwordx2 v[70:71], v[32:33], off offset:128
	global_store_dwordx2 v[70:71], v[30:31], off offset:160
	global_store_dwordx2 v[70:71], v[28:29], off offset:192
	global_store_dwordx2 v[70:71], v[24:25], off offset:224
	global_load_dwordx4 v[28:31], v[162:163], off
	v_fmac_f32_e32 v88, v14, v14
	v_fmac_f32_e32 v88, v15, v15
	v_fmac_f32_e32 v88, v16, v16
	v_fmac_f32_e32 v88, v17, v17
	v_fmac_f32_e32 v88, v10, v10
	v_fmac_f32_e32 v88, v11, v11
	v_fmac_f32_e32 v88, v12, v12
	v_pk_mul_f32 v[32:33], v[6:7], v[6:7]
	v_fmac_f32_e32 v88, v13, v13
	v_add_f32_e32 v0, v32, v88
	v_pk_mul_f32 v[24:25], v[8:9], v[8:9]
	v_add_f32_e32 v0, v33, v0
	v_add_f32_e32 v0, v24, v0
	v_pk_mul_f32 v[68:69], v[2:3], v[2:3]
	v_add_f32_e32 v0, v25, v0
	v_add_f32_e32 v0, v68, v0
	v_pk_mul_f32 v[66:67], v[4:5], v[4:5]
	v_add_f32_e32 v0, v69, v0
	v_add_f32_e32 v0, v66, v0
	v_add_f32_e32 v0, v67, v0
	v_mov_b32_e32 v24, v0
	s_waitcnt lgkmcnt(0)
	s_nop 1
	v_permlane16_swap_b32_e32 v24, v0
	v_add_f32_e32 v0, v0, v24
	v_mov_b32_e32 v24, v0
	s_waitcnt lgkmcnt(0)
	s_nop 1
	v_permlane32_swap_b32_e32 v24, v0
	v_add_f32_e32 v0, v0, v24
	v_fmamk_f32 v0, v0, 0x3c000000, v178
	v_mul_f32_e32 v24, 0x4b800000, v0
	v_cmp_gt_f32_e32 vcc, s64, v0
	s_nop 1
	v_cndmask_b32_e32 v0, v0, v24, vcc
	v_rsq_f32_e32 v0, v0
	s_nop 0
	v_mul_f32_e32 v24, 0x45800000, v0
	v_cndmask_b32_e32 v0, v0, v24, vcc
	v_mul_f32_e32 v37, v44, v0
	v_pk_mul_f32 v[32:33], v[22:23], v[0:1] op_sel_hi:[1,0]
	v_mul_f32_e32 v22, v64, v37
	s_waitcnt vmcnt(0)
	v_pk_mul_f32 v[24:25], v[28:29], v[0:1] op_sel_hi:[1,0]
	v_pk_mul_f32 v[28:29], v[30:31], v[0:1] op_sel_hi:[1,0]
	v_pk_mul_f32 v[14:15], v[14:15], v[24:25]
	v_pk_mul_f32 v[16:17], v[16:17], v[28:29]
	v_cvt_pk_bf16_f32 v14, v14, v15
	v_cvt_pk_bf16_f32 v15, v16, v17
	global_store_dwordx2 v[70:71], v[14:15], off offset:256
	global_load_dwordx4 v[14:17], v[162:163], off offset:64
	v_pk_mul_f32 v[24:25], v[18:19], v[0:1] op_sel_hi:[1,0]
	s_waitcnt vmcnt(0)
	v_pk_mul_f32 v[14:15], v[14:15], v[0:1] op_sel_hi:[1,0]
	v_pk_mul_f32 v[16:17], v[16:17], v[0:1] op_sel_hi:[1,0]
	v_pk_mul_f32 v[10:11], v[10:11], v[14:15]
	v_pk_mul_f32 v[12:13], v[12:13], v[16:17]
	v_cvt_pk_bf16_f32 v10, v10, v11
	v_cvt_pk_bf16_f32 v11, v12, v13
	global_store_dwordx2 v[70:71], v[10:11], off offset:288
	global_load_dwordx4 v[10:13], v[162:163], off offset:128
	v_pk_mul_f32 v[20:21], v[20:21], v[24:25]
	v_pk_mul_f32 v[14:15], v[46:47], v[0:1] op_sel_hi:[1,0]
	v_pk_mul_f32 v[16:17], v[42:43], v[0:1] op_sel_hi:[1,0]
	s_waitcnt vmcnt(0)
	v_pk_mul_f32 v[10:11], v[10:11], v[0:1] op_sel_hi:[1,0]
	v_pk_mul_f32 v[12:13], v[12:13], v[0:1] op_sel_hi:[1,0]
	v_pk_mul_f32 v[6:7], v[6:7], v[10:11]
	v_pk_mul_f32 v[8:9], v[8:9], v[12:13]
	v_cvt_pk_bf16_f32 v6, v6, v7
	v_cvt_pk_bf16_f32 v7, v8, v9
	global_store_dwordx2 v[70:71], v[6:7], off offset:320
	global_load_dwordx4 v[28:31], v[162:163], off offset:192
	v_pk_mul_f32 v[6:7], v[34:35], v[0:1] op_sel_hi:[1,0]
	v_pk_mul_f32 v[8:9], v[38:39], v[0:1] op_sel_hi:[1,0]
	v_mul_f32_e32 v34, v36, v0
	v_mul_f32_e32 v35, v40, v0
	v_mul_f32_e32 v36, v48, v0
	v_pk_mul_f32 v[12:13], v[50:51], v[6:7]
	v_pk_mul_f32 v[10:11], v[54:55], v[8:9]
	v_pk_mul_f32 v[8:9], v[58:59], v[14:15]
	v_pk_mul_f32 v[6:7], v[62:63], v[16:17]
	v_mul_f32_e32 v14, v52, v34
	v_mul_f32_e32 v16, v56, v35
	v_mul_f32_e32 v18, v60, v36
	s_waitcnt vmcnt(0)
	v_pk_mul_f32 v[24:25], v[28:29], v[0:1] op_sel_hi:[1,0]
	v_pk_mul_f32 v[28:29], v[30:31], v[0:1] op_sel_hi:[1,0]
	v_pk_mul_f32 v[2:3], v[2:3], v[24:25]
	v_pk_mul_f32 v[4:5], v[4:5], v[28:29]
	v_cvt_pk_bf16_f32 v2, v2, v3
	v_cvt_pk_bf16_f32 v3, v4, v5
	global_store_dwordx2 v[70:71], v[2:3], off offset:352
	v_pk_mul_f32 v[2:3], v[26:27], v[32:33]
	s_and_saveexec_b64 s[8:9], s[20:21]
	s_cbranch_execz .LBB0_1286
	global_load_dwordx4 v[24:27], v[78:79], off
	global_load_dwordx4 v[28:31], v[74:75], off
	global_load_dwordx4 v[32:35], v[76:77], off
	global_load_dwordx4 v[36:39], v[72:73], off
	s_waitcnt vmcnt(3)
	v_mul_f32_e32 v42, v14, v26
	s_waitcnt vmcnt(2)
	v_pk_mul_f32 v[4:5], v[10:11], v[28:29]
	v_mul_f32_e32 v44, v16, v30
	v_mul_f32_e32 v16, v16, v26
	v_mov_b32_e32 v26, v31
	v_pk_mul_f32 v[28:29], v[12:13], v[28:29]
	v_mul_f32_e32 v46, v14, v30
	s_waitcnt vmcnt(1)
	v_mul_f32_e32 v48, v18, v34
	s_waitcnt vmcnt(0)
	v_mul_f32_e32 v50, v22, v38
	v_mul_f32_e32 v22, v22, v34
	v_mul_f32_e32 v52, v18, v38
	v_mov_b32_e32 v30, v27
	v_pk_fma_f32 v[12:13], v[12:13], v[24:25], v[4:5] neg_lo:[0,0,1] neg_hi:[0,0,1]
	v_pk_mul_f32 v[4:5], v[20:21], v[26:27]
	v_mov_b32_e32 v38, v35
	v_mov_b32_e32 v34, v39
	v_pk_mul_f32 v[14:15], v[20:21], v[30:31]
	v_mov_b32_e32 v17, v5
	v_mov_b32_e32 v47, v4
	v_pk_mul_f32 v[4:5], v[2:3], v[38:39]
	v_pk_mul_f32 v[2:3], v[2:3], v[34:35]
	v_mov_b32_e32 v43, v14
	v_mov_b32_e32 v45, v15
	v_mov_b32_e32 v49, v4
	v_mov_b32_e32 v51, v5
	v_mov_b32_e32 v23, v3
	v_mov_b32_e32 v53, v2
	v_pk_mul_f32 v[40:41], v[6:7], v[36:37]
	v_pk_mul_f32 v[36:37], v[8:9], v[36:37]
	v_pk_add_f32 v[14:15], v[42:43], v[44:45] neg_lo:[0,1] neg_hi:[0,1]
	v_pk_add_f32 v[16:17], v[16:17], v[46:47]
	v_pk_add_f32 v[18:19], v[48:49], v[50:51] neg_lo:[0,1] neg_hi:[0,1]
	v_pk_add_f32 v[22:23], v[22:23], v[52:53]
	v_pk_fma_f32 v[10:11], v[10:11], v[24:25], v[28:29]
	v_pk_fma_f32 v[8:9], v[8:9], v[32:33], v[40:41] neg_lo:[0,0,1] neg_hi:[0,0,1]
	v_pk_fma_f32 v[6:7], v[6:7], v[32:33], v[36:37]
	v_mov_b32_e32 v20, v15
	v_mov_b32_e32 v21, v17
	v_mov_b32_e32 v2, v19
	v_mov_b32_e32 v3, v23

.LBB0_1293:
	s_waitcnt vmcnt(10)
	v_mul_f32_e32 v134, v111, v111
	v_fmac_f32_e32 v134, v110, v110
	v_fmac_f32_e32 v134, v112, v112
	v_fmac_f32_e32 v134, v113, v113
	v_fmac_f32_e32 v134, v106, v106
	v_fmac_f32_e32 v134, v107, v107
	v_fmac_f32_e32 v134, v108, v108
	v_fmac_f32_e32 v134, v109, v109
	v_fmac_f32_e32 v134, v102, v102
	v_fmac_f32_e32 v134, v103, v103
	v_fmac_f32_e32 v134, v104, v104
	v_fmac_f32_e32 v134, v105, v105
	v_fmac_f32_e32 v134, v98, v98
	v_mov_b32_e32 v0, v179
	v_mov_b32_e32 v130, v179
	v_fmac_f32_e32 v134, v99, v99
	v_fmac_f32_e32 v134, v100, v100
	s_waitcnt vmcnt(6)
	v_and_b32_e32 v153, 15, v0
	v_and_b32_e32 v130, 0xffffffc0, v130
	v_or_b32_e32 v131, s8, v153
	v_fmac_f32_e32 v134, v101, v101
	v_add_u32_e32 v150, v131, v130
	v_and_b32_e32 v131, 64, v215
	v_fmac_f32_e32 v134, v126, v126
	v_xor_b32_e32 v130, 16, v215
	v_add_u32_e32 v131, 64, v131
	v_fmac_f32_e32 v134, v127, v127
	v_cmp_lt_i32_e32 vcc, v130, v131
	v_fmac_f32_e32 v134, v128, v128
	s_mov_b64 s[20:21], 0
	v_cndmask_b32_e32 v130, v215, v130, vcc
	v_fmac_f32_e32 v134, v129, v129
	s_waitcnt vmcnt(2)
	v_lshlrev_b32_e32 v168, 2, v130
	v_xor_b32_e32 v130, 32, v215
	v_lshrrev_b32_e32 v0, 2, v0
	v_fmac_f32_e32 v134, v122, v122
	s_add_u32 s20, s90, s20
	v_cmp_lt_i32_e32 vcc, v130, v131
	v_and_b32_e32 v151, 12, v0
	v_fmac_f32_e32 v134, v123, v123
	s_addc_u32 s21, s91, s21
	v_cndmask_b32_e32 v130, v215, v130, vcc
	v_lshlrev_b32_e32 v0, 2, v151
	v_fmac_f32_e32 v134, v124, v124
	v_lshlrev_b32_e32 v169, 2, v130
	v_lshl_add_u64 v[130:131], s[20:21], 0, v[0:1]
	s_mov_b64 s[8:9], 0x7b700
	v_fmac_f32_e32 v134, v125, v125
	v_pk_mul_f32 v[132:133], v[118:119], v[118:119]
	v_lshl_add_u64 v[148:149], v[130:131], 0, s[8:9]
	s_mov_b64 s[8:9], 0x7c700
	v_add_f32_e32 v132, v134, v132
	v_lshl_add_u64 v[146:147], v[130:131], 0, s[8:9]
	v_pk_mul_f32 v[130:131], v[120:121], v[120:121]
	v_add_f32_e32 v132, v133, v132
	v_add_f32_e32 v130, v130, v132
	v_add_f32_e32 v134, v131, v130
	v_pk_mul_f32 v[132:133], v[114:115], v[114:115]
	v_pk_mul_f32 v[130:131], v[116:117], v[116:117]
	v_add_f32_e32 v132, v134, v132
	v_add_f32_e32 v132, v133, v132
	v_add_f32_e32 v130, v130, v132
	v_add_f32_e32 v130, v131, v130
	v_mov_b32_e32 v131, v130
	s_waitcnt lgkmcnt(0)
	s_nop 1
	v_permlane16_swap_b32_e32 v131, v130
	v_add_f32_e32 v130, v130, v131
	v_mov_b32_e32 v131, v130
	s_waitcnt lgkmcnt(0)
	s_nop 1
	v_permlane32_swap_b32_e32 v131, v130
	v_add_f32_e32 v130, v130, v131
	v_fmamk_f32 v130, v130, 0x3c000000, v178
	v_cmp_gt_f32_e32 vcc, s64, v130
	v_mul_f32_e32 v131, 0x4b800000, v130
	s_nop 0
	v_cndmask_b32_e32 v130, v130, v131, vcc
	v_rsq_f32_e32 v130, v130
	s_nop 0
	v_mul_f32_e32 v131, 0x45800000, v130
	v_cndmask_b32_e32 v152, v130, v131, vcc
	global_load_dwordx4 v[142:145], v0, s[2:3]
	global_load_dwordx4 v[138:141], v0, s[2:3] offset:64
	global_load_dwordx4 v[134:137], v0, s[2:3] offset:128
	global_load_dwordx4 v[130:133], v0, s[2:3] offset:192
	global_load_dwordx4 v[160:163], v0, s[2:3] offset:256
	global_load_dwordx4 v[164:167], v0, s[2:3] offset:320
	v_cmp_lt_i32_e32 vcc, s11, v150
	s_waitcnt vmcnt(1)
	v_mul_f32_e32 v154, v162, v152
	v_mul_f32_e32 v158, v128, v154
	v_pk_mul_f32 v[154:155], v[160:161], v[152:153] op_sel_hi:[1,0]
	s_waitcnt vmcnt(0)
	v_mov_b32_e32 v162, v167
	v_pk_mul_f32 v[156:157], v[126:127], v[154:155]
	v_pk_mul_f32 v[126:127], v[164:165], v[152:153] op_sel_hi:[1,0]
	v_mov_b32_e32 v128, v125
	v_pk_mul_f32 v[154:155], v[122:123], v[126:127]
	v_mul_f32_e32 v122, v166, v152
	v_mul_f32_e32 v160, v124, v122
	v_pk_mul_f32 v[122:123], v[162:163], v[152:153] op_sel_hi:[1,0]
	s_nop 0
	v_pk_mul_f32 v[164:165], v[128:129], v[122:123]
	global_load_dwordx4 v[122:125], v0, s[2:3] offset:384
	global_load_dwordx4 v[126:129], v0, s[2:3] offset:448
	s_waitcnt vmcnt(1)
	v_pk_mul_f32 v[122:123], v[122:123], v[152:153] op_sel_hi:[1,0]
	v_mul_f32_e32 v124, v124, v152
	v_pk_mul_f32 v[166:167], v[118:119], v[122:123]
	s_waitcnt vmcnt(0)
	v_pk_mul_f32 v[118:119], v[152:153], v[126:127] op_sel_hi:[0,1]
	v_mul_f32_e32 v162, v120, v124
	v_pk_mul_f32 v[122:123], v[114:115], v[118:119]
	v_mul_f32_e32 v114, v152, v128
	v_mov_b32_e32 v124, v129
	v_mul_f32_e32 v126, v116, v114
	v_pk_mul_f32 v[114:115], v[152:153], v[124:125] op_sel_hi:[0,1]
	v_mov_b32_e32 v120, v117
	v_pk_mul_f32 v[120:121], v[120:121], v[114:115]
	v_and_b32_e32 v116, 0xfc0, v150
	s_and_saveexec_b64 s[8:9], vcc
	s_cbranch_execz .LBB0_1295
	v_mov_b32_e32 v117, v1
	v_lshl_add_u64 v[114:115], v[148:149], 0, v[116:117]
	global_load_dwordx4 v[170:173], v[114:115], off
	v_lshl_add_u64 v[114:115], v[146:147], 0, v[116:117]
	global_load_dwordx4 v[174:177], v[114:115], off
	v_lshlrev_b32_e32 v114, 6, v153
	v_mov_b32_e32 v115, v1
	v_lshl_add_u64 v[118:119], v[148:149], 0, v[114:115]
	v_lshl_add_u64 v[114:115], v[146:147], 0, v[114:115]
	global_load_dwordx4 v[180:183], v[118:119], off
	global_load_dwordx4 v[184:187], v[114:115], off
	s_waitcnt vmcnt(2)
	v_pk_mul_f32 v[114:115], v[154:155], v[174:175]
	v_mul_f32_e32 v188, v158, v176
	v_pk_mul_f32 v[118:119], v[156:157], v[174:175]
	v_pk_fma_f32 v[156:157], v[156:157], v[170:171], v[114:115] neg_lo:[0,0,1] neg_hi:[0,0,1]
	v_mul_f32_e32 v174, v158, v172
	s_waitcnt vmcnt(1)
	v_mul_f32_e32 v190, v162, v182
	s_waitcnt vmcnt(0)
	v_pk_mul_f32 v[124:125], v[122:123], v[184:185]
	v_pk_mul_f32 v[128:129], v[166:167], v[184:185]
	v_mul_f32_e32 v184, v160, v176
	v_mov_b32_e32 v176, v173
	v_mul_f32_e32 v192, v126, v186
	v_mul_f32_e32 v126, v126, v182
	v_pk_mul_f32 v[114:115], v[164:165], v[176:177]
	v_mov_b32_e32 v182, v187
	v_mul_f32_e32 v160, v160, v172
	v_mul_f32_e32 v194, v162, v186
	v_mov_b32_e32 v172, v177
	v_mov_b32_e32 v161, v114
	v_mov_b32_e32 v189, v115
	v_pk_mul_f32 v[114:115], v[120:121], v[182:183]
	v_mov_b32_e32 v186, v183
	v_pk_mul_f32 v[158:159], v[164:165], v[172:173]
	v_mov_b32_e32 v191, v115
	v_mov_b32_e32 v193, v114
	v_pk_mul_f32 v[114:115], v[120:121], v[186:187]
	v_mov_b32_e32 v175, v159
	v_mov_b32_e32 v185, v158
	v_mov_b32_e32 v127, v114
	v_mov_b32_e32 v195, v115
	v_pk_add_f32 v[158:159], v[174:175], v[184:185] neg_lo:[0,1] neg_hi:[0,1]
	v_pk_add_f32 v[160:161], v[160:161], v[188:189]
	v_pk_add_f32 v[162:163], v[190:191], v[192:193] neg_lo:[0,1] neg_hi:[0,1]
	v_pk_add_f32 v[126:127], v[126:127], v[194:195]
	v_pk_fma_f32 v[154:155], v[154:155], v[170:171], v[118:119]
	v_pk_fma_f32 v[166:167], v[166:167], v[180:181], v[124:125] neg_lo:[0,0,1] neg_hi:[0,0,1]
	v_pk_fma_f32 v[122:123], v[122:123], v[180:181], v[128:129]
	v_mov_b32_e32 v120, v127
	v_mov_b32_e32 v121, v163
	v_mov_b32_e32 v164, v161
	v_mov_b32_e32 v165, v159
.LBB0_1295:
	s_or_b64 exec, exec, s[8:9]
	v_mov_b32_e32 v153, v152
	v_pk_mul_f32 v[124:125], v[142:143], v[152:153]
	s_lshl_b32 s8, s13, 1
	v_pk_mul_f32 v[110:111], v[110:111], v[124:125]
	v_pk_mul_f32 v[124:125], v[144:145], v[152:153]
	s_add_u32 s8, s20, s8
	v_pk_mul_f32 v[112:113], v[112:113], v[124:125]
	v_pk_mul_f32 v[124:125], v[138:139], v[152:153]
	v_lshl_add_u64 v[118:119], s[2:3], 0, v[0:1]
	v_pk_mul_f32 v[106:107], v[106:107], v[124:125]
	v_pk_mul_f32 v[124:125], v[140:141], v[152:153]
	s_addc_u32 s9, s21, 0
	v_pk_mul_f32 v[108:109], v[108:109], v[124:125]
	v_pk_mul_f32 v[124:125], v[134:135], v[152:153]
	v_lshlrev_b32_e32 v0, 1, v151
	v_pk_mul_f32 v[102:103], v[102:103], v[124:125]
	v_pk_mul_f32 v[124:125], v[136:137], v[152:153]
	v_lshl_add_u64 v[114:115], s[8:9], 0, v[0:1]
	v_pk_mul_f32 v[104:105], v[104:105], v[124:125]
	v_pk_mul_f32 v[124:125], v[130:131], v[152:153]
	s_mov_b64 s[8:9], 0x1733d700
	v_pk_mul_f32 v[98:99], v[98:99], v[124:125]
	v_pk_mul_f32 v[124:125], v[132:133], v[152:153]
	v_ashrrev_i32_e32 v151, 31, v150
	v_lshl_add_u64 v[114:115], v[114:115], 0, s[8:9]
	v_pk_mul_f32 v[100:101], v[100:101], v[124:125]
	v_lshlrev_b64 v[124:125], 11, v[150:151]
	v_lshl_add_u64 v[124:125], v[114:115], 0, v[124:125]
	v_cvt_pk_bf16_f32 v98, v98, v99
	v_cvt_pk_bf16_f32 v99, v100, v101
	global_store_dwordx2 v[124:125], v[98:99], off offset:96
	v_cvt_pk_bf16_f32 v98, v156, v157
	v_cvt_pk_bf16_f32 v99, v158, v165
	global_store_dwordx2 v[124:125], v[98:99], off offset:128
	v_cvt_pk_bf16_f32 v98, v154, v155
	v_cvt_pk_bf16_f32 v99, v160, v164
	global_store_dwordx2 v[124:125], v[98:99], off offset:160
	v_cvt_pk_bf16_f32 v98, v166, v167
	v_cvt_pk_bf16_f32 v99, v162, v121
	v_cvt_pk_bf16_f32 v110, v110, v111
	v_cvt_pk_bf16_f32 v111, v112, v113
	v_cvt_pk_bf16_f32 v106, v106, v107
	v_cvt_pk_bf16_f32 v107, v108, v109
	v_cvt_pk_bf16_f32 v102, v102, v103
	v_cvt_pk_bf16_f32 v103, v104, v105
	global_store_dwordx2 v[124:125], v[98:99], off offset:192
	v_cvt_pk_bf16_f32 v98, v122, v123
	v_cvt_pk_bf16_f32 v99, v126, v120
	global_store_dwordx2 v[124:125], v[110:111], off
	global_store_dwordx2 v[124:125], v[106:107], off offset:32
	global_store_dwordx2 v[124:125], v[102:103], off offset:64
	global_store_dwordx2 v[124:125], v[98:99], off offset:224
	global_load_dwordx4 v[126:129], v[118:119], off offset:256
	global_load_dwordx4 v[130:133], v[118:119], off offset:320
	global_load_dwordx4 v[134:137], v[118:119], off offset:384
	global_load_dwordx4 v[138:141], v[118:119], off offset:448
	global_load_dwordx4 v[110:113], v[118:119], off
	global_load_dwordx4 v[106:109], v[118:119], off offset:64
	global_load_dwordx4 v[102:105], v[118:119], off offset:128
	global_load_dwordx4 v[98:101], v[118:119], off offset:192
	v_mul_f32_e32 v0, v79, v79
	v_fmac_f32_e32 v0, v78, v78
	v_fmac_f32_e32 v0, v80, v80
	v_fmac_f32_e32 v0, v81, v81
	v_fmac_f32_e32 v0, v74, v74
	v_fmac_f32_e32 v0, v75, v75
	v_fmac_f32_e32 v0, v76, v76
	v_fmac_f32_e32 v0, v77, v77
	v_fmac_f32_e32 v0, v70, v70
	v_fmac_f32_e32 v0, v71, v71
	v_fmac_f32_e32 v0, v72, v72
	v_fmac_f32_e32 v0, v73, v73
	v_fmac_f32_e32 v0, v66, v66
	v_fmac_f32_e32 v0, v67, v67
	v_fmac_f32_e32 v0, v68, v68
	v_fmac_f32_e32 v0, v69, v69
	v_fmac_f32_e32 v0, v94, v94
	v_fmac_f32_e32 v0, v95, v95
	v_fmac_f32_e32 v0, v96, v96
	v_fmac_f32_e32 v0, v97, v97
	v_fmac_f32_e32 v0, v90, v90
	v_fmac_f32_e32 v0, v91, v91
	v_fmac_f32_e32 v0, v92, v92
	v_fmac_f32_e32 v0, v93, v93
	v_pk_mul_f32 v[122:123], v[86:87], v[86:87]
	v_pk_mul_f32 v[120:121], v[88:89], v[88:89]
	v_add_f32_e32 v0, v0, v122
	v_add_f32_e32 v0, v123, v0
	v_add_f32_e32 v0, v120, v0
	v_add_f32_e32 v0, v121, v0
	v_pk_mul_f32 v[122:123], v[82:83], v[82:83]
	v_pk_mul_f32 v[120:121], v[84:85], v[84:85]
	v_add_f32_e32 v0, v0, v122
	v_add_f32_e32 v0, v123, v0
	v_add_f32_e32 v0, v120, v0
	v_add_f32_e32 v0, v121, v0
	v_mov_b32_e32 v117, v0
	v_or_b32_e32 v120, 16, v150
	s_waitcnt lgkmcnt(0)
	s_nop 1
	v_permlane16_swap_b32_e32 v117, v0
	v_add_f32_e32 v0, v0, v117
	v_mov_b32_e32 v117, v0
	s_waitcnt lgkmcnt(0)
	s_nop 1
	v_permlane32_swap_b32_e32 v117, v0
	v_add_f32_e32 v0, v0, v117
	v_fmamk_f32 v0, v0, 0x3c000000, v178
	v_mul_f32_e32 v117, 0x4b800000, v0
	v_cmp_gt_f32_e32 vcc, s64, v0
	s_nop 1
	v_cndmask_b32_e32 v0, v0, v117, vcc
	v_rsq_f32_e32 v0, v0
	s_nop 0
	v_mul_f32_e32 v117, 0x45800000, v0
	v_cndmask_b32_e32 v124, v0, v117, vcc
	v_cmp_lt_i32_e32 vcc, s11, v120
	s_waitcnt vmcnt(7)
	v_mul_f32_e32 v0, v128, v124
	v_pk_mul_f32 v[126:127], v[126:127], v[124:125] op_sel_hi:[1,0]
	v_mul_f32_e32 v122, v96, v0
	v_pk_mul_f32 v[94:95], v[94:95], v[126:127]
	s_waitcnt vmcnt(6)
	v_pk_mul_f32 v[126:127], v[130:131], v[124:125] op_sel_hi:[1,0]
	v_mul_f32_e32 v0, v132, v124
	v_mov_b32_e32 v128, v133
	v_pk_mul_f32 v[90:91], v[90:91], v[126:127]
	v_mul_f32_e32 v92, v92, v0
	v_pk_mul_f32 v[126:127], v[128:129], v[124:125] op_sel_hi:[1,0]
	v_mov_b32_e32 v96, v93
	s_waitcnt vmcnt(5)
	v_mul_f32_e32 v0, v136, v124
	v_pk_mul_f32 v[128:129], v[134:135], v[124:125] op_sel_hi:[1,0]
	s_waitcnt vmcnt(4)
	v_mov_b32_e32 v136, v141
	v_pk_mul_f32 v[126:127], v[96:97], v[126:127]
	v_mul_f32_e32 v96, v88, v0
	v_pk_mul_f32 v[86:87], v[86:87], v[128:129]
	v_pk_mul_f32 v[128:129], v[124:125], v[138:139] op_sel_hi:[0,1]
	v_mul_f32_e32 v0, v124, v140
	v_pk_mul_f32 v[130:131], v[124:125], v[136:137] op_sel_hi:[0,1]
	v_mov_b32_e32 v88, v85
	v_pk_mul_f32 v[82:83], v[82:83], v[128:129]
	v_mul_f32_e32 v128, v84, v0
	v_pk_mul_f32 v[84:85], v[88:89], v[130:131]
	s_and_saveexec_b64 s[8:9], vcc
	s_cbranch_execz .LBB0_1297
	v_mov_b32_e32 v117, v1
	v_lshl_add_u64 v[88:89], v[148:149], 0, v[116:117]
	v_lshlrev_b32_e32 v0, 6, v120
	global_load_dwordx4 v[130:133], v[88:89], off
	v_lshl_add_u64 v[88:89], v[146:147], 0, v[116:117]
	v_and_b32_e32 v0, 0x7c0, v0
	global_load_dwordx4 v[134:137], v[88:89], off
	v_lshl_add_u64 v[88:89], v[148:149], 0, v[0:1]
	global_load_dwordx4 v[138:141], v[88:89], off
	v_lshl_add_u64 v[88:89], v[146:147], 0, v[0:1]
	global_load_dwordx4 v[142:145], v[88:89], off
	s_waitcnt vmcnt(3)
	v_mul_f32_e32 v154, v122, v132
	s_waitcnt vmcnt(2)
	v_pk_mul_f32 v[88:89], v[90:91], v[134:135]
	v_mul_f32_e32 v156, v92, v136
	v_mul_f32_e32 v158, v122, v136
	v_mov_b32_e32 v136, v133
	v_pk_mul_f32 v[134:135], v[94:95], v[134:135]
	v_mul_f32_e32 v92, v92, v132
	s_waitcnt vmcnt(1)
	v_mul_f32_e32 v160, v96, v140
	s_waitcnt vmcnt(0)
	v_mul_f32_e32 v162, v128, v144
	v_mul_f32_e32 v128, v128, v140
	v_mul_f32_e32 v164, v96, v144
	v_mov_b32_e32 v132, v137
	v_pk_fma_f32 v[94:95], v[94:95], v[130:131], v[88:89] neg_lo:[0,0,1] neg_hi:[0,0,1]
	v_pk_mul_f32 v[88:89], v[126:127], v[136:137]
	v_mov_b32_e32 v140, v145
	v_mov_b32_e32 v144, v141
	v_pk_mul_f32 v[96:97], v[126:127], v[132:133]
	v_mov_b32_e32 v93, v88
	v_mov_b32_e32 v159, v89
	v_pk_mul_f32 v[88:89], v[84:85], v[140:141]
	v_pk_mul_f32 v[84:85], v[84:85], v[144:145]
	v_mov_b32_e32 v155, v97
	v_mov_b32_e32 v157, v96
	v_mov_b32_e32 v161, v89
	v_mov_b32_e32 v163, v88
	v_mov_b32_e32 v129, v84
	v_mov_b32_e32 v165, v85
	v_pk_mul_f32 v[152:153], v[82:83], v[142:143]
	v_pk_mul_f32 v[142:143], v[86:87], v[142:143]
	v_pk_add_f32 v[122:123], v[154:155], v[156:157] neg_lo:[0,1] neg_hi:[0,1]
	v_pk_add_f32 v[92:93], v[92:93], v[158:159]
	v_pk_add_f32 v[96:97], v[160:161], v[162:163] neg_lo:[0,1] neg_hi:[0,1]
	v_pk_add_f32 v[128:129], v[128:129], v[164:165]
	v_pk_fma_f32 v[90:91], v[90:91], v[130:131], v[134:135]
	v_pk_fma_f32 v[86:87], v[86:87], v[138:139], v[152:153] neg_lo:[0,0,1] neg_hi:[0,0,1]
	v_pk_fma_f32 v[82:83], v[82:83], v[138:139], v[142:143]
	v_mov_b32_e32 v84, v129
	v_mov_b32_e32 v85, v97
	v_mov_b32_e32 v126, v93
	v_mov_b32_e32 v127, v123
.LBB0_1297:
	s_or_b64 exec, exec, s[8:9]
	v_mov_b32_e32 v125, v124
	s_waitcnt vmcnt(3)
	v_pk_mul_f32 v[88:89], v[110:111], v[124:125]
	v_ashrrev_i32_e32 v121, 31, v120
	v_pk_mul_f32 v[78:79], v[78:79], v[88:89]
	v_pk_mul_f32 v[88:89], v[112:113], v[124:125]
	v_cvt_pk_bf16_f32 v78, v78, v79
	v_pk_mul_f32 v[80:81], v[80:81], v[88:89]
	s_waitcnt vmcnt(2)
	v_pk_mul_f32 v[88:89], v[106:107], v[124:125]
	v_cvt_pk_bf16_f32 v79, v80, v81
	v_pk_mul_f32 v[74:75], v[74:75], v[88:89]
	v_pk_mul_f32 v[88:89], v[108:109], v[124:125]
	v_cvt_pk_bf16_f32 v74, v74, v75
	v_pk_mul_f32 v[76:77], v[76:77], v[88:89]
	s_waitcnt vmcnt(1)
	v_pk_mul_f32 v[88:89], v[102:103], v[124:125]
	v_cvt_pk_bf16_f32 v75, v76, v77
	v_pk_mul_f32 v[70:71], v[70:71], v[88:89]
	v_pk_mul_f32 v[88:89], v[104:105], v[124:125]
	v_cvt_pk_bf16_f32 v70, v70, v71
	v_pk_mul_f32 v[72:73], v[72:73], v[88:89]
	s_waitcnt vmcnt(0)
	v_pk_mul_f32 v[88:89], v[98:99], v[124:125]
	v_cvt_pk_bf16_f32 v71, v72, v73
	v_pk_mul_f32 v[66:67], v[66:67], v[88:89]
	v_pk_mul_f32 v[88:89], v[100:101], v[124:125]
	v_cvt_pk_bf16_f32 v66, v66, v67
	v_pk_mul_f32 v[68:69], v[68:69], v[88:89]
	v_lshlrev_b64 v[88:89], 11, v[120:121]
	v_lshl_add_u64 v[88:89], v[114:115], 0, v[88:89]
	v_cvt_pk_bf16_f32 v67, v68, v69
	global_store_dwordx2 v[88:89], v[66:67], off offset:96
	v_cvt_pk_bf16_f32 v66, v94, v95
	v_cvt_pk_bf16_f32 v67, v122, v127
	global_store_dwordx2 v[88:89], v[66:67], off offset:128
	v_cvt_pk_bf16_f32 v66, v90, v91
	v_cvt_pk_bf16_f32 v67, v92, v126
	global_store_dwordx2 v[88:89], v[66:67], off offset:160
	v_cvt_pk_bf16_f32 v66, v86, v87
	v_cvt_pk_bf16_f32 v67, v96, v85
	global_store_dwordx2 v[88:89], v[66:67], off offset:192
	v_cvt_pk_bf16_f32 v66, v82, v83
	v_cvt_pk_bf16_f32 v67, v128, v84
	global_store_dwordx2 v[88:89], v[78:79], off
	global_store_dwordx2 v[88:89], v[74:75], off offset:32
	global_store_dwordx2 v[88:89], v[70:71], off offset:64
	global_store_dwordx2 v[88:89], v[66:67], off offset:224
	global_load_dwordx4 v[88:91], v[118:119], off offset:256
	s_nop 0
	global_load_dwordx4 v[92:95], v[118:119], off offset:320
	global_load_dwordx4 v[96:99], v[118:119], off offset:384
	global_load_dwordx4 v[100:103], v[118:119], off offset:448
	global_load_dwordx4 v[78:81], v[118:119], off
	global_load_dwordx4 v[74:77], v[118:119], off offset:64
	global_load_dwordx4 v[70:73], v[118:119], off offset:128
	global_load_dwordx4 v[66:69], v[118:119], off offset:192
	v_mul_f32_e32 v0, v47, v47
	v_fmac_f32_e32 v0, v46, v46
	v_fmac_f32_e32 v0, v48, v48
	v_fmac_f32_e32 v0, v49, v49
	v_fmac_f32_e32 v0, v42, v42
	v_fmac_f32_e32 v0, v43, v43
	v_fmac_f32_e32 v0, v44, v44
	v_fmac_f32_e32 v0, v45, v45
	v_fmac_f32_e32 v0, v38, v38
	v_fmac_f32_e32 v0, v39, v39
	v_fmac_f32_e32 v0, v40, v40
	v_fmac_f32_e32 v0, v41, v41
	v_fmac_f32_e32 v0, v34, v34
	v_fmac_f32_e32 v0, v35, v35
	v_fmac_f32_e32 v0, v36, v36
	v_fmac_f32_e32 v0, v37, v37
	v_fmac_f32_e32 v0, v62, v62
	v_fmac_f32_e32 v0, v63, v63
	v_fmac_f32_e32 v0, v64, v64
	v_fmac_f32_e32 v0, v65, v65
	v_fmac_f32_e32 v0, v58, v58
	v_fmac_f32_e32 v0, v59, v59
	v_fmac_f32_e32 v0, v60, v60
	v_fmac_f32_e32 v0, v61, v61
	v_pk_mul_f32 v[84:85], v[54:55], v[54:55]
	v_pk_mul_f32 v[82:83], v[56:57], v[56:57]
	v_add_f32_e32 v0, v0, v84
	v_add_f32_e32 v0, v85, v0
	v_add_f32_e32 v0, v82, v0
	v_add_f32_e32 v0, v83, v0
	v_pk_mul_f32 v[84:85], v[50:51], v[50:51]
	v_pk_mul_f32 v[82:83], v[52:53], v[52:53]
	v_add_f32_e32 v0, v0, v84
	v_add_f32_e32 v0, v85, v0
	v_add_f32_e32 v0, v82, v0
	v_add_f32_e32 v0, v83, v0
	v_mov_b32_e32 v82, v0
	s_waitcnt lgkmcnt(0)
	s_nop 1
	v_permlane16_swap_b32_e32 v82, v0
	v_add_f32_e32 v0, v0, v82
	v_mov_b32_e32 v82, v0
	s_waitcnt lgkmcnt(0)
	s_nop 1
	v_permlane32_swap_b32_e32 v82, v0
	v_add_f32_e32 v0, v0, v82
	v_fmamk_f32 v0, v0, 0x3c000000, v178
	v_mul_f32_e32 v82, 0x4b800000, v0
	v_cmp_gt_f32_e32 vcc, s64, v0
	s_nop 1
	v_cndmask_b32_e32 v0, v0, v82, vcc
	v_rsq_f32_e32 v0, v0
	v_or_b32_e32 v82, 32, v150
	v_mul_f32_e32 v83, 0x45800000, v0
	v_cndmask_b32_e32 v86, v0, v83, vcc
	v_cmp_lt_i32_e32 vcc, s11, v82
	s_waitcnt vmcnt(7)
	v_mul_f32_e32 v0, v90, v86
	v_pk_mul_f32 v[88:89], v[88:89], v[86:87] op_sel_hi:[1,0]
	v_mul_f32_e32 v84, v64, v0
	v_pk_mul_f32 v[62:63], v[62:63], v[88:89]
	s_waitcnt vmcnt(6)
	v_pk_mul_f32 v[88:89], v[92:93], v[86:87] op_sel_hi:[1,0]
	v_mul_f32_e32 v0, v94, v86
	v_mov_b32_e32 v90, v95
	v_pk_mul_f32 v[58:59], v[58:59], v[88:89]
	v_mul_f32_e32 v60, v60, v0
	v_pk_mul_f32 v[88:89], v[90:91], v[86:87] op_sel_hi:[1,0]
	v_mov_b32_e32 v64, v61
	s_waitcnt vmcnt(5)
	v_mul_f32_e32 v0, v98, v86
	v_pk_mul_f32 v[90:91], v[96:97], v[86:87] op_sel_hi:[1,0]
	s_waitcnt vmcnt(4)
	v_mov_b32_e32 v98, v103
	v_pk_mul_f32 v[88:89], v[64:65], v[88:89]
	v_mul_f32_e32 v64, v56, v0
	v_pk_mul_f32 v[54:55], v[54:55], v[90:91]
	v_pk_mul_f32 v[90:91], v[86:87], v[100:101] op_sel_hi:[0,1]
	v_mul_f32_e32 v0, v86, v102
	v_pk_mul_f32 v[92:93], v[86:87], v[98:99] op_sel_hi:[0,1]
	v_mov_b32_e32 v56, v53
	v_pk_mul_f32 v[50:51], v[50:51], v[90:91]
	v_mul_f32_e32 v90, v52, v0
	v_pk_mul_f32 v[52:53], v[56:57], v[92:93]
	s_and_saveexec_b64 s[8:9], vcc
	s_cbranch_execz .LBB0_1299
	v_mov_b32_e32 v117, v1
	v_lshl_add_u64 v[56:57], v[148:149], 0, v[116:117]
	v_lshlrev_b32_e32 v0, 6, v82
	global_load_dwordx4 v[92:95], v[56:57], off
	v_lshl_add_u64 v[56:57], v[146:147], 0, v[116:117]
	v_and_b32_e32 v0, 0xbc0, v0
	global_load_dwordx4 v[96:99], v[56:57], off
	v_lshl_add_u64 v[56:57], v[148:149], 0, v[0:1]
	global_load_dwordx4 v[100:103], v[56:57], off
	v_lshl_add_u64 v[56:57], v[146:147], 0, v[0:1]
	global_load_dwordx4 v[104:107], v[56:57], off
	s_waitcnt vmcnt(3)
	v_mul_f32_e32 v110, v84, v94
	s_waitcnt vmcnt(2)
	v_pk_mul_f32 v[56:57], v[58:59], v[96:97]
	v_mul_f32_e32 v112, v60, v98
	v_mul_f32_e32 v120, v84, v98
	v_mov_b32_e32 v98, v95
	v_pk_mul_f32 v[96:97], v[62:63], v[96:97]
	v_mul_f32_e32 v60, v60, v94
	s_waitcnt vmcnt(1)
	v_mul_f32_e32 v122, v64, v102
	s_waitcnt vmcnt(0)
	v_mul_f32_e32 v124, v90, v106
	v_mul_f32_e32 v90, v90, v102
	v_mul_f32_e32 v126, v64, v106
	v_mov_b32_e32 v94, v99
	v_pk_fma_f32 v[62:63], v[62:63], v[92:93], v[56:57] neg_lo:[0,0,1] neg_hi:[0,0,1]
	v_pk_mul_f32 v[56:57], v[88:89], v[98:99]
	v_mov_b32_e32 v102, v107
	v_mov_b32_e32 v106, v103
	v_pk_mul_f32 v[64:65], v[88:89], v[94:95]
	v_mov_b32_e32 v61, v56
	v_mov_b32_e32 v121, v57
	v_pk_mul_f32 v[56:57], v[52:53], v[102:103]
	v_pk_mul_f32 v[52:53], v[52:53], v[106:107]
	v_mov_b32_e32 v111, v65
	v_mov_b32_e32 v113, v64
	v_mov_b32_e32 v123, v57
	v_mov_b32_e32 v125, v56
	v_mov_b32_e32 v91, v52
	v_mov_b32_e32 v127, v53
	v_pk_mul_f32 v[108:109], v[50:51], v[104:105]
	v_pk_mul_f32 v[104:105], v[54:55], v[104:105]
	v_pk_add_f32 v[84:85], v[110:111], v[112:113] neg_lo:[0,1] neg_hi:[0,1]
	v_pk_add_f32 v[60:61], v[60:61], v[120:121]
	v_pk_add_f32 v[64:65], v[122:123], v[124:125] neg_lo:[0,1] neg_hi:[0,1]
	v_pk_add_f32 v[90:91], v[90:91], v[126:127]
	v_pk_fma_f32 v[58:59], v[58:59], v[92:93], v[96:97]
	v_pk_fma_f32 v[54:55], v[54:55], v[100:101], v[108:109] neg_lo:[0,0,1] neg_hi:[0,0,1]
	v_pk_fma_f32 v[50:51], v[50:51], v[100:101], v[104:105]
	v_mov_b32_e32 v52, v91
	v_mov_b32_e32 v53, v65
	v_mov_b32_e32 v88, v61
	v_mov_b32_e32 v89, v85
.LBB0_1299:
	s_or_b64 exec, exec, s[8:9]
	v_mov_b32_e32 v87, v86
	s_waitcnt vmcnt(3)
	v_pk_mul_f32 v[56:57], v[78:79], v[86:87]
	v_ashrrev_i32_e32 v83, 31, v82
	v_pk_mul_f32 v[46:47], v[46:47], v[56:57]
	v_pk_mul_f32 v[56:57], v[80:81], v[86:87]
	v_cvt_pk_bf16_f32 v46, v46, v47
	v_pk_mul_f32 v[48:49], v[48:49], v[56:57]
	s_waitcnt vmcnt(2)
	v_pk_mul_f32 v[56:57], v[74:75], v[86:87]
	v_cvt_pk_bf16_f32 v47, v48, v49
	v_pk_mul_f32 v[42:43], v[42:43], v[56:57]
	v_pk_mul_f32 v[56:57], v[76:77], v[86:87]
	v_cvt_pk_bf16_f32 v42, v42, v43
	v_pk_mul_f32 v[44:45], v[44:45], v[56:57]
	s_waitcnt vmcnt(1)
	v_pk_mul_f32 v[56:57], v[70:71], v[86:87]
	v_cvt_pk_bf16_f32 v43, v44, v45
	v_pk_mul_f32 v[38:39], v[38:39], v[56:57]
	v_pk_mul_f32 v[56:57], v[72:73], v[86:87]
	v_cvt_pk_bf16_f32 v38, v38, v39
	v_pk_mul_f32 v[40:41], v[40:41], v[56:57]
	s_waitcnt vmcnt(0)
	v_pk_mul_f32 v[56:57], v[66:67], v[86:87]
	v_cvt_pk_bf16_f32 v39, v40, v41
	v_pk_mul_f32 v[34:35], v[34:35], v[56:57]
	v_pk_mul_f32 v[56:57], v[68:69], v[86:87]
	v_cvt_pk_bf16_f32 v34, v34, v35
	v_pk_mul_f32 v[36:37], v[36:37], v[56:57]
	v_lshlrev_b64 v[56:57], 11, v[82:83]
	v_lshl_add_u64 v[56:57], v[114:115], 0, v[56:57]
	v_cvt_pk_bf16_f32 v35, v36, v37
	global_store_dwordx2 v[56:57], v[34:35], off offset:96
	v_cvt_pk_bf16_f32 v34, v62, v63
	v_cvt_pk_bf16_f32 v35, v84, v89
	global_store_dwordx2 v[56:57], v[34:35], off offset:128
	v_cvt_pk_bf16_f32 v34, v58, v59
	v_cvt_pk_bf16_f32 v35, v60, v88
	global_store_dwordx2 v[56:57], v[34:35], off offset:160
	v_cvt_pk_bf16_f32 v34, v54, v55
	v_cvt_pk_bf16_f32 v35, v64, v53
	global_store_dwordx2 v[56:57], v[34:35], off offset:192
	v_cvt_pk_bf16_f32 v34, v50, v51
	v_cvt_pk_bf16_f32 v35, v90, v52
	global_store_dwordx2 v[56:57], v[46:47], off
	global_store_dwordx2 v[56:57], v[42:43], off offset:32
	global_store_dwordx2 v[56:57], v[38:39], off offset:64
	global_store_dwordx2 v[56:57], v[34:35], off offset:224
	global_load_dwordx4 v[56:59], v[118:119], off offset:256
	s_nop 0
	global_load_dwordx4 v[60:63], v[118:119], off offset:320
	global_load_dwordx4 v[64:67], v[118:119], off offset:384
	global_load_dwordx4 v[68:71], v[118:119], off offset:448
	global_load_dwordx4 v[46:49], v[118:119], off
	global_load_dwordx4 v[42:45], v[118:119], off offset:64
	global_load_dwordx4 v[38:41], v[118:119], off offset:128
	global_load_dwordx4 v[34:37], v[118:119], off offset:192
	v_mul_f32_e32 v0, v15, v15
	v_fmac_f32_e32 v0, v14, v14
	v_fmac_f32_e32 v0, v16, v16
	v_fmac_f32_e32 v0, v17, v17
	v_fmac_f32_e32 v0, v10, v10
	v_fmac_f32_e32 v0, v11, v11
	v_fmac_f32_e32 v0, v12, v12
	v_fmac_f32_e32 v0, v13, v13
	v_fmac_f32_e32 v0, v6, v6
	v_fmac_f32_e32 v0, v7, v7
	v_fmac_f32_e32 v0, v8, v8
	v_fmac_f32_e32 v0, v9, v9
	v_fmac_f32_e32 v0, v2, v2
	v_fmac_f32_e32 v0, v3, v3
	v_fmac_f32_e32 v0, v4, v4
	v_fmac_f32_e32 v0, v5, v5
	v_fmac_f32_e32 v0, v30, v30
	v_fmac_f32_e32 v0, v31, v31
	v_fmac_f32_e32 v0, v32, v32
	v_fmac_f32_e32 v0, v33, v33
	v_fmac_f32_e32 v0, v26, v26
	v_fmac_f32_e32 v0, v27, v27
	v_fmac_f32_e32 v0, v28, v28
	v_fmac_f32_e32 v0, v29, v29
	v_pk_mul_f32 v[52:53], v[22:23], v[22:23]
	v_pk_mul_f32 v[50:51], v[24:25], v[24:25]
	v_add_f32_e32 v0, v0, v52
	v_add_f32_e32 v0, v53, v0
	v_add_f32_e32 v0, v50, v0
	v_add_f32_e32 v0, v51, v0
	v_pk_mul_f32 v[52:53], v[18:19], v[18:19]
	v_pk_mul_f32 v[50:51], v[20:21], v[20:21]
	v_add_f32_e32 v0, v0, v52
	v_add_f32_e32 v0, v53, v0
	v_add_f32_e32 v0, v50, v0
	v_add_f32_e32 v0, v51, v0
	v_mov_b32_e32 v50, v0
	v_or_b32_e32 v54, 48, v150
	s_waitcnt lgkmcnt(0)
	s_nop 1
	v_permlane16_swap_b32_e32 v50, v0
	v_add_f32_e32 v0, v0, v50
	v_mov_b32_e32 v50, v0
	s_waitcnt lgkmcnt(0)
	s_nop 1
	v_permlane32_swap_b32_e32 v50, v0
	v_add_f32_e32 v0, v0, v50
	v_fmamk_f32 v0, v0, 0x3c000000, v178
	v_mul_f32_e32 v50, 0x4b800000, v0
	v_cmp_gt_f32_e32 vcc, s64, v0
	s_nop 1
	v_cndmask_b32_e32 v0, v0, v50, vcc
	v_rsq_f32_e32 v0, v0
	s_nop 0
	v_mul_f32_e32 v50, 0x45800000, v0
	v_cndmask_b32_e32 v50, v0, v50, vcc
	v_cmp_lt_i32_e32 vcc, s11, v54
	s_waitcnt vmcnt(7)
	v_mul_f32_e32 v0, v58, v50
	v_pk_mul_f32 v[56:57], v[56:57], v[50:51] op_sel_hi:[1,0]
	v_mul_f32_e32 v52, v32, v0
	v_pk_mul_f32 v[30:31], v[30:31], v[56:57]
	s_waitcnt vmcnt(6)
	v_pk_mul_f32 v[56:57], v[60:61], v[50:51] op_sel_hi:[1,0]
	v_mul_f32_e32 v0, v62, v50
	v_mov_b32_e32 v58, v63
	v_pk_mul_f32 v[26:27], v[26:27], v[56:57]
	v_mul_f32_e32 v28, v28, v0
	v_pk_mul_f32 v[56:57], v[58:59], v[50:51] op_sel_hi:[1,0]
	v_mov_b32_e32 v32, v29
	s_waitcnt vmcnt(5)
	v_mul_f32_e32 v0, v66, v50
	v_pk_mul_f32 v[58:59], v[64:65], v[50:51] op_sel_hi:[1,0]
	s_waitcnt vmcnt(4)
	v_mov_b32_e32 v66, v71
	v_pk_mul_f32 v[56:57], v[32:33], v[56:57]
	v_mul_f32_e32 v32, v24, v0
	v_pk_mul_f32 v[22:23], v[22:23], v[58:59]
	v_pk_mul_f32 v[58:59], v[50:51], v[68:69] op_sel_hi:[0,1]
	v_mul_f32_e32 v0, v50, v70
	v_pk_mul_f32 v[60:61], v[50:51], v[66:67] op_sel_hi:[0,1]
	v_mov_b32_e32 v24, v21
	v_pk_mul_f32 v[18:19], v[18:19], v[58:59]
	v_mul_f32_e32 v58, v20, v0
	v_pk_mul_f32 v[20:21], v[24:25], v[60:61]
	s_and_saveexec_b64 s[8:9], vcc
	s_cbranch_execz .LBB0_1192
	v_mov_b32_e32 v117, v1
	v_lshl_add_u64 v[24:25], v[148:149], 0, v[116:117]
	v_lshlrev_b32_e32 v0, 6, v54
	global_load_dwordx4 v[60:63], v[24:25], off
	v_lshl_add_u64 v[24:25], v[146:147], 0, v[116:117]
	v_and_b32_e32 v0, 0xfc0, v0
	global_load_dwordx4 v[64:67], v[24:25], off
	v_lshl_add_u64 v[24:25], v[148:149], 0, v[0:1]
	global_load_dwordx4 v[68:71], v[24:25], off
	v_lshl_add_u64 v[24:25], v[146:147], 0, v[0:1]
	global_load_dwordx4 v[72:75], v[24:25], off
	s_waitcnt vmcnt(3)
	v_mul_f32_e32 v78, v52, v62
	s_waitcnt vmcnt(2)
	v_pk_mul_f32 v[24:25], v[26:27], v[64:65]
	v_mul_f32_e32 v80, v28, v66
	v_mul_f32_e32 v82, v52, v66
	v_mov_b32_e32 v66, v63
	v_pk_mul_f32 v[64:65], v[30:31], v[64:65]
	v_mul_f32_e32 v28, v28, v62
	s_waitcnt vmcnt(1)
	v_mul_f32_e32 v84, v32, v70
	s_waitcnt vmcnt(0)
	v_mul_f32_e32 v86, v58, v74
	v_mul_f32_e32 v58, v58, v70
	v_mul_f32_e32 v88, v32, v74
	v_mov_b32_e32 v62, v67
	v_pk_fma_f32 v[30:31], v[30:31], v[60:61], v[24:25] neg_lo:[0,0,1] neg_hi:[0,0,1]
	v_pk_mul_f32 v[24:25], v[56:57], v[66:67]
	v_mov_b32_e32 v70, v75
	v_mov_b32_e32 v74, v71
	v_pk_mul_f32 v[32:33], v[56:57], v[62:63]
	v_mov_b32_e32 v29, v24
	v_mov_b32_e32 v83, v25
	v_pk_mul_f32 v[24:25], v[20:21], v[70:71]
	v_pk_mul_f32 v[20:21], v[20:21], v[74:75]
	v_mov_b32_e32 v79, v33
	v_mov_b32_e32 v81, v32
	v_mov_b32_e32 v85, v25
	v_mov_b32_e32 v87, v24
	v_mov_b32_e32 v59, v20
	v_mov_b32_e32 v89, v21
	v_pk_mul_f32 v[76:77], v[18:19], v[72:73]
	v_pk_mul_f32 v[72:73], v[22:23], v[72:73]
	v_pk_add_f32 v[52:53], v[78:79], v[80:81] neg_lo:[0,1] neg_hi:[0,1]
	v_pk_add_f32 v[28:29], v[28:29], v[82:83]
	v_pk_add_f32 v[32:33], v[84:85], v[86:87] neg_lo:[0,1] neg_hi:[0,1]
	v_pk_add_f32 v[58:59], v[58:59], v[88:89]
	v_pk_fma_f32 v[26:27], v[26:27], v[60:61], v[64:65]
	v_pk_fma_f32 v[22:23], v[22:23], v[68:69], v[76:77] neg_lo:[0,0,1] neg_hi:[0,0,1]
	v_pk_fma_f32 v[18:19], v[18:19], v[68:69], v[72:73]
	v_mov_b32_e32 v20, v59
	v_mov_b32_e32 v21, v33
	v_mov_b32_e32 v56, v29
	v_mov_b32_e32 v57, v53
	s_branch .LBB0_1192

.LBB0_1560:
	v_ashrrev_i32_e32 v31, 31, v30
	v_lshlrev_b64 v[36:37], 11, v[30:31]
	v_lshl_or_b32 v10, v32, 2, v36
	v_mov_b32_e32 v11, v37
	v_lshl_add_u64 v[12:13], s[20:21], 0, v[10:11]
	global_load_dwordx4 v[14:17], v[12:13], off
	global_load_dwordx4 v[40:43], v[12:13], off offset:16
	v_lshl_add_u64 v[12:13], s[22:23], 0, v[10:11]
	global_load_dwordx4 v[18:21], v[12:13], off
	global_load_dwordx4 v[48:51], v[12:13], off offset:16
	v_lshl_add_u64 v[12:13], s[34:35], 0, v[10:11]
	v_lshl_add_u64 v[10:11], s[40:41], 0, v[10:11]
	global_load_dwordx4 v[22:25], v[12:13], off
	global_load_dwordx4 v[52:55], v[12:13], off offset:16
	global_load_dwordx4 v[26:29], v[10:11], off
	global_load_dwordx4 v[56:59], v[10:11], off offset:16
	v_mov_b64_e32 v[10:11], s[6:7]
	v_mad_i64_i32 v[10:11], s[8:9], v30, s2, v[10:11]
	v_lshlrev_b32_e32 v0, 1, v32
	v_lshl_add_u64 v[10:11], v[10:11], 0, v[0:1]
	s_mov_b32 s8, 0xdabd000
	v_add_co_u32_e32 v10, vcc, s8, v10
	v_add_u32_e32 v30, s30, v30
	s_nop 0
	v_addc_co_u32_e32 v11, vcc, 0, v11, vcc
	global_load_dwordx4 v[10:13], v[10:11], off offset:3840
	s_waitcnt vmcnt(4)
	v_pk_add_f32 v[18:19], v[18:19], v[22:23]
	s_waitcnt vmcnt(3)
	v_pk_add_f32 v[38:39], v[50:51], v[54:55]
	v_pk_add_f32 v[48:49], v[48:49], v[52:53]
	s_waitcnt vmcnt(1)
	v_pk_add_f32 v[38:39], v[38:39], v[58:59]
	v_pk_add_f32 v[48:49], v[48:49], v[56:57]
	v_pk_add_f32 v[38:39], v[42:43], v[38:39]
	v_pk_add_f32 v[40:41], v[40:41], v[48:49]
	v_pk_add_f32 v[18:19], v[18:19], v[26:27]
	v_pk_add_f32 v[20:21], v[20:21], v[24:25]
	v_pk_add_f32 v[14:15], v[14:15], v[18:19]
	v_pk_add_f32 v[20:21], v[20:21], v[28:29]
	s_waitcnt vmcnt(0)
	v_lshlrev_b32_e32 v0, 16, v13
	v_and_b32_e32 v13, 0xffff0000, v13
	v_mul_f32_e32 v31, 0xbfb8aa3b, v0
	v_exp_f32_e32 v42, v31
	v_mul_f32_e32 v31, 0xbfb8aa3b, v13
	v_exp_f32_e32 v43, v31
	v_pk_add_f32 v[16:17], v[16:17], v[20:21]
	v_pk_add_f32 v[42:43], v[42:43], 1.0 op_sel_hi:[1,0]
	s_nop 0
	v_div_scale_f32 v31, s[8:9], v43, v43, v13
	v_rcp_f32_e32 v47, v31
	s_nop 0
	v_fma_f32 v48, -v31, v47, 1.0
	v_fmac_f32_e32 v47, v48, v47
	v_div_scale_f32 v48, vcc, v13, v43, v13
	v_mul_f32_e32 v49, v48, v47
	v_fma_f32 v50, -v31, v49, v48
	v_fmac_f32_e32 v49, v50, v47
	v_fma_f32 v31, -v31, v49, v48
	v_div_fmas_f32 v31, v31, v47, v49
	v_div_fixup_f32 v43, v31, v43, v13
	v_div_scale_f32 v13, s[8:9], v42, v42, v0
	v_rcp_f32_e32 v31, v13
	s_nop 0
	v_fma_f32 v47, -v13, v31, 1.0
	v_fmac_f32_e32 v31, v47, v31
	v_div_scale_f32 v47, vcc, v0, v42, v0
	v_mul_f32_e32 v48, v47, v31
	v_fma_f32 v49, -v13, v48, v47
	v_fmac_f32_e32 v48, v49, v31
	v_fma_f32 v13, -v13, v48, v47
	v_div_fmas_f32 v13, v13, v31, v48
	v_div_fixup_f32 v42, v13, v42, v0
	v_lshlrev_b32_e32 v0, 16, v12
	v_and_b32_e32 v31, 0xffff0000, v12
	v_mul_f32_e32 v12, 0xbfb8aa3b, v0
	v_mul_f32_e32 v13, 0xbfb8aa3b, v31
	v_exp_f32_e32 v12, v12
	v_exp_f32_e32 v13, v13
	s_nop 0
	v_pk_add_f32 v[12:13], v[12:13], 1.0 op_sel_hi:[1,0]
	s_nop 0
	v_div_scale_f32 v47, s[8:9], v13, v13, v31
	v_rcp_f32_e32 v48, v47
	s_nop 0
	v_fma_f32 v49, -v47, v48, 1.0
	v_fmac_f32_e32 v48, v49, v48
	v_div_scale_f32 v49, vcc, v31, v13, v31
	v_mul_f32_e32 v50, v49, v48
	v_fma_f32 v51, -v47, v50, v49
	v_fmac_f32_e32 v50, v51, v48
	v_fma_f32 v47, -v47, v50, v49
	v_div_fmas_f32 v47, v47, v48, v50
	v_div_fixup_f32 v13, v47, v13, v31
	v_div_scale_f32 v31, s[8:9], v12, v12, v0
	v_rcp_f32_e32 v47, v31
	s_nop 0
	v_fma_f32 v48, -v31, v47, 1.0
	v_fmac_f32_e32 v47, v48, v47
	v_div_scale_f32 v48, vcc, v0, v12, v0
	v_mul_f32_e32 v49, v48, v47
	v_fma_f32 v50, -v31, v49, v48
	v_fmac_f32_e32 v49, v50, v47
	v_fma_f32 v31, -v31, v49, v48
	v_div_fmas_f32 v31, v31, v47, v49
	v_div_fixup_f32 v12, v31, v12, v0
	v_lshlrev_b32_e32 v0, 16, v11
	v_and_b32_e32 v11, 0xffff0000, v11
	v_mul_f32_e32 v18, 0xbfb8aa3b, v0
	v_mul_f32_e32 v19, 0xbfb8aa3b, v11
	v_exp_f32_e32 v18, v18
	v_exp_f32_e32 v19, v19
	s_nop 0
	v_pk_add_f32 v[18:19], v[18:19], 1.0 op_sel_hi:[1,0]
	s_nop 0
	v_div_scale_f32 v20, s[8:9], v19, v19, v11
	v_rcp_f32_e32 v21, v20
	s_nop 0
	v_fma_f32 v22, -v20, v21, 1.0
	v_fmac_f32_e32 v21, v22, v21
	v_div_scale_f32 v22, vcc, v11, v19, v11
	v_mul_f32_e32 v23, v22, v21
	v_fma_f32 v24, -v20, v23, v22
	v_fmac_f32_e32 v23, v24, v21
	v_fma_f32 v20, -v20, v23, v22
	v_div_fmas_f32 v20, v20, v21, v23
	v_div_fixup_f32 v19, v20, v19, v11
	v_div_scale_f32 v11, s[8:9], v18, v18, v0
	v_rcp_f32_e32 v20, v11
	v_and_b32_e32 v24, 0xffff0000, v10
	v_fma_f32 v21, -v11, v20, 1.0
	v_fmac_f32_e32 v20, v21, v20
	v_div_scale_f32 v21, vcc, v0, v18, v0
	v_mul_f32_e32 v22, v21, v20
	v_fma_f32 v23, -v11, v22, v21
	v_fmac_f32_e32 v22, v23, v20
	v_fma_f32 v11, -v11, v22, v21
	v_div_fmas_f32 v11, v11, v20, v22
	v_div_fixup_f32 v18, v11, v18, v0
	v_lshlrev_b32_e32 v0, 16, v10
	v_mul_f32_e32 v10, 0xbfb8aa3b, v0
	v_mul_f32_e32 v11, 0xbfb8aa3b, v24
	v_exp_f32_e32 v10, v10
	v_exp_f32_e32 v11, v11
	v_pk_mul_f32 v[22:23], v[40:41], v[40:41]
	v_pk_mul_f32 v[20:21], v[38:39], v[38:39]
	v_pk_fma_f32 v[22:23], v[14:15], v[14:15], v[22:23]
	v_pk_add_f32 v[10:11], v[10:11], 1.0 op_sel_hi:[1,0]
	v_pk_fma_f32 v[20:21], v[16:17], v[16:17], v[20:21]
	v_div_scale_f32 v25, s[8:9], v11, v11, v24
	v_rcp_f32_e32 v26, v25
	s_nop 0
	v_fma_f32 v27, -v25, v26, 1.0
	v_fmac_f32_e32 v26, v27, v26
	v_div_scale_f32 v27, vcc, v24, v11, v24
	v_mul_f32_e32 v28, v27, v26
	v_fma_f32 v29, -v25, v28, v27
	v_fmac_f32_e32 v28, v29, v26
	v_fma_f32 v25, -v25, v28, v27
	v_div_fmas_f32 v25, v25, v26, v28
	v_div_fixup_f32 v11, v25, v11, v24
	v_div_scale_f32 v24, s[8:9], v10, v10, v0
	v_rcp_f32_e32 v25, v24
	s_nop 0
	v_fma_f32 v26, -v24, v25, 1.0
	v_fmac_f32_e32 v25, v26, v25
	v_div_scale_f32 v26, vcc, v0, v10, v0
	v_mul_f32_e32 v27, v26, v25
	v_fma_f32 v28, -v24, v27, v26
	v_fmac_f32_e32 v27, v28, v25
	v_fma_f32 v24, -v24, v27, v26
	v_div_fmas_f32 v24, v24, v25, v27
	v_div_fixup_f32 v10, v24, v10, v0
	v_add_f32_e32 v0, v22, v23
	v_add_f32_e32 v0, v20, v0
	v_add_f32_e32 v0, v21, v0
	s_waitcnt lgkmcnt(0)
	s_nop 1
	v_add_f32_dpp v0, v0, v0 quad_perm:[1,0,3,2] row_mask:0xf bank_mask:0xf
	s_waitcnt lgkmcnt(0)
	s_nop 1
	v_add_f32_dpp v0, v0, v0 quad_perm:[2,3,0,1] row_mask:0xf bank_mask:0xf
	ds_bpermute_b32 v20, v45, v0
	s_waitcnt lgkmcnt(0)
	v_add_f32_e32 v0, v0, v20
	s_waitcnt lgkmcnt(0)
	s_nop 1
	v_add_f32_dpp v0, v0, v0 row_ror:8 row_mask:0xf bank_mask:0xf
	v_fmamk_f32 v0, v0, 0x3c000000, v178
	v_cmp_gt_f32_e32 vcc, s64, v0
	v_mul_f32_e32 v20, 0x4b800000, v0
	s_nop 0
	v_cndmask_b32_e32 v0, v0, v20, vcc
	v_rsq_f32_e32 v0, v0
	s_nop 0
	v_mul_f32_e32 v20, 0x45800000, v0
	v_cndmask_b32_e32 v0, v0, v20, vcc
	v_pk_mul_f32 v[14:15], v[14:15], v[0:1] op_sel_hi:[1,0]
	v_cmp_lt_i32_e32 vcc, s73, v30
	v_pk_mul_f32 v[14:15], v[2:3], v[14:15]
	s_or_b64 s[42:43], vcc, s[42:43]
	v_pk_mul_f32 v[10:11], v[10:11], v[14:15]
	v_pk_mul_f32 v[14:15], v[40:41], v[0:1] op_sel_hi:[1,0]
	v_cvt_pk_bf16_f32 v10, v10, v11
	v_pk_mul_f32 v[14:15], v[6:7], v[14:15]
	s_nop 0
	v_pk_mul_f32 v[12:13], v[12:13], v[14:15]
	v_pk_mul_f32 v[14:15], v[16:17], v[0:1] op_sel_hi:[1,0]
	v_pk_mul_f32 v[16:17], v[38:39], v[0:1] op_sel_hi:[1,0]
	v_pk_mul_f32 v[14:15], v[4:5], v[14:15]
	v_pk_mul_f32 v[16:17], v[8:9], v[16:17]
	v_pk_mul_f32 v[14:15], v[18:19], v[14:15]
	v_pk_mul_f32 v[16:17], v[42:43], v[16:17]
	v_cvt_pk_bf16_f32 v11, v14, v15
	v_cvt_pk_bf16_f32 v12, v12, v13
	v_cvt_pk_bf16_f32 v13, v16, v17
	v_lshl_add_u64 v[14:15], v[34:35], 0, v[36:37]
	global_store_dwordx4 v[14:15], v[10:13], off
	s_andn2_b64 exec, exec, s[42:43]
	s_cbranch_execnz .LBB0_1560

.LBB0_1735:
	v_ashrrev_i32_e32 v3, 31, v2
	v_lshlrev_b64 v[24:25], 12, v[2:3]
	v_lshl_add_u64 v[42:43], v[14:15], 0, v[24:25]
	global_load_dwordx4 v[24:27], v[42:43], off
	global_load_dwordx4 v[28:31], v[42:43], off offset:1024
	global_load_dwordx4 v[32:35], v[42:43], off offset:2048
	s_nop 0
	global_load_dwordx4 v[42:45], v[42:43], off offset:3072
	v_add_u32_e32 v19, 0xffffe000, v2
	v_lshrrev_b32_e32 v19, 12, v19
	v_add_u32_e32 v19, 1, v19
	v_cmp_lt_i32_e32 vcc, s11, v2
	s_mul_i32 s0, s36, 5
	v_mov_b64_e32 v[46:47], s[20:21]
	v_cndmask_b32_e32 v19, 0, v19, vcc
	v_add_u32_e32 v19, s0, v19
	v_mad_u64_u32 v[54:55], s[0:1], v19, s29, v[46:47]
	v_lshlrev_b32_e32 v0, 2, v4
	v_lshl_add_u64 v[58:59], v[54:55], 0, s[96:97]
	v_lshl_add_u64 v[46:47], v[58:59], 0, v[0:1]
	global_load_dwordx4 v[46:49], v[46:47], off
	s_nop 0
	global_load_dwordx4 v[50:53], v[6:7], off
	v_lshl_add_u64 v[60:61], v[54:55], 0, v[0:1]
	global_load_dwordx4 v[54:57], v[60:61], off
	v_mov_b32_e32 v23, v1
	s_mov_b64 s[0:1], 0
	s_mov_b32 s3, 0x43dc0000
	s_waitcnt vmcnt(6)
	v_mov_b32_e32 v68, v25
	s_waitcnt vmcnt(5)
	v_mov_b32_e32 v69, v29
	v_mov_b32_e32 v66, v24
	v_mov_b32_e32 v67, v28
	s_waitcnt vmcnt(4)
	v_mov_b32_e32 v76, v33
	s_waitcnt vmcnt(3)
	v_mov_b32_e32 v77, v43
	v_pk_mul_f32 v[68:69], v[68:69], v[68:69]
	v_mov_b32_e32 v62, v26
	v_mov_b32_e32 v63, v30
	v_mov_b32_e32 v74, v32
	v_mov_b32_e32 v75, v42
	v_pk_mul_f32 v[76:77], v[76:77], v[76:77]
	v_pk_fma_f32 v[66:67], v[66:67], v[66:67], v[68:69]
	v_mov_b32_e32 v64, v27
	v_mov_b32_e32 v65, v31
	v_mov_b32_e32 v70, v34
	v_mov_b32_e32 v71, v44
	v_pk_fma_f32 v[68:69], v[74:75], v[74:75], v[76:77]
	v_pk_fma_f32 v[62:63], v[62:63], v[62:63], v[66:67]
	v_mov_b32_e32 v72, v35
	v_mov_b32_e32 v73, v45
	v_pk_fma_f32 v[66:67], v[70:71], v[70:71], v[68:69]
	v_pk_fma_f32 v[62:63], v[64:65], v[64:65], v[62:63]
	v_pk_fma_f32 v[64:65], v[72:73], v[72:73], v[66:67]
	v_add_f32_e32 v0, v62, v63
	v_add_f32_e32 v0, v0, v64
	v_add_f32_e32 v0, v0, v65
	v_mov_b32_e32 v19, v0
	s_waitcnt vmcnt(2)
	v_pk_add_f32 v[48:49], v[48:49], 1.0 op_sel_hi:[1,0]
	v_pk_add_f32 v[46:47], v[46:47], 1.0 op_sel_hi:[1,0]
	v_lshlrev_b64 v[62:63], 11, v[2:3]
	v_lshl_add_u64 v[62:63], v[16:17], 0, v[62:63]
	s_waitcnt lgkmcnt(0)
	s_nop 1
	v_permlane32_swap_b32_e32 v19, v0
	v_add_f32_e32 v0, v0, v19
	v_mov_b32_e32 v19, v0
	s_waitcnt lgkmcnt(0)
	s_nop 1
	v_permlane16_swap_b32_e32 v19, v0
	v_add_f32_e32 v0, v0, v19
	s_waitcnt lgkmcnt(0)
	s_nop 1
	v_add_f32_dpp v0, v0, v0 row_ror:8 row_mask:0xf bank_mask:0xf
	ds_bpermute_b32 v19, v39, v0
	s_waitcnt lgkmcnt(0)
	v_add_f32_e32 v0, v0, v19
	s_waitcnt lgkmcnt(0)
	s_nop 1
	v_add_f32_dpp v0, v0, v0 quad_perm:[2,3,0,1] row_mask:0xf bank_mask:0xf
	v_mov_b32_e32 v19, v1
	v_lshl_add_u64 v[64:65], v[58:59], 0, v[18:19]
	s_waitcnt lgkmcnt(0)
	s_nop 1
	v_add_f32_dpp v0, v0, v0 quad_perm:[1,0,3,2] row_mask:0xf bank_mask:0xf
	v_fmamk_f32 v0, v0, 0x3a800000, v178
	v_mul_f32_e32 v21, 0x4b800000, v0
	v_cmp_gt_f32_e32 vcc, s64, v0
	s_nop 1
	v_cndmask_b32_e32 v0, v0, v21, vcc
	v_rsq_f32_e32 v0, v0
	v_mov_b32_e32 v21, v1
	v_mul_f32_e32 v19, 0x45800000, v0
	v_cndmask_b32_e32 v0, v0, v19, vcc
	v_pk_mul_f32 v[24:25], v[24:25], v[0:1] op_sel_hi:[1,0]
	v_pk_mul_f32 v[26:27], v[26:27], v[0:1] op_sel_hi:[1,0]
	s_waitcnt vmcnt(1)
	v_pk_mul_f32 v[24:25], v[50:51], v[24:25]
	v_pk_mul_f32 v[50:51], v[52:53], v[26:27]
	s_waitcnt vmcnt(0)
	v_pk_fma_f32 v[26:27], v[46:47], v[24:25], v[54:55]
	v_pk_fma_f32 v[24:25], v[48:49], v[50:51], v[56:57]
	v_cvt_pk_bf16_f32 v46, v26, v27
	v_cvt_pk_bf16_f32 v47, v24, v25
	global_store_dwordx2 v[62:63], v[46:47], off
	global_load_dwordx4 v[46:49], v[8:9], off
	s_nop 0
	global_load_dwordx4 v[50:53], v[64:65], off
	global_load_dwordx4 v[54:57], v[60:61], off offset:1024
	v_pk_mul_f32 v[28:29], v[28:29], v[0:1] op_sel_hi:[1,0]
	v_pk_mul_f32 v[30:31], v[30:31], v[0:1] op_sel_hi:[1,0]
	v_lshl_add_u64 v[64:65], v[58:59], 0, v[20:21]
	v_pk_mul_f32 v[32:33], v[32:33], v[0:1] op_sel_hi:[1,0]
	v_pk_mul_f32 v[34:35], v[34:35], v[0:1] op_sel_hi:[1,0]
	v_lshl_add_u64 v[58:59], v[58:59], 0, v[22:23]
	v_pk_mul_f32 v[44:45], v[44:45], v[0:1] op_sel_hi:[1,0]
	v_pk_mul_f32 v[42:43], v[42:43], v[0:1] op_sel_hi:[1,0]
	v_max_f32_e64 v0, |v24|, |v25|
	v_max3_f32 v0, |v26|, |v27|, v0
	s_waitcnt vmcnt(2)
	v_pk_mul_f32 v[28:29], v[28:29], v[46:47]
	s_waitcnt vmcnt(1)
	v_pk_add_f32 v[46:47], v[50:51], 1.0 op_sel_hi:[1,0]
	v_pk_mul_f32 v[48:49], v[30:31], v[48:49]
	v_pk_add_f32 v[50:51], v[52:53], 1.0 op_sel_hi:[1,0]
	s_waitcnt vmcnt(0)
	v_pk_fma_f32 v[30:31], v[28:29], v[46:47], v[54:55]
	v_pk_fma_f32 v[28:29], v[48:49], v[50:51], v[56:57]
	v_cvt_pk_bf16_f32 v46, v30, v31
	v_cvt_pk_bf16_f32 v47, v28, v29
	global_store_dwordx2 v[62:63], v[46:47], off offset:512
	global_load_dwordx4 v[46:49], v[10:11], off
	s_nop 0
	global_load_dwordx4 v[50:53], v[64:65], off
	global_load_dwordx4 v[54:57], v[60:61], off offset:2048
	v_max_f32_e64 v19, |v28|, |v29|
	v_max3_f32 v19, |v30|, |v31|, v19
	v_max3_f32 v0, v0, 0, v19
	s_waitcnt vmcnt(2)
	v_pk_mul_f32 v[32:33], v[32:33], v[46:47]
	s_waitcnt vmcnt(1)
	v_pk_add_f32 v[46:47], v[50:51], 1.0 op_sel_hi:[1,0]
	v_pk_mul_f32 v[48:49], v[34:35], v[48:49]
	v_pk_add_f32 v[50:51], v[52:53], 1.0 op_sel_hi:[1,0]
	s_waitcnt vmcnt(0)
	v_pk_fma_f32 v[34:35], v[32:33], v[46:47], v[54:55]
	v_pk_fma_f32 v[32:33], v[48:49], v[50:51], v[56:57]
	v_cvt_pk_bf16_f32 v46, v34, v35
	v_cvt_pk_bf16_f32 v47, v32, v33
	global_store_dwordx2 v[62:63], v[46:47], off offset:1024
	global_load_dwordx4 v[46:49], v[12:13], off
	s_nop 0
	global_load_dwordx4 v[50:53], v[58:59], off
	global_load_dwordx4 v[54:57], v[60:61], off offset:3072
	v_max_f32_e64 v19, |v32|, |v33|
	v_max3_f32 v19, |v34|, |v35|, v19
	s_waitcnt vmcnt(2)
	v_pk_mul_f32 v[44:45], v[44:45], v[48:49]
	s_waitcnt vmcnt(1)
	v_pk_add_f32 v[48:49], v[52:53], 1.0 op_sel_hi:[1,0]
	v_pk_mul_f32 v[42:43], v[42:43], v[46:47]
	v_pk_add_f32 v[46:47], v[50:51], 1.0 op_sel_hi:[1,0]
	s_waitcnt vmcnt(0)
	v_pk_fma_f32 v[44:45], v[44:45], v[48:49], v[56:57]
	v_pk_fma_f32 v[42:43], v[42:43], v[46:47], v[54:55]
	v_max_f32_e64 v21, |v44|, |v45|
	v_max3_f32 v21, |v42|, |v43|, v21
	v_max3_f32 v0, v0, v19, v21
	v_mov_b32_e32 v19, v0
	v_cvt_pk_bf16_f32 v48, v42, v43
	v_cvt_pk_bf16_f32 v49, v44, v45
	global_store_dwordx2 v[62:63], v[48:49], off offset:1536
	s_waitcnt lgkmcnt(0)
	s_nop 1
	v_permlane32_swap_b32_e32 v19, v0
	v_max_f32_e32 v0, v0, v19
	v_mov_b32_e32 v19, v0
	s_add_u32 s0, s90, s0
	v_lshlrev_b64 v[46:47], 10, v[2:3]
	s_addc_u32 s1, s91, s1
	v_lshl_add_u64 v[46:47], s[0:1], 0, v[46:47]
	s_waitcnt lgkmcnt(0)
	s_nop 1
	v_permlane16_swap_b32_e32 v19, v0
	v_max_f32_e32 v0, v0, v19
	v_lshl_add_u64 v[46:47], v[46:47], 0, v[4:5]
	s_mov_b64 s[0:1], 0x341fd700
	v_lshl_add_u64 v[48:49], v[46:47], 0, s[0:1]
	v_mov_b32_e32 v21, v1
	s_waitcnt lgkmcnt(0)
	s_nop 1
	v_max_f32_dpp v0, v0, v0 row_ror:8 row_mask:0xf bank_mask:0xf
	ds_bpermute_b32 v19, v39, v0
	v_mov_b32_e32 v50, v1
	v_mov_b32_e32 v51, v1
	s_waitcnt lgkmcnt(0)
	v_max_f32_e32 v19, v19, v19
	v_max_f32_e32 v0, v0, v19
	s_waitcnt lgkmcnt(0)
	s_nop 1
	v_max_f32_dpp v0, v0, v0 quad_perm:[2,3,0,1] row_mask:0xf bank_mask:0xf
	s_waitcnt lgkmcnt(0)
	s_nop 1
	v_max_f32_dpp v0, v0, v0 quad_perm:[1,0,3,2] row_mask:0xf bank_mask:0xf
	v_div_scale_f32 v19, s[0:1], v0, v0, s3
	v_rcp_f32_e32 v52, v19
	s_mov_b32 s0, 0x341fd000
	v_add_co_u32_e32 v46, vcc, s0, v46
	v_fma_f32 v54, -v19, v52, 1.0
	s_nop 0
	v_addc_co_u32_e32 v47, vcc, 0, v47, vcc
	v_div_scale_f32 v53, vcc, s3, v0, s3
	v_fmac_f32_e32 v52, v54, v52
	v_mul_f32_e32 v54, v53, v52
	v_fma_f32 v55, -v19, v54, v53
	v_fmac_f32_e32 v54, v55, v52
	v_fma_f32 v19, -v19, v54, v53
	v_div_fmas_f32 v19, v19, v52, v54
	v_div_fixup_f32 v19, v19, v0, s3
	v_cmp_lt_f32_e64 s[0:1], 0, v0
	s_nop 1
	v_cndmask_b32_e64 v19, 1.0, v19, s[0:1]
	v_mul_f32_e32 v26, v26, v19
	v_mul_f32_e32 v27, v27, v19
	v_mul_f32_e32 v30, v30, v19
	v_mul_f32_e32 v31, v31, v19
	v_cvt_pk_fp8_f32 v21, v26, v27
	v_mul_f32_e32 v34, v34, v19
	v_mul_f32_e32 v35, v35, v19
	v_cvt_pk_fp8_f32 v23, v30, v31
	v_mul_f32_e32 v42, v42, v19
	v_mul_f32_e32 v43, v43, v19
	v_cvt_pk_fp8_f32 v50, v34, v35
	v_mul_f32_e32 v24, v24, v19
	v_mul_f32_e32 v25, v25, v19
	v_cvt_pk_fp8_f32 v51, v42, v43
	v_mul_f32_e32 v28, v28, v19
	v_mul_f32_e32 v29, v29, v19
	v_cvt_pk_fp8_f32 v21, v24, v25 op_sel:[0,0,1]
	v_mul_f32_e32 v32, v32, v19
	v_mul_f32_e32 v33, v33, v19
	v_cvt_pk_fp8_f32 v23, v28, v29 op_sel:[0,0,1]
	v_mul_f32_e32 v44, v44, v19
	v_mul_f32_e32 v19, v45, v19
	v_cvt_pk_fp8_f32 v50, v32, v33 op_sel:[0,0,1]
	v_cvt_pk_fp8_f32 v51, v44, v19 op_sel:[0,0,1]
	global_store_dword v[46:47], v21, off offset:1792
	global_store_dword v[48:49], v23, off offset:256
	global_store_dword v[48:49], v50, off offset:512
	global_store_dword v[48:49], v51, off offset:768
	s_and_saveexec_b64 s[22:23], s[40:41]
	s_cbranch_execz .LBB0_1734
	v_div_scale_f32 v19, s[34:35], s3, s3, v0
	v_rcp_f32_e32 v21, v19
	v_div_scale_f32 v23, vcc, v0, s3, v0
	v_fma_f32 v24, -v19, v21, 1.0
	v_fmac_f32_e32 v21, v24, v21
	v_mul_f32_e32 v24, v23, v21
	v_fma_f32 v25, -v19, v24, v23
	v_fmac_f32_e32 v24, v25, v21
	v_fma_f32 v19, -v19, v24, v23
	v_div_fmas_f32 v19, v19, v21, v24
	v_div_fixup_f32 v0, v19, s3, v0
	v_cndmask_b32_e64 v0, 1.0, v0, s[0:1]
	s_mov_b64 s[0:1], 0
	s_add_u32 s0, s90, s0
	s_addc_u32 s1, s91, s1
	v_lshl_add_u64 v[24:25], v[2:3], 2, s[0:1]
	v_add_co_u32_e32 v24, vcc, 0x359fd000, v24
	s_nop 1
	v_addc_co_u32_e32 v25, vcc, 0, v25, vcc
	global_store_dword v[24:25], v0, off offset:1792
	s_branch .LBB0_1734

.LBB0_2144:
	v_cmp_gt_i32_e32 vcc, s29, v54
	s_and_saveexec_b64 s[20:21], vcc
	s_cbranch_execz .LBB0_2143
	v_ashrrev_i32_e32 v55, 31, v54
	v_lshlrev_b64 v[2:3], 12, v[54:55]
	v_lshl_add_u64 v[10:11], v[88:89], 0, v[2:3]
	global_load_dwordx4 v[6:9], v[10:11], off offset:32
	global_load_dwordx4 v[2:5], v[10:11], off offset:48
	global_load_dwordx4 v[26:29], v[10:11], off
	s_nop 0
	global_load_dwordx4 v[10:13], v[10:11], off offset:16
	s_waitcnt vmcnt(3)
	v_mov_b32_e32 v18, v7
	s_waitcnt vmcnt(2)
	v_mov_b32_e32 v19, v3
	s_waitcnt vmcnt(1)
	v_mov_b32_e32 v16, v27
	s_waitcnt vmcnt(0)
	v_mov_b32_e32 v17, v11
	v_mov_b32_e32 v14, v26
	v_mov_b32_e32 v15, v10
	v_pk_mul_f32 v[16:17], v[16:17], v[16:17]
	v_pk_mul_f32 v[18:19], v[18:19], v[18:19]
	v_pk_fma_f32 v[14:15], v[14:15], v[14:15], v[16:17]
	v_mov_b32_e32 v16, v28
	v_mov_b32_e32 v17, v12
	v_pk_fma_f32 v[14:15], v[16:17], v[16:17], v[14:15]
	v_mov_b32_e32 v16, v29
	v_mov_b32_e32 v17, v13
	v_pk_fma_f32 v[14:15], v[16:17], v[16:17], v[14:15]
	v_mov_b32_e32 v16, v6
	v_mov_b32_e32 v17, v2
	v_pk_fma_f32 v[16:17], v[16:17], v[16:17], v[18:19]
	v_mov_b32_e32 v18, v8
	v_mov_b32_e32 v19, v4
	v_add_f32_e32 v0, v14, v15
	v_and_b32_e32 v14, 64, v215
	v_pk_fma_f32 v[16:17], v[18:19], v[18:19], v[16:17]
	v_mov_b32_e32 v18, v9
	v_mov_b32_e32 v19, v5
	v_add_u32_e32 v14, 64, v14
	v_xor_b32_e32 v15, 32, v215
	v_pk_fma_f32 v[16:17], v[18:19], v[18:19], v[16:17]
	v_cmp_lt_i32_e32 vcc, v15, v14
	v_add_f32_e32 v0, v0, v16
	v_add_f32_e32 v0, v0, v17
	v_cndmask_b32_e32 v15, v215, v15, vcc
	v_lshlrev_b32_e32 v15, 2, v15
	v_mov_b32_e32 v15, v0
	s_waitcnt lgkmcnt(0)
	s_nop 1
	v_permlane32_swap_b32_e32 v15, v0
	v_add_f32_e32 v0, v0, v15
	v_xor_b32_e32 v15, 16, v215
	v_cmp_lt_i32_e32 vcc, v15, v14
	s_nop 1
	v_cndmask_b32_e32 v15, v215, v15, vcc
	v_lshlrev_b32_e32 v15, 2, v15
	v_mov_b32_e32 v15, v0
	s_waitcnt lgkmcnt(0)
	s_nop 1
	v_permlane16_swap_b32_e32 v15, v0
	v_add_f32_e32 v0, v0, v15
	v_xor_b32_e32 v15, 8, v215
	v_cmp_lt_i32_e32 vcc, v15, v14
	s_nop 1
	v_cndmask_b32_e32 v15, v215, v15, vcc
	v_lshlrev_b32_e32 v15, 2, v15
	s_waitcnt lgkmcnt(0)
	s_nop 1
	v_add_f32_dpp v0, v0, v0 row_ror:8 row_mask:0xf bank_mask:0xf
	v_xor_b32_e32 v15, 4, v215
	v_cmp_lt_i32_e32 vcc, v15, v14
	s_nop 1
	v_cndmask_b32_e32 v15, v215, v15, vcc
	v_lshlrev_b32_e32 v15, 2, v15
	ds_bpermute_b32 v15, v15, v0
	s_waitcnt lgkmcnt(0)
	v_add_f32_e32 v0, v0, v15
	v_xor_b32_e32 v15, 2, v215
	v_cmp_lt_i32_e32 vcc, v15, v14
	s_nop 1
	v_cndmask_b32_e32 v15, v215, v15, vcc
	v_lshlrev_b32_e32 v15, 2, v15
	s_waitcnt lgkmcnt(0)
	s_nop 1
	v_add_f32_dpp v0, v0, v0 quad_perm:[2,3,0,1] row_mask:0xf bank_mask:0xf
	v_xor_b32_e32 v15, 1, v215
	v_cmp_lt_i32_e32 vcc, v15, v14
	s_nop 1
	v_cndmask_b32_e32 v14, v215, v15, vcc
	v_lshlrev_b32_e32 v14, 2, v14
	s_waitcnt lgkmcnt(0)
	s_nop 1
	v_add_f32_dpp v0, v0, v0 quad_perm:[1,0,3,2] row_mask:0xf bank_mask:0xf
	v_fmamk_f32 v0, v0, 0x3a800000, v178
	v_cmp_gt_f32_e32 vcc, s64, v0
	v_mul_f32_e32 v14, 0x4b800000, v0
	s_nop 0
	v_cndmask_b32_e32 v0, v0, v14, vcc
	v_rsq_f32_e32 v0, v0
	s_nop 0
	v_mul_f32_e32 v14, 0x45800000, v0
	v_cndmask_b32_e32 v0, v0, v14, vcc
	v_add_u32_e32 v14, 0xffffe000, v54
	v_lshrrev_b32_e32 v14, 12, v14
	v_add_u32_e32 v14, 1, v14
	v_cmp_lt_i32_e32 vcc, s11, v54
	v_pk_mul_f32 v[26:27], v[26:27], v[0:1] op_sel_hi:[1,0]
	v_pk_mul_f32 v[28:29], v[28:29], v[0:1] op_sel_hi:[1,0]
	v_cndmask_b32_e32 v14, 0, v14, vcc
	v_add_u32_e32 v14, s35, v14
	v_mad_u64_u32 v[22:23], s[50:51], v14, s29, v[82:83]
	v_lshl_add_u64 v[50:51], v[22:23], 0, s[96:97]
	global_load_dwordx4 v[18:21], v[90:91], off offset:48
	global_load_dwordx4 v[34:37], v[90:91], off offset:32
	global_load_dwordx4 v[46:49], v[90:91], off offset:16
	global_load_dwordx4 v[56:59], v[90:91], off
	global_load_dwordx4 v[14:17], v[22:23], off offset:48
	global_load_dwordx4 v[30:33], v[22:23], off offset:32
	global_load_dwordx4 v[42:45], v[22:23], off offset:16
	global_load_dwordx4 v[60:63], v[22:23], off
	v_add_co_u32_e32 v22, vcc, s14, v22
	v_pk_mul_f32 v[10:11], v[10:11], v[0:1] op_sel_hi:[1,0]
	s_nop 0
	v_addc_co_u32_e32 v23, vcc, 0, v23, vcc
	global_load_dwordx4 v[64:67], v[22:23], off
	s_nop 0
	global_load_dwordx4 v[22:25], v[50:51], off offset:48
	global_load_dwordx4 v[38:41], v[50:51], off offset:32
	s_nop 0
	global_load_dwordx4 v[50:53], v[50:51], off offset:16
	v_pk_mul_f32 v[6:7], v[6:7], v[0:1] op_sel_hi:[1,0]
	v_pk_mul_f32 v[8:9], v[8:9], v[0:1] op_sel_hi:[1,0]
	v_pk_mul_f32 v[2:3], v[2:3], v[0:1] op_sel_hi:[1,0]
	s_waitcnt vmcnt(10)
	v_pk_mul_f32 v[6:7], v[34:35], v[6:7]
	s_waitcnt vmcnt(9)
	v_pk_mul_f32 v[10:11], v[46:47], v[10:11]
	s_waitcnt vmcnt(8)
	v_pk_mul_f32 v[26:27], v[56:57], v[26:27]
	v_pk_mul_f32 v[28:29], v[58:59], v[28:29]
	v_pk_mul_f32 v[8:9], v[36:37], v[8:9]
	v_pk_mul_f32 v[2:3], v[18:19], v[2:3]
	s_waitcnt vmcnt(3)
	v_pk_add_f32 v[56:57], v[64:65], 1.0 op_sel_hi:[1,0]
	s_nop 0
	v_pk_fma_f32 v[26:27], v[56:57], v[26:27], v[60:61]
	v_pk_add_f32 v[56:57], v[66:67], 1.0 op_sel_hi:[1,0]
	v_cvt_pk_bf16_f32 v26, v26, v27
	v_pk_fma_f32 v[28:29], v[56:57], v[28:29], v[62:63]
	s_nop 0
	v_cvt_pk_bf16_f32 v27, v28, v29
	s_waitcnt vmcnt(0)
	v_pk_add_f32 v[28:29], v[50:51], 1.0 op_sel_hi:[1,0]
	s_nop 0
	v_pk_fma_f32 v[10:11], v[28:29], v[10:11], v[42:43]
	s_nop 0
	v_cvt_pk_bf16_f32 v28, v10, v11
	v_pk_mul_f32 v[10:11], v[12:13], v[0:1] op_sel_hi:[1,0]
	v_pk_add_f32 v[12:13], v[52:53], 1.0 op_sel_hi:[1,0]
	v_pk_mul_f32 v[10:11], v[48:49], v[10:11]
	s_nop 0
	v_pk_fma_f32 v[10:11], v[12:13], v[10:11], v[44:45]
	s_nop 0
	v_cvt_pk_bf16_f32 v29, v10, v11
	v_pk_add_f32 v[10:11], v[38:39], 1.0 op_sel_hi:[1,0]
	s_nop 0
	v_pk_fma_f32 v[6:7], v[10:11], v[6:7], v[30:31]
	v_pk_add_f32 v[10:11], v[40:41], 1.0 op_sel_hi:[1,0]
	v_cvt_pk_bf16_f32 v6, v6, v7
	v_pk_fma_f32 v[8:9], v[10:11], v[8:9], v[32:33]
	s_nop 0
	v_cvt_pk_bf16_f32 v7, v8, v9
	v_pk_add_f32 v[8:9], v[22:23], 1.0 op_sel_hi:[1,0]
	s_nop 0
	v_pk_fma_f32 v[2:3], v[8:9], v[2:3], v[14:15]
	s_nop 0
	v_cvt_pk_bf16_f32 v8, v2, v3
	v_pk_mul_f32 v[2:3], v[4:5], v[0:1] op_sel_hi:[1,0]
	v_pk_add_f32 v[4:5], v[24:25], 1.0 op_sel_hi:[1,0]
	v_pk_mul_f32 v[2:3], v[20:21], v[2:3]
	s_nop 0
	v_pk_fma_f32 v[2:3], v[4:5], v[2:3], v[16:17]
	s_nop 0
	v_cvt_pk_bf16_f32 v9, v2, v3
	v_lshlrev_b64 v[2:3], 11, v[54:55]
	v_lshl_add_u64 v[2:3], v[84:85], 0, v[2:3]
	global_store_dwordx4 v[2:3], v[26:29], off
	global_store_dwordx4 v[2:3], v[6:9], off offset:16
	s_branch .LBB0_2143
